# v21: v16 with all per-segment s_setprio deleted from the K-loops and one static s_setprio 1 for waves 4-7 at kernel entry
# baseline (speedup 1.0000x reference)
; #define LAS __attribute__((address_space(3)))
; __global__ void __launch_bounds__(512, 2) mk_fwd(Args args) {
;     {
;         LAS unsigned char* lds0 = (LAS unsigned char*)lds_raw;
;         for (int u = threadIdx.x; u < (LDS_BYTES - RING_BYTES) / 4; u += 512) ((LAS unsigned*)(lds0 + RING_BYTES))[u] = 0u;
;         __syncthreads();
;     }
;     const int lo = args.ph_lo, hi = args.ph_hi;
_Z6mk_fwd4Args:
	v_readfirstlane_b32 s100, v0
	s_nop 3
	s_and_b32 s100, s100, 0x3ff
	s_lshr_b32 s100, s100, 6
	s_cmp_ge_u32 s100, 4
	s_cbranch_scc0 .Lprio_done
	s_setprio 1
.Lprio_done:
	s_load_dwordx4 s[76:79], s[0:1], 0x138
	v_lshl_add_u32 v2, v0, 2, 0
	s_mov_b64 s[72:73], s[0:1]
	v_or_b32_e32 v1, 0xfffffe00, v0
	v_add_u32_e32 v2, 0x20000, v2
	s_mov_b64 s[0:1], 0
	v_mov_b32_e32 v3, 0
	s_movk_i32 s3, 0x1dff

; #define PG8_STAGE(bufoff, gbase, voff) do { _Pragma("unroll") for (int _i = 0; _i < 2; ++_i) \
;         __builtin_amdgcn_global_load_lds((const unsigned*)((const char*)(gbase) + (voff)[_i]), (PG8_LAS unsigned*)(lds + (bufoff) + ldsw + _i * 8192), 16, 0, 0); } while (0)
; #define PG8_LDA(dst, b, h) do { _Pragma("unroll") for (int m = 0; m < 4; ++m) _Pragma("unroll") for (int k = 0; k < 2; ++k) dst[m][k] = *(const PG8_LAS bf16x8*)(lds + PG8_SA(b, h) + aoff + m * 2048 + k * 1024); } while (0)
; #define PG8_LDB(dst, b, h) do { _Pragma("unroll") for (int n = 0; n < 2; ++n) _Pragma("unroll") for (int k = 0; k < 2; ++k) dst[n][k] = *(const PG8_LAS bf16x8*)(lds + PG8_SB(b, h) + boff + n * 2048 + k * 1024); } while (0)
; #define PG8_MMA(ai, bj, At, Bt) do { __builtin_amdgcn_s_setprio(1); _Pragma("unroll") for (int m = 0; m < 4; ++m) _Pragma("unroll") for (int n = 0; n < 2; ++n) _Pragma("unroll") for (int k = 0; k < 2; ++k) \
;         acc[ai][bj][m][n] = __builtin_amdgcn_mfma_f32_16x16x32_bf16(Bt[n][k], At[m][k], acc[ai][bj][m][n], 0, 0, 0); __builtin_amdgcn_s_setprio(0); } while (0)
; #define PG8_WAIT_V(n) asm volatile("s_waitcnt vmcnt(" #n ")" ::: "memory")
; #define PG8_WAIT_L(n) asm volatile("s_waitcnt lgkmcnt(" #n ")" ::: "memory")
; #define PG8_BAR __builtin_amdgcn_s_barrier()
; #define PG8_SCHED __builtin_amdgcn_sched_barrier(0)
; template <class Epi, class Sched, bool ALIGN_EPI = false, bool SP2 = false>
; __device__ __forceinline__ void gemm_phase(PG8_LAS unsigned char* lds, const Gemm g, const Sched& S, const Epi& E) {
;     ...
;             PG8_LDB(B0, 0, 0); PG8_LDB(B1, 0, 1); PG8_SCHED; PG8_LDA(At, 0, 0); PG8_STAGE(PG8_SA(1, 1), a1 + hstep, voffA);
;             PG8_WAIT_V(8); PG8_WAIT_L(0); PG8_BAR; PG8_MMA(0, 0, At, B0); PG8_MMA(0, 1, At, B1); PG8_BAR; PG8_SCHED;
;             PG8_LDA(At, 0, 1); PG8_STAGE(PG8_SB(0, 0), b2, voffB); PG8_STAGE(PG8_SB(0, 1), b2 + hstep, voffB); PG8_STAGE(PG8_SA(0, 0), a2, voffA);
;             PG8_WAIT_V(8); PG8_WAIT_L(0); PG8_BAR; PG8_MMA(1, 0, At, B0); PG8_MMA(1, 1, At, B1); PG8_BAR; PG8_SCHED;
.LBB0_816:
	ds_read_b128 v[142:145], v198
	ds_read_b128 v[146:149], v198 offset:1024
	ds_read_b128 v[154:157], v198 offset:2048
	ds_read_b128 v[158:161], v198 offset:3072
	ds_read_b128 v[162:165], v198 offset:16384
	ds_read_b128 v[166:169], v198 offset:17408
	ds_read_b128 v[170:173], v198 offset:18432
	ds_read_b128 v[174:177], v198 offset:19456
	ds_read_b128 v[178:181], v153
	ds_read_b128 v[182:185], v153 offset:1024
	ds_read_b128 v[186:189], v153 offset:2048
	ds_read_b128 v[190:193], v153 offset:3072
	ds_read_b128 v[194:197], v153 offset:4096
	ds_read_b128 v[214:217], v153 offset:5120
	ds_read_b128 v[218:221], v153 offset:6144
	ds_read_b128 v[234:237], v153 offset:7168
	s_add_u32 s0, s50, 0xfff00080
	s_addc_u32 s1, s51, -1
	s_add_i32 s61, 0, 0x10000
	s_cmp_eq_u32 s60, 60
	s_cselect_b32 s27, s47, s1
	s_cselect_b32 s26, s46, s0
	s_cselect_b32 s1, s49, s45
	s_cselect_b32 s0, s48, s43
	s_add_i32 s64, 0, 0x14000
	s_add_u32 s100, s50, 0xfff00000
	s_addc_u32 s101, s51, -1
	s_mov_b32 m0, s54
	s_nop 0
	global_load_lds_dwordx4 v136, s[100:101]
	s_mov_b32 m0, s55
	s_nop 0
	global_load_lds_dwordx4 v134, s[100:101]
	s_add_i32 m0, s9, 0xc000
	s_nop 0
	global_load_lds_dwordx4 v138, s[50:51]
	s_add_i32 m0, s9, 0xe000
	s_nop 0
	global_load_lds_dwordx4 v140, s[50:51]
	s_nop 0
	s_waitcnt vmcnt(8)
	s_waitcnt lgkmcnt(0)
	s_barrier
	v_mfma_f32_16x16x32_bf16 v[128:131], v[142:145], v[178:181], v[128:131]
	v_mfma_f32_16x16x32_bf16 v[128:131], v[146:149], v[182:185], v[128:131]
	v_mfma_f32_16x16x32_bf16 v[124:127], v[154:157], v[178:181], v[124:127]
	v_mfma_f32_16x16x32_bf16 v[124:127], v[158:161], v[182:185], v[124:127]
	v_mfma_f32_16x16x32_bf16 v[108:111], v[154:157], v[186:189], v[108:111]
	v_mfma_f32_16x16x32_bf16 v[108:111], v[158:161], v[190:193], v[108:111]
	v_mfma_f32_16x16x32_bf16 v[116:119], v[142:145], v[186:189], v[116:119]
	v_mfma_f32_16x16x32_bf16 v[116:119], v[146:149], v[190:193], v[116:119]
	v_mfma_f32_16x16x32_bf16 v[100:103], v[142:145], v[194:197], v[100:103]
	v_mfma_f32_16x16x32_bf16 v[100:103], v[146:149], v[214:217], v[100:103]
	v_mfma_f32_16x16x32_bf16 v[92:95], v[154:157], v[194:197], v[92:95]
	v_mfma_f32_16x16x32_bf16 v[92:95], v[158:161], v[214:217], v[92:95]
	v_mfma_f32_16x16x32_bf16 v[76:79], v[154:157], v[218:221], v[76:79]
	v_mfma_f32_16x16x32_bf16 v[76:79], v[158:161], v[234:237], v[76:79]
	v_mfma_f32_16x16x32_bf16 v[84:87], v[142:145], v[218:221], v[84:87]
	v_mfma_f32_16x16x32_bf16 v[84:87], v[146:149], v[234:237], v[84:87]
	v_mfma_f32_16x16x32_bf16 v[120:123], v[162:165], v[178:181], v[120:123]
	v_mfma_f32_16x16x32_bf16 v[120:123], v[166:169], v[182:185], v[120:123]
	v_mfma_f32_16x16x32_bf16 v[112:115], v[170:173], v[178:181], v[112:115]
	v_mfma_f32_16x16x32_bf16 v[112:115], v[174:177], v[182:185], v[112:115]
	v_mfma_f32_16x16x32_bf16 v[96:99], v[170:173], v[186:189], v[96:99]
	v_mfma_f32_16x16x32_bf16 v[96:99], v[174:177], v[190:193], v[96:99]
	v_mfma_f32_16x16x32_bf16 v[104:107], v[162:165], v[186:189], v[104:107]
	v_mfma_f32_16x16x32_bf16 v[104:107], v[166:169], v[190:193], v[104:107]
	v_mfma_f32_16x16x32_bf16 v[88:91], v[162:165], v[194:197], v[88:91]
	v_mfma_f32_16x16x32_bf16 v[88:91], v[166:169], v[214:217], v[88:91]
	v_mfma_f32_16x16x32_bf16 v[80:83], v[170:173], v[194:197], v[80:83]
	v_mfma_f32_16x16x32_bf16 v[80:83], v[174:177], v[214:217], v[80:83]
	v_mfma_f32_16x16x32_bf16 v[68:71], v[170:173], v[218:221], v[68:71]
	v_mfma_f32_16x16x32_bf16 v[68:71], v[174:177], v[234:237], v[68:71]
	v_mfma_f32_16x16x32_bf16 v[72:75], v[162:165], v[218:221], v[72:75]
	v_mfma_f32_16x16x32_bf16 v[72:75], v[166:169], v[234:237], v[72:75]
	s_barrier
	ds_read_b128 v[178:181], v153 offset:16384
	ds_read_b128 v[182:185], v153 offset:17408
	ds_read_b128 v[186:189], v153 offset:18432
	ds_read_b128 v[190:193], v153 offset:19456
	ds_read_b128 v[194:197], v153 offset:20480
	ds_read_b128 v[214:217], v153 offset:21504
	ds_read_b128 v[218:221], v153 offset:22528
	ds_read_b128 v[234:237], v153 offset:23552
	s_add_i32 s61, s61, s8
	s_mov_b32 m0, s61
	s_nop 0
	global_load_lds_dwordx4 v2, s[0:1]
	s_add_i32 m0, s61, 0x2000
	s_add_u32 s62, s0, 0x100000
	s_addc_u32 s63, s1, 0
	s_add_i32 s61, s64, s8
	global_load_lds_dwordx4 v132, s[0:1]
	s_mov_b32 m0, s61
	s_nop 0
	global_load_lds_dwordx4 v2, s[62:63]
	s_add_i32 m0, s61, 0x2000
	s_nop 0
	global_load_lds_dwordx4 v132, s[62:63]
	s_waitcnt vmcnt(6)
	s_waitcnt lgkmcnt(0)
	s_barrier
	v_mfma_f32_16x16x32_bf16 v[64:67], v[142:145], v[178:181], v[64:67]
	v_mfma_f32_16x16x32_bf16 v[64:67], v[146:149], v[182:185], v[64:67]
	v_mfma_f32_16x16x32_bf16 v[60:63], v[154:157], v[178:181], v[60:63]
	v_mfma_f32_16x16x32_bf16 v[60:63], v[158:161], v[182:185], v[60:63]
	v_mfma_f32_16x16x32_bf16 v[44:47], v[154:157], v[186:189], v[44:47]
	v_mfma_f32_16x16x32_bf16 v[44:47], v[158:161], v[190:193], v[44:47]
	v_mfma_f32_16x16x32_bf16 v[52:55], v[142:145], v[186:189], v[52:55]
	v_mfma_f32_16x16x32_bf16 v[52:55], v[146:149], v[190:193], v[52:55]
	v_mfma_f32_16x16x32_bf16 v[36:39], v[142:145], v[194:197], v[36:39]
	v_mfma_f32_16x16x32_bf16 v[36:39], v[146:149], v[214:217], v[36:39]
	v_mfma_f32_16x16x32_bf16 v[28:31], v[154:157], v[194:197], v[28:31]
	v_mfma_f32_16x16x32_bf16 v[28:31], v[158:161], v[214:217], v[28:31]
	v_mfma_f32_16x16x32_bf16 v[12:15], v[154:157], v[218:221], v[12:15]
	v_mfma_f32_16x16x32_bf16 v[12:15], v[158:161], v[234:237], v[12:15]
	v_mfma_f32_16x16x32_bf16 v[16:19], v[142:145], v[218:221], v[16:19]
	v_mfma_f32_16x16x32_bf16 v[16:19], v[146:149], v[234:237], v[16:19]
	v_mfma_f32_16x16x32_bf16 v[56:59], v[162:165], v[178:181], v[56:59]
	v_mfma_f32_16x16x32_bf16 v[56:59], v[166:169], v[182:185], v[56:59]
	v_mfma_f32_16x16x32_bf16 v[48:51], v[170:173], v[178:181], v[48:51]
	v_mfma_f32_16x16x32_bf16 v[48:51], v[174:177], v[182:185], v[48:51]
	v_mfma_f32_16x16x32_bf16 v[32:35], v[170:173], v[186:189], v[32:35]
	v_mfma_f32_16x16x32_bf16 v[32:35], v[174:177], v[190:193], v[32:35]
	v_mfma_f32_16x16x32_bf16 v[40:43], v[162:165], v[186:189], v[40:43]
	v_mfma_f32_16x16x32_bf16 v[40:43], v[166:169], v[190:193], v[40:43]
	v_mfma_f32_16x16x32_bf16 v[24:27], v[162:165], v[194:197], v[24:27]
	v_mfma_f32_16x16x32_bf16 v[24:27], v[166:169], v[214:217], v[24:27]
	v_mfma_f32_16x16x32_bf16 v[20:23], v[170:173], v[194:197], v[20:23]
	v_mfma_f32_16x16x32_bf16 v[20:23], v[174:177], v[214:217], v[20:23]
	v_mfma_f32_16x16x32_bf16 v[4:7], v[170:173], v[218:221], v[4:7]
	v_mfma_f32_16x16x32_bf16 v[4:7], v[174:177], v[234:237], v[4:7]
	v_mfma_f32_16x16x32_bf16 v[8:11], v[162:165], v[218:221], v[8:11]
	v_mfma_f32_16x16x32_bf16 v[8:11], v[166:169], v[234:237], v[8:11]
	s_barrier
; #define PG8_STAGE(bufoff, gbase, voff) do { _Pragma("unroll") for (int _i = 0; _i < 2; ++_i) \
;         __builtin_amdgcn_global_load_lds((const unsigned*)((const char*)(gbase) + (voff)[_i]), (PG8_LAS unsigned*)(lds + (bufoff) + ldsw + _i * 8192), 16, 0, 0); } while (0)
; #define PG8_LDA(dst, b, h) do { _Pragma("unroll") for (int m = 0; m < 4; ++m) _Pragma("unroll") for (int k = 0; k < 2; ++k) dst[m][k] = *(const PG8_LAS bf16x8*)(lds + PG8_SA(b, h) + aoff + m * 2048 + k * 1024); } while (0)
; #define PG8_LDB(dst, b, h) do { _Pragma("unroll") for (int n = 0; n < 2; ++n) _Pragma("unroll") for (int k = 0; k < 2; ++k) dst[n][k] = *(const PG8_LAS bf16x8*)(lds + PG8_SB(b, h) + boff + n * 2048 + k * 1024); } while (0)
; #define PG8_MMA(ai, bj, At, Bt) do { __builtin_amdgcn_s_setprio(1); _Pragma("unroll") for (int m = 0; m < 4; ++m) _Pragma("unroll") for (int n = 0; n < 2; ++n) _Pragma("unroll") for (int k = 0; k < 2; ++k) \
;         acc[ai][bj][m][n] = __builtin_amdgcn_mfma_f32_16x16x32_bf16(Bt[n][k], At[m][k], acc[ai][bj][m][n], 0, 0, 0); __builtin_amdgcn_s_setprio(0); } while (0)
; #define PG8_WAIT_V(n) asm volatile("s_waitcnt vmcnt(" #n ")" ::: "memory")
; #define PG8_WAIT_L(n) asm volatile("s_waitcnt lgkmcnt(" #n ")" ::: "memory")
; #define PG8_BAR __builtin_amdgcn_s_barrier()
; #define PG8_SCHED __builtin_amdgcn_sched_barrier(0)
; template <class Epi, class Sched, bool ALIGN_EPI = false, bool SP2 = false>
; __device__ __forceinline__ void gemm_phase(PG8_LAS unsigned char* lds, const Gemm g, const Sched& S, const Epi& E) {
;     ...
;         for (int t = 0; t < nt; t += 2) {
;             const bool last = (t == nt - 2);
;     ...
;             PG8_LDB(B0, 1, 0); PG8_LDB(B1, 1, 1); PG8_SCHED; PG8_LDA(At, 1, 0); PG8_STAGE(PG8_SA(0, 1), a2 + hstep, voffA);
;             PG8_WAIT_V(8); PG8_WAIT_L(0); PG8_BAR; PG8_MMA(0, 0, At, B0); PG8_MMA(0, 1, At, B1); PG8_BAR; PG8_SCHED;
;             PG8_LDA(At, 1, 1); PG8_STAGE(PG8_SB(1, 0), b3, voffB); PG8_STAGE(PG8_SB(1, 1), b3 + hstep, voffB); PG8_STAGE(PG8_SA(1, 0), a3, voffA);
;             PG8_WAIT_V(8); PG8_WAIT_L(0); PG8_BAR; PG8_MMA(1, 0, At, B0); PG8_MMA(1, 1, At, B1); PG8_BAR; PG8_SCHED;
	ds_read_b128 v[142:145], v198 offset:32768
	ds_read_b128 v[146:149], v198 offset:33792
	ds_read_b128 v[154:157], v198 offset:34816
	ds_read_b128 v[158:161], v198 offset:35840
	ds_read_b128 v[162:165], v198 offset:49152
	ds_read_b128 v[166:169], v198 offset:50176
	ds_read_b128 v[170:173], v198 offset:51200
	ds_read_b128 v[174:177], v198 offset:52224
	ds_read_b128 v[178:181], v153 offset:32768
	ds_read_b128 v[182:185], v153 offset:33792
	ds_read_b128 v[186:189], v153 offset:34816
	ds_read_b128 v[190:193], v153 offset:35840
	ds_read_b128 v[194:197], v153 offset:36864
	ds_read_b128 v[214:217], v153 offset:37888
	ds_read_b128 v[218:221], v153 offset:38912
	ds_read_b128 v[234:237], v153 offset:39936
	s_add_i32 s61, 0, 0x18000
	s_add_i32 s62, 0, 0x1c000
	s_mov_b32 m0, s9
	s_nop 0
	global_load_lds_dwordx4 v136, s[26:27]
	s_mov_b32 m0, s10
	s_nop 0
	global_load_lds_dwordx4 v134, s[26:27]
	s_add_u32 s26, s26, 0x100000
	s_addc_u32 s27, s27, 0
	s_mov_b32 m0, s11
	s_nop 0
	global_load_lds_dwordx4 v136, s[26:27]
	s_mov_b32 m0, s52
	s_nop 0
	global_load_lds_dwordx4 v134, s[26:27]
	s_nop 0
	s_waitcnt vmcnt(8)
	s_waitcnt lgkmcnt(0)
	s_barrier
	v_mfma_f32_16x16x32_bf16 v[128:131], v[142:145], v[178:181], v[128:131]
	v_mfma_f32_16x16x32_bf16 v[128:131], v[146:149], v[182:185], v[128:131]
	v_mfma_f32_16x16x32_bf16 v[124:127], v[154:157], v[178:181], v[124:127]
	v_mfma_f32_16x16x32_bf16 v[124:127], v[158:161], v[182:185], v[124:127]
	v_mfma_f32_16x16x32_bf16 v[108:111], v[154:157], v[186:189], v[108:111]
	v_mfma_f32_16x16x32_bf16 v[108:111], v[158:161], v[190:193], v[108:111]
	v_mfma_f32_16x16x32_bf16 v[116:119], v[142:145], v[186:189], v[116:119]
	v_mfma_f32_16x16x32_bf16 v[116:119], v[146:149], v[190:193], v[116:119]
	v_mfma_f32_16x16x32_bf16 v[100:103], v[142:145], v[194:197], v[100:103]
	v_mfma_f32_16x16x32_bf16 v[100:103], v[146:149], v[214:217], v[100:103]
	v_mfma_f32_16x16x32_bf16 v[92:95], v[154:157], v[194:197], v[92:95]
	v_mfma_f32_16x16x32_bf16 v[92:95], v[158:161], v[214:217], v[92:95]
	v_mfma_f32_16x16x32_bf16 v[76:79], v[154:157], v[218:221], v[76:79]
	v_mfma_f32_16x16x32_bf16 v[76:79], v[158:161], v[234:237], v[76:79]
	v_mfma_f32_16x16x32_bf16 v[84:87], v[142:145], v[218:221], v[84:87]
	v_mfma_f32_16x16x32_bf16 v[84:87], v[146:149], v[234:237], v[84:87]
	v_mfma_f32_16x16x32_bf16 v[120:123], v[162:165], v[178:181], v[120:123]
	v_mfma_f32_16x16x32_bf16 v[120:123], v[166:169], v[182:185], v[120:123]
	v_mfma_f32_16x16x32_bf16 v[112:115], v[170:173], v[178:181], v[112:115]
	v_mfma_f32_16x16x32_bf16 v[112:115], v[174:177], v[182:185], v[112:115]
	v_mfma_f32_16x16x32_bf16 v[96:99], v[170:173], v[186:189], v[96:99]
	v_mfma_f32_16x16x32_bf16 v[96:99], v[174:177], v[190:193], v[96:99]
	v_mfma_f32_16x16x32_bf16 v[104:107], v[162:165], v[186:189], v[104:107]
	v_mfma_f32_16x16x32_bf16 v[104:107], v[166:169], v[190:193], v[104:107]
	v_mfma_f32_16x16x32_bf16 v[88:91], v[162:165], v[194:197], v[88:91]
	v_mfma_f32_16x16x32_bf16 v[88:91], v[166:169], v[214:217], v[88:91]
	v_mfma_f32_16x16x32_bf16 v[80:83], v[170:173], v[194:197], v[80:83]
	v_mfma_f32_16x16x32_bf16 v[80:83], v[174:177], v[214:217], v[80:83]
	v_mfma_f32_16x16x32_bf16 v[68:71], v[170:173], v[218:221], v[68:71]
	v_mfma_f32_16x16x32_bf16 v[68:71], v[174:177], v[234:237], v[68:71]
	v_mfma_f32_16x16x32_bf16 v[72:75], v[162:165], v[218:221], v[72:75]
	v_mfma_f32_16x16x32_bf16 v[72:75], v[166:169], v[234:237], v[72:75]
	s_barrier
	ds_read_b128 v[178:181], v153 offset:49152
	ds_read_b128 v[182:185], v153 offset:50176
	ds_read_b128 v[186:189], v153 offset:51200
	ds_read_b128 v[190:193], v153 offset:52224
	ds_read_b128 v[194:197], v153 offset:53248
	ds_read_b128 v[214:217], v153 offset:54272
	ds_read_b128 v[218:221], v153 offset:55296
	ds_read_b128 v[234:237], v153 offset:56320
	s_add_i32 s26, s61, s8
	s_mov_b32 m0, s26
	s_add_u32 s0, s0, 0x80
	s_addc_u32 s1, s1, 0
	global_load_lds_dwordx4 v2, s[0:1]
	s_add_i32 m0, s26, 0x2000
	s_add_i32 s26, s62, s8
	global_load_lds_dwordx4 v132, s[0:1]
	s_add_u32 s0, s0, 0x100000
	s_addc_u32 s1, s1, 0
	s_mov_b32 m0, s26
	s_nop 0
	global_load_lds_dwordx4 v2, s[0:1]
	s_add_i32 m0, s26, 0x2000
	s_nop 0
	global_load_lds_dwordx4 v132, s[0:1]
	s_waitcnt vmcnt(6)
	s_waitcnt lgkmcnt(0)
	s_barrier
	v_mfma_f32_16x16x32_bf16 v[64:67], v[142:145], v[178:181], v[64:67]
	v_mfma_f32_16x16x32_bf16 v[64:67], v[146:149], v[182:185], v[64:67]
	v_mfma_f32_16x16x32_bf16 v[60:63], v[154:157], v[178:181], v[60:63]
	v_mfma_f32_16x16x32_bf16 v[60:63], v[158:161], v[182:185], v[60:63]
	v_mfma_f32_16x16x32_bf16 v[44:47], v[154:157], v[186:189], v[44:47]
	v_mfma_f32_16x16x32_bf16 v[44:47], v[158:161], v[190:193], v[44:47]
	v_mfma_f32_16x16x32_bf16 v[52:55], v[142:145], v[186:189], v[52:55]
	v_mfma_f32_16x16x32_bf16 v[52:55], v[146:149], v[190:193], v[52:55]
	v_mfma_f32_16x16x32_bf16 v[36:39], v[142:145], v[194:197], v[36:39]
	v_mfma_f32_16x16x32_bf16 v[36:39], v[146:149], v[214:217], v[36:39]
	v_mfma_f32_16x16x32_bf16 v[28:31], v[154:157], v[194:197], v[28:31]
	v_mfma_f32_16x16x32_bf16 v[28:31], v[158:161], v[214:217], v[28:31]
	v_mfma_f32_16x16x32_bf16 v[12:15], v[154:157], v[218:221], v[12:15]
	v_mfma_f32_16x16x32_bf16 v[12:15], v[158:161], v[234:237], v[12:15]
	v_mfma_f32_16x16x32_bf16 v[16:19], v[142:145], v[218:221], v[16:19]
	v_mfma_f32_16x16x32_bf16 v[16:19], v[146:149], v[234:237], v[16:19]
	s_add_i32 s60, s60, 2
	s_add_u32 s50, s50, 0x100
	s_addc_u32 s51, s51, 0
	s_add_u32 s43, s43, 0x100
	s_addc_u32 s45, s45, 0
	s_nop 0
	v_mfma_f32_16x16x32_bf16 v[56:59], v[162:165], v[178:181], v[56:59]
	v_mfma_f32_16x16x32_bf16 v[56:59], v[166:169], v[182:185], v[56:59]
	v_mfma_f32_16x16x32_bf16 v[48:51], v[170:173], v[178:181], v[48:51]
	v_mfma_f32_16x16x32_bf16 v[48:51], v[174:177], v[182:185], v[48:51]
	v_mfma_f32_16x16x32_bf16 v[32:35], v[170:173], v[186:189], v[32:35]
	v_mfma_f32_16x16x32_bf16 v[32:35], v[174:177], v[190:193], v[32:35]
	v_mfma_f32_16x16x32_bf16 v[40:43], v[162:165], v[186:189], v[40:43]
	v_mfma_f32_16x16x32_bf16 v[40:43], v[166:169], v[190:193], v[40:43]
	v_mfma_f32_16x16x32_bf16 v[24:27], v[162:165], v[194:197], v[24:27]
	v_mfma_f32_16x16x32_bf16 v[24:27], v[166:169], v[214:217], v[24:27]
	v_mfma_f32_16x16x32_bf16 v[20:23], v[170:173], v[194:197], v[20:23]
	v_mfma_f32_16x16x32_bf16 v[20:23], v[174:177], v[214:217], v[20:23]
	v_mfma_f32_16x16x32_bf16 v[4:7], v[170:173], v[218:221], v[4:7]
	v_mfma_f32_16x16x32_bf16 v[4:7], v[174:177], v[234:237], v[4:7]
	v_mfma_f32_16x16x32_bf16 v[8:11], v[162:165], v[218:221], v[8:11]
	v_mfma_f32_16x16x32_bf16 v[8:11], v[166:169], v[234:237], v[8:11]
	s_barrier
	s_cmp_gt_u32 s60, 61
	s_cbranch_scc0 .LBB0_816
	s_and_b64 vcc, exec, s[40:41]
	s_cbranch_vccz .LBB0_819
	s_barrier

; #define PG8_STAGE(bufoff, gbase, voff) do { _Pragma("unroll") for (int _i = 0; _i < 2; ++_i) \
;         __builtin_amdgcn_global_load_lds((const unsigned*)((const char*)(gbase) + (voff)[_i]), (PG8_LAS unsigned*)(lds + (bufoff) + ldsw + _i * 8192), 16, 0, 0); } while (0)
; #define PG8_LDA(dst, b, h) do { _Pragma("unroll") for (int m = 0; m < 4; ++m) _Pragma("unroll") for (int k = 0; k < 2; ++k) dst[m][k] = *(const PG8_LAS bf16x8*)(lds + PG8_SA(b, h) + aoff + m * 2048 + k * 1024); } while (0)
; #define PG8_LDB(dst, b, h) do { _Pragma("unroll") for (int n = 0; n < 2; ++n) _Pragma("unroll") for (int k = 0; k < 2; ++k) dst[n][k] = *(const PG8_LAS bf16x8*)(lds + PG8_SB(b, h) + boff + n * 2048 + k * 1024); } while (0)
; #define PG8_MMA(ai, bj, At, Bt) do { __builtin_amdgcn_s_setprio(1); _Pragma("unroll") for (int m = 0; m < 4; ++m) _Pragma("unroll") for (int n = 0; n < 2; ++n) _Pragma("unroll") for (int k = 0; k < 2; ++k) \
;         acc[ai][bj][m][n] = __builtin_amdgcn_mfma_f32_16x16x32_bf16(Bt[n][k], At[m][k], acc[ai][bj][m][n], 0, 0, 0); __builtin_amdgcn_s_setprio(0); } while (0)
; #define PG8_WAIT_V(n) asm volatile("s_waitcnt vmcnt(" #n ")" ::: "memory")
; #define PG8_WAIT_L(n) asm volatile("s_waitcnt lgkmcnt(" #n ")" ::: "memory")
; #define PG8_BAR __builtin_amdgcn_s_barrier()
; #define PG8_SCHED __builtin_amdgcn_sched_barrier(0)
; template <class Epi, class Sched, bool ALIGN_EPI = false, bool SP2 = false>
; __device__ __forceinline__ void gemm_phase(PG8_LAS unsigned char* lds, const Gemm g, const Sched& S, const Epi& E) {
;     ...
;             PG8_LDB(B0, 0, 0); PG8_LDB(B1, 0, 1); PG8_SCHED; PG8_LDA(At, 0, 0); PG8_STAGE(PG8_SA(1, 1), a1 + hstep, voffA);
;             PG8_WAIT_V(8); PG8_WAIT_L(0); PG8_BAR; PG8_MMA(0, 0, At, B0); PG8_MMA(0, 1, At, B1); PG8_BAR; PG8_SCHED;
;             PG8_LDA(At, 0, 1); PG8_STAGE(PG8_SB(0, 0), b2, voffB); PG8_STAGE(PG8_SB(0, 1), b2 + hstep, voffB); PG8_STAGE(PG8_SA(0, 0), a2, voffA);
;             PG8_WAIT_V(8); PG8_WAIT_L(0); PG8_BAR; PG8_MMA(1, 0, At, B0); PG8_MMA(1, 1, At, B1); PG8_BAR; PG8_SCHED;
.LBB0_1032:
	ds_read_b128 v[146:149], v198
	ds_read_b128 v[150:153], v198 offset:1024
	ds_read_b128 v[154:157], v198 offset:2048
	ds_read_b128 v[158:161], v198 offset:3072
	ds_read_b128 v[162:165], v198 offset:16384
	ds_read_b128 v[166:169], v198 offset:17408
	ds_read_b128 v[170:173], v198 offset:18432
	ds_read_b128 v[174:177], v198 offset:19456
	ds_read_b128 v[178:181], v145
	ds_read_b128 v[182:185], v145 offset:1024
	ds_read_b128 v[186:189], v145 offset:2048
	ds_read_b128 v[190:193], v145 offset:3072
	ds_read_b128 v[194:197], v145 offset:4096
	ds_read_b128 v[214:217], v145 offset:5120
	ds_read_b128 v[218:221], v145 offset:6144
	ds_read_b128 v[234:237], v145 offset:7168
	s_add_u32 s0, s50, 0xfffc0080
	s_addc_u32 s1, s51, -1
	s_add_i32 s53, 0, 0x10000
	s_cmp_eq_u32 s52, 12
	s_cselect_b32 s27, s47, s1
	s_cselect_b32 s26, s46, s0
	s_cselect_b32 s1, s49, s45
	s_cselect_b32 s0, s48, s43
	s_add_i32 s64, 0, 0x14000
	s_add_u32 s100, s50, 0xfffc0000
	s_addc_u32 s101, s51, -1
	s_mov_b32 m0, s57
	s_nop 0
	global_load_lds_dwordx4 v136, s[100:101]
	s_mov_b32 m0, s58
	s_nop 0
	global_load_lds_dwordx4 v134, s[100:101]
	s_add_i32 m0, s37, 0xc000
	s_nop 0
	global_load_lds_dwordx4 v138, s[50:51]
	s_add_i32 m0, s37, 0xe000
	s_nop 0
	global_load_lds_dwordx4 v140, s[50:51]
	s_nop 0
	s_waitcnt vmcnt(8)
	s_waitcnt lgkmcnt(0)
	s_barrier
	v_mfma_f32_16x16x32_bf16 v[128:131], v[146:149], v[178:181], v[128:131]
	v_mfma_f32_16x16x32_bf16 v[128:131], v[150:153], v[182:185], v[128:131]
	v_mfma_f32_16x16x32_bf16 v[124:127], v[154:157], v[178:181], v[124:127]
	v_mfma_f32_16x16x32_bf16 v[124:127], v[158:161], v[182:185], v[124:127]
	v_mfma_f32_16x16x32_bf16 v[116:119], v[154:157], v[186:189], v[116:119]
	v_mfma_f32_16x16x32_bf16 v[116:119], v[158:161], v[190:193], v[116:119]
	v_mfma_f32_16x16x32_bf16 v[120:123], v[146:149], v[186:189], v[120:123]
	v_mfma_f32_16x16x32_bf16 v[120:123], v[150:153], v[190:193], v[120:123]
	v_mfma_f32_16x16x32_bf16 v[104:107], v[146:149], v[194:197], v[104:107]
	v_mfma_f32_16x16x32_bf16 v[104:107], v[150:153], v[214:217], v[104:107]
	v_mfma_f32_16x16x32_bf16 v[100:103], v[154:157], v[194:197], v[100:103]
	v_mfma_f32_16x16x32_bf16 v[100:103], v[158:161], v[214:217], v[100:103]
	v_mfma_f32_16x16x32_bf16 v[84:87], v[154:157], v[218:221], v[84:87]
	v_mfma_f32_16x16x32_bf16 v[84:87], v[158:161], v[234:237], v[84:87]
	v_mfma_f32_16x16x32_bf16 v[88:91], v[146:149], v[218:221], v[88:91]
	v_mfma_f32_16x16x32_bf16 v[88:91], v[150:153], v[234:237], v[88:91]
	v_mfma_f32_16x16x32_bf16 v[112:115], v[162:165], v[178:181], v[112:115]
	v_mfma_f32_16x16x32_bf16 v[112:115], v[166:169], v[182:185], v[112:115]
	v_mfma_f32_16x16x32_bf16 v[108:111], v[170:173], v[178:181], v[108:111]
	v_mfma_f32_16x16x32_bf16 v[108:111], v[174:177], v[182:185], v[108:111]
	v_mfma_f32_16x16x32_bf16 v[92:95], v[170:173], v[186:189], v[92:95]
	v_mfma_f32_16x16x32_bf16 v[92:95], v[174:177], v[190:193], v[92:95]
	v_mfma_f32_16x16x32_bf16 v[96:99], v[162:165], v[186:189], v[96:99]
	v_mfma_f32_16x16x32_bf16 v[96:99], v[166:169], v[190:193], v[96:99]
	v_mfma_f32_16x16x32_bf16 v[80:83], v[162:165], v[194:197], v[80:83]
	v_mfma_f32_16x16x32_bf16 v[80:83], v[166:169], v[214:217], v[80:83]
	v_mfma_f32_16x16x32_bf16 v[76:79], v[170:173], v[194:197], v[76:79]
	v_mfma_f32_16x16x32_bf16 v[76:79], v[174:177], v[214:217], v[76:79]
	v_mfma_f32_16x16x32_bf16 v[68:71], v[170:173], v[218:221], v[68:71]
	v_mfma_f32_16x16x32_bf16 v[68:71], v[174:177], v[234:237], v[68:71]
	v_mfma_f32_16x16x32_bf16 v[72:75], v[162:165], v[218:221], v[72:75]
	v_mfma_f32_16x16x32_bf16 v[72:75], v[166:169], v[234:237], v[72:75]
	s_barrier
	ds_read_b128 v[178:181], v145 offset:16384
	ds_read_b128 v[182:185], v145 offset:17408
	ds_read_b128 v[186:189], v145 offset:18432
	ds_read_b128 v[190:193], v145 offset:19456
	ds_read_b128 v[194:197], v145 offset:20480
	ds_read_b128 v[214:217], v145 offset:21504
	ds_read_b128 v[218:221], v145 offset:22528
	ds_read_b128 v[234:237], v145 offset:23552
	s_add_i32 s53, s53, s10
	s_mov_b32 m0, s53
	s_nop 0
	global_load_lds_dwordx4 v2, s[0:1]
	s_add_i32 m0, s53, 0x2000
	s_add_u32 s62, s0, 0x40000
	s_addc_u32 s63, s1, 0
	s_add_i32 s53, s64, s10
	global_load_lds_dwordx4 v132, s[0:1]
	s_mov_b32 m0, s53
	s_nop 0
	global_load_lds_dwordx4 v2, s[62:63]
	s_add_i32 m0, s53, 0x2000
	s_nop 0
	global_load_lds_dwordx4 v132, s[62:63]
	s_waitcnt vmcnt(6)
	s_waitcnt lgkmcnt(0)
	s_barrier
	v_mfma_f32_16x16x32_bf16 v[64:67], v[146:149], v[178:181], v[64:67]
	v_mfma_f32_16x16x32_bf16 v[64:67], v[150:153], v[182:185], v[64:67]
	v_mfma_f32_16x16x32_bf16 v[60:63], v[154:157], v[178:181], v[60:63]
	v_mfma_f32_16x16x32_bf16 v[60:63], v[158:161], v[182:185], v[60:63]
	v_mfma_f32_16x16x32_bf16 v[52:55], v[154:157], v[186:189], v[52:55]
	v_mfma_f32_16x16x32_bf16 v[52:55], v[158:161], v[190:193], v[52:55]
	v_mfma_f32_16x16x32_bf16 v[56:59], v[146:149], v[186:189], v[56:59]
	v_mfma_f32_16x16x32_bf16 v[56:59], v[150:153], v[190:193], v[56:59]
	v_mfma_f32_16x16x32_bf16 v[40:43], v[146:149], v[194:197], v[40:43]
	v_mfma_f32_16x16x32_bf16 v[40:43], v[150:153], v[214:217], v[40:43]
	v_mfma_f32_16x16x32_bf16 v[36:39], v[154:157], v[194:197], v[36:39]
	v_mfma_f32_16x16x32_bf16 v[36:39], v[158:161], v[214:217], v[36:39]
	v_mfma_f32_16x16x32_bf16 v[20:23], v[154:157], v[218:221], v[20:23]
	v_mfma_f32_16x16x32_bf16 v[20:23], v[158:161], v[234:237], v[20:23]
	v_mfma_f32_16x16x32_bf16 v[24:27], v[146:149], v[218:221], v[24:27]
	v_mfma_f32_16x16x32_bf16 v[24:27], v[150:153], v[234:237], v[24:27]
	v_mfma_f32_16x16x32_bf16 v[48:51], v[162:165], v[178:181], v[48:51]
	v_mfma_f32_16x16x32_bf16 v[48:51], v[166:169], v[182:185], v[48:51]
	v_mfma_f32_16x16x32_bf16 v[44:47], v[170:173], v[178:181], v[44:47]
	v_mfma_f32_16x16x32_bf16 v[44:47], v[174:177], v[182:185], v[44:47]
	v_mfma_f32_16x16x32_bf16 v[28:31], v[170:173], v[186:189], v[28:31]
	v_mfma_f32_16x16x32_bf16 v[28:31], v[174:177], v[190:193], v[28:31]
	v_mfma_f32_16x16x32_bf16 v[32:35], v[162:165], v[186:189], v[32:35]
	v_mfma_f32_16x16x32_bf16 v[32:35], v[166:169], v[190:193], v[32:35]
	v_mfma_f32_16x16x32_bf16 v[16:19], v[162:165], v[194:197], v[16:19]
	v_mfma_f32_16x16x32_bf16 v[16:19], v[166:169], v[214:217], v[16:19]
	v_mfma_f32_16x16x32_bf16 v[12:15], v[170:173], v[194:197], v[12:15]
	v_mfma_f32_16x16x32_bf16 v[12:15], v[174:177], v[214:217], v[12:15]
	v_mfma_f32_16x16x32_bf16 v[4:7], v[170:173], v[218:221], v[4:7]
	v_mfma_f32_16x16x32_bf16 v[4:7], v[174:177], v[234:237], v[4:7]
	v_mfma_f32_16x16x32_bf16 v[8:11], v[162:165], v[218:221], v[8:11]
	v_mfma_f32_16x16x32_bf16 v[8:11], v[166:169], v[234:237], v[8:11]
	s_barrier
; #define PG8_STAGE(bufoff, gbase, voff) do { _Pragma("unroll") for (int _i = 0; _i < 2; ++_i) \
;         __builtin_amdgcn_global_load_lds((const unsigned*)((const char*)(gbase) + (voff)[_i]), (PG8_LAS unsigned*)(lds + (bufoff) + ldsw + _i * 8192), 16, 0, 0); } while (0)
; #define PG8_LDA(dst, b, h) do { _Pragma("unroll") for (int m = 0; m < 4; ++m) _Pragma("unroll") for (int k = 0; k < 2; ++k) dst[m][k] = *(const PG8_LAS bf16x8*)(lds + PG8_SA(b, h) + aoff + m * 2048 + k * 1024); } while (0)
; #define PG8_LDB(dst, b, h) do { _Pragma("unroll") for (int n = 0; n < 2; ++n) _Pragma("unroll") for (int k = 0; k < 2; ++k) dst[n][k] = *(const PG8_LAS bf16x8*)(lds + PG8_SB(b, h) + boff + n * 2048 + k * 1024); } while (0)
; #define PG8_MMA(ai, bj, At, Bt) do { __builtin_amdgcn_s_setprio(1); _Pragma("unroll") for (int m = 0; m < 4; ++m) _Pragma("unroll") for (int n = 0; n < 2; ++n) _Pragma("unroll") for (int k = 0; k < 2; ++k) \
;         acc[ai][bj][m][n] = __builtin_amdgcn_mfma_f32_16x16x32_bf16(Bt[n][k], At[m][k], acc[ai][bj][m][n], 0, 0, 0); __builtin_amdgcn_s_setprio(0); } while (0)
; #define PG8_WAIT_V(n) asm volatile("s_waitcnt vmcnt(" #n ")" ::: "memory")
; #define PG8_WAIT_L(n) asm volatile("s_waitcnt lgkmcnt(" #n ")" ::: "memory")
; #define PG8_BAR __builtin_amdgcn_s_barrier()
; #define PG8_SCHED __builtin_amdgcn_sched_barrier(0)
; template <class Epi, class Sched, bool ALIGN_EPI = false, bool SP2 = false>
; __device__ __forceinline__ void gemm_phase(PG8_LAS unsigned char* lds, const Gemm g, const Sched& S, const Epi& E) {
;     ...
;         for (int t = 0; t < nt; t += 2) {
;             const bool last = (t == nt - 2);
;     ...
;             PG8_LDB(B0, 1, 0); PG8_LDB(B1, 1, 1); PG8_SCHED; PG8_LDA(At, 1, 0); PG8_STAGE(PG8_SA(0, 1), a2 + hstep, voffA);
;             PG8_WAIT_V(8); PG8_WAIT_L(0); PG8_BAR; PG8_MMA(0, 0, At, B0); PG8_MMA(0, 1, At, B1); PG8_BAR; PG8_SCHED;
;             PG8_LDA(At, 1, 1); PG8_STAGE(PG8_SB(1, 0), b3, voffB); PG8_STAGE(PG8_SB(1, 1), b3 + hstep, voffB); PG8_STAGE(PG8_SA(1, 0), a3, voffA);
;             PG8_WAIT_V(8); PG8_WAIT_L(0); PG8_BAR; PG8_MMA(1, 0, At, B0); PG8_MMA(1, 1, At, B1); PG8_BAR; PG8_SCHED;
	ds_read_b128 v[146:149], v198 offset:32768
	ds_read_b128 v[150:153], v198 offset:33792
	ds_read_b128 v[154:157], v198 offset:34816
	ds_read_b128 v[158:161], v198 offset:35840
	ds_read_b128 v[162:165], v198 offset:49152
	ds_read_b128 v[166:169], v198 offset:50176
	ds_read_b128 v[170:173], v198 offset:51200
	ds_read_b128 v[174:177], v198 offset:52224
	ds_read_b128 v[178:181], v145 offset:32768
	ds_read_b128 v[182:185], v145 offset:33792
	ds_read_b128 v[186:189], v145 offset:34816
	ds_read_b128 v[190:193], v145 offset:35840
	ds_read_b128 v[194:197], v145 offset:36864
	ds_read_b128 v[214:217], v145 offset:37888
	ds_read_b128 v[218:221], v145 offset:38912
	ds_read_b128 v[234:237], v145 offset:39936
	s_add_i32 s53, 0, 0x18000
	s_add_i32 s62, 0, 0x1c000
	s_mov_b32 m0, s37
	s_nop 0
	global_load_lds_dwordx4 v136, s[26:27]
	s_mov_b32 m0, s54
	s_nop 0
	global_load_lds_dwordx4 v134, s[26:27]
	s_add_u32 s26, s26, 0x40000
	s_addc_u32 s27, s27, 0
	s_mov_b32 m0, s55
	s_nop 0
	global_load_lds_dwordx4 v136, s[26:27]
	s_mov_b32 m0, s56
	s_nop 0
	global_load_lds_dwordx4 v134, s[26:27]
	s_nop 0
	s_waitcnt vmcnt(8)
	s_waitcnt lgkmcnt(0)
	s_barrier
	v_mfma_f32_16x16x32_bf16 v[128:131], v[146:149], v[178:181], v[128:131]
	v_mfma_f32_16x16x32_bf16 v[128:131], v[150:153], v[182:185], v[128:131]
	v_mfma_f32_16x16x32_bf16 v[124:127], v[154:157], v[178:181], v[124:127]
	v_mfma_f32_16x16x32_bf16 v[124:127], v[158:161], v[182:185], v[124:127]
	v_mfma_f32_16x16x32_bf16 v[116:119], v[154:157], v[186:189], v[116:119]
	v_mfma_f32_16x16x32_bf16 v[116:119], v[158:161], v[190:193], v[116:119]
	v_mfma_f32_16x16x32_bf16 v[120:123], v[146:149], v[186:189], v[120:123]
	v_mfma_f32_16x16x32_bf16 v[120:123], v[150:153], v[190:193], v[120:123]
	v_mfma_f32_16x16x32_bf16 v[104:107], v[146:149], v[194:197], v[104:107]
	v_mfma_f32_16x16x32_bf16 v[104:107], v[150:153], v[214:217], v[104:107]
	v_mfma_f32_16x16x32_bf16 v[100:103], v[154:157], v[194:197], v[100:103]
	v_mfma_f32_16x16x32_bf16 v[100:103], v[158:161], v[214:217], v[100:103]
	v_mfma_f32_16x16x32_bf16 v[84:87], v[154:157], v[218:221], v[84:87]
	v_mfma_f32_16x16x32_bf16 v[84:87], v[158:161], v[234:237], v[84:87]
	v_mfma_f32_16x16x32_bf16 v[88:91], v[146:149], v[218:221], v[88:91]
	v_mfma_f32_16x16x32_bf16 v[88:91], v[150:153], v[234:237], v[88:91]
	v_mfma_f32_16x16x32_bf16 v[112:115], v[162:165], v[178:181], v[112:115]
	v_mfma_f32_16x16x32_bf16 v[112:115], v[166:169], v[182:185], v[112:115]
	v_mfma_f32_16x16x32_bf16 v[108:111], v[170:173], v[178:181], v[108:111]
	v_mfma_f32_16x16x32_bf16 v[108:111], v[174:177], v[182:185], v[108:111]
	v_mfma_f32_16x16x32_bf16 v[92:95], v[170:173], v[186:189], v[92:95]
	v_mfma_f32_16x16x32_bf16 v[92:95], v[174:177], v[190:193], v[92:95]
	v_mfma_f32_16x16x32_bf16 v[96:99], v[162:165], v[186:189], v[96:99]
	v_mfma_f32_16x16x32_bf16 v[96:99], v[166:169], v[190:193], v[96:99]
	v_mfma_f32_16x16x32_bf16 v[80:83], v[162:165], v[194:197], v[80:83]
	v_mfma_f32_16x16x32_bf16 v[80:83], v[166:169], v[214:217], v[80:83]
	v_mfma_f32_16x16x32_bf16 v[76:79], v[170:173], v[194:197], v[76:79]
	v_mfma_f32_16x16x32_bf16 v[76:79], v[174:177], v[214:217], v[76:79]
	v_mfma_f32_16x16x32_bf16 v[68:71], v[170:173], v[218:221], v[68:71]
	v_mfma_f32_16x16x32_bf16 v[68:71], v[174:177], v[234:237], v[68:71]
	v_mfma_f32_16x16x32_bf16 v[72:75], v[162:165], v[218:221], v[72:75]
	v_mfma_f32_16x16x32_bf16 v[72:75], v[166:169], v[234:237], v[72:75]
	s_barrier
	ds_read_b128 v[178:181], v145 offset:49152
	ds_read_b128 v[182:185], v145 offset:50176
	ds_read_b128 v[186:189], v145 offset:51200
	ds_read_b128 v[190:193], v145 offset:52224
	ds_read_b128 v[194:197], v145 offset:53248
	ds_read_b128 v[214:217], v145 offset:54272
	ds_read_b128 v[218:221], v145 offset:55296
	ds_read_b128 v[234:237], v145 offset:56320
	s_add_i32 s26, s53, s10
	s_mov_b32 m0, s26
	s_add_u32 s0, s0, 0x80
	s_addc_u32 s1, s1, 0
	global_load_lds_dwordx4 v2, s[0:1]
	s_add_i32 m0, s26, 0x2000
	s_add_i32 s26, s62, s10
	global_load_lds_dwordx4 v132, s[0:1]
	s_add_u32 s0, s0, 0x40000
	s_addc_u32 s1, s1, 0
	s_mov_b32 m0, s26
	s_nop 0
	global_load_lds_dwordx4 v2, s[0:1]
	s_add_i32 m0, s26, 0x2000
	s_nop 0
	global_load_lds_dwordx4 v132, s[0:1]
	s_waitcnt vmcnt(6)
	s_waitcnt lgkmcnt(0)
	s_barrier
	v_mfma_f32_16x16x32_bf16 v[64:67], v[146:149], v[178:181], v[64:67]
	v_mfma_f32_16x16x32_bf16 v[64:67], v[150:153], v[182:185], v[64:67]
	v_mfma_f32_16x16x32_bf16 v[60:63], v[154:157], v[178:181], v[60:63]
	v_mfma_f32_16x16x32_bf16 v[60:63], v[158:161], v[182:185], v[60:63]
	v_mfma_f32_16x16x32_bf16 v[52:55], v[154:157], v[186:189], v[52:55]
	v_mfma_f32_16x16x32_bf16 v[52:55], v[158:161], v[190:193], v[52:55]
	v_mfma_f32_16x16x32_bf16 v[56:59], v[146:149], v[186:189], v[56:59]
	v_mfma_f32_16x16x32_bf16 v[56:59], v[150:153], v[190:193], v[56:59]
	v_mfma_f32_16x16x32_bf16 v[40:43], v[146:149], v[194:197], v[40:43]
	v_mfma_f32_16x16x32_bf16 v[40:43], v[150:153], v[214:217], v[40:43]
	v_mfma_f32_16x16x32_bf16 v[36:39], v[154:157], v[194:197], v[36:39]
	v_mfma_f32_16x16x32_bf16 v[36:39], v[158:161], v[214:217], v[36:39]
	v_mfma_f32_16x16x32_bf16 v[20:23], v[154:157], v[218:221], v[20:23]
	v_mfma_f32_16x16x32_bf16 v[20:23], v[158:161], v[234:237], v[20:23]
	v_mfma_f32_16x16x32_bf16 v[24:27], v[146:149], v[218:221], v[24:27]
	v_mfma_f32_16x16x32_bf16 v[24:27], v[150:153], v[234:237], v[24:27]
	s_add_i32 s52, s52, 2
	s_add_u32 s50, s50, 0x100
	s_addc_u32 s51, s51, 0
	s_add_u32 s43, s43, 0x100
	s_addc_u32 s45, s45, 0
	s_nop 0
	v_mfma_f32_16x16x32_bf16 v[48:51], v[162:165], v[178:181], v[48:51]
	v_mfma_f32_16x16x32_bf16 v[48:51], v[166:169], v[182:185], v[48:51]
	v_mfma_f32_16x16x32_bf16 v[44:47], v[170:173], v[178:181], v[44:47]
	v_mfma_f32_16x16x32_bf16 v[44:47], v[174:177], v[182:185], v[44:47]
	v_mfma_f32_16x16x32_bf16 v[28:31], v[170:173], v[186:189], v[28:31]
	v_mfma_f32_16x16x32_bf16 v[28:31], v[174:177], v[190:193], v[28:31]
	v_mfma_f32_16x16x32_bf16 v[32:35], v[162:165], v[186:189], v[32:35]
	v_mfma_f32_16x16x32_bf16 v[32:35], v[166:169], v[190:193], v[32:35]
	v_mfma_f32_16x16x32_bf16 v[16:19], v[162:165], v[194:197], v[16:19]
	v_mfma_f32_16x16x32_bf16 v[16:19], v[166:169], v[214:217], v[16:19]
	v_mfma_f32_16x16x32_bf16 v[12:15], v[170:173], v[194:197], v[12:15]
	v_mfma_f32_16x16x32_bf16 v[12:15], v[174:177], v[214:217], v[12:15]
	v_mfma_f32_16x16x32_bf16 v[4:7], v[170:173], v[218:221], v[4:7]
	v_mfma_f32_16x16x32_bf16 v[4:7], v[174:177], v[234:237], v[4:7]
	v_mfma_f32_16x16x32_bf16 v[8:11], v[162:165], v[218:221], v[8:11]
	v_mfma_f32_16x16x32_bf16 v[8:11], v[166:169], v[234:237], v[8:11]
	s_barrier
	s_cmp_gt_u32 s52, 13
	s_cbranch_scc0 .LBB0_1032
	s_and_b64 vcc, exec, s[40:41]
	s_cbranch_vccz .LBB0_1035
	s_barrier

; #define PG8_STAGE(bufoff, gbase, voff) do { _Pragma("unroll") for (int _i = 0; _i < 2; ++_i) \
;         __builtin_amdgcn_global_load_lds((const unsigned*)((const char*)(gbase) + (voff)[_i]), (PG8_LAS unsigned*)(lds + (bufoff) + ldsw + _i * 8192), 16, 0, 0); } while (0)
; #define PG8_LDA(dst, b, h) do { _Pragma("unroll") for (int m = 0; m < 4; ++m) _Pragma("unroll") for (int k = 0; k < 2; ++k) dst[m][k] = *(const PG8_LAS bf16x8*)(lds + PG8_SA(b, h) + aoff + m * 2048 + k * 1024); } while (0)
; #define PG8_LDB(dst, b, h) do { _Pragma("unroll") for (int n = 0; n < 2; ++n) _Pragma("unroll") for (int k = 0; k < 2; ++k) dst[n][k] = *(const PG8_LAS bf16x8*)(lds + PG8_SB(b, h) + boff + n * 2048 + k * 1024); } while (0)
; #define PG8_MMA(ai, bj, At, Bt) do { __builtin_amdgcn_s_setprio(1); _Pragma("unroll") for (int m = 0; m < 4; ++m) _Pragma("unroll") for (int n = 0; n < 2; ++n) _Pragma("unroll") for (int k = 0; k < 2; ++k) \
;         acc[ai][bj][m][n] = __builtin_amdgcn_mfma_f32_16x16x32_bf16(Bt[n][k], At[m][k], acc[ai][bj][m][n], 0, 0, 0); __builtin_amdgcn_s_setprio(0); } while (0)
; #define PG8_WAIT_V(n) asm volatile("s_waitcnt vmcnt(" #n ")" ::: "memory")
; #define PG8_WAIT_L(n) asm volatile("s_waitcnt lgkmcnt(" #n ")" ::: "memory")
; #define PG8_BAR __builtin_amdgcn_s_barrier()
; #define PG8_SCHED __builtin_amdgcn_sched_barrier(0)
; template <class Epi, class Sched, bool ALIGN_EPI = false, bool SP2 = false>
; __device__ __forceinline__ void gemm_phase(PG8_LAS unsigned char* lds, const Gemm g, const Sched& S, const Epi& E) {
;     ...
;             PG8_LDB(B0, 0, 0); PG8_LDB(B1, 0, 1); PG8_SCHED; PG8_LDA(At, 0, 0); PG8_STAGE(PG8_SA(1, 1), a1 + hstep, voffA);
;             PG8_WAIT_V(8); PG8_WAIT_L(0); PG8_BAR; PG8_MMA(0, 0, At, B0); PG8_MMA(0, 1, At, B1); PG8_BAR; PG8_SCHED;
;             PG8_LDA(At, 0, 1); PG8_STAGE(PG8_SB(0, 0), b2, voffB); PG8_STAGE(PG8_SB(0, 1), b2 + hstep, voffB); PG8_STAGE(PG8_SA(0, 0), a2, voffA);
;             PG8_WAIT_V(8); PG8_WAIT_L(0); PG8_BAR; PG8_MMA(1, 0, At, B0); PG8_MMA(1, 1, At, B1); PG8_BAR; PG8_SCHED;
.LBB0_1051:
	ds_read_b128 v[84:87], v154
	ds_read_b128 v[88:91], v154 offset:1024
	ds_read_b128 v[162:165], v154 offset:2048
	ds_read_b128 v[166:169], v154 offset:3072
	ds_read_b128 v[170:173], v154 offset:16384
	ds_read_b128 v[174:177], v154 offset:17408
	ds_read_b128 v[178:181], v154 offset:18432
	ds_read_b128 v[182:185], v154 offset:19456
	ds_read_b128 v[186:189], v160
	ds_read_b128 v[190:193], v160 offset:1024
	ds_read_b128 v[194:197], v160 offset:2048
	ds_read_b128 v[214:217], v160 offset:3072
	ds_read_b128 v[218:221], v160 offset:4096
	ds_read_b128 v[234:237], v160 offset:5120
	ds_read_b128 v[238:241], v160 offset:6144
	ds_read_b128 v[242:245], v160 offset:7168
	s_add_u32 s0, s52, 0xfffe0080
	s_addc_u32 s1, s53, -1
	s_add_i32 s63, 0, 0x10000
	s_cmp_eq_u32 s62, 4
	s_cselect_b32 s27, s45, s1
	s_cselect_b32 s26, s58, s0
	s_cselect_b32 s1, s43, s61
	s_cselect_b32 s0, s59, s60
	s_add_i32 s66, 0, 0x14000
	s_add_u32 s100, s52, 0xfffe0000
	s_addc_u32 s101, s53, -1
	s_mov_b32 m0, s54
	s_nop 0
	global_load_lds_dwordx4 v140, s[100:101]
	s_mov_b32 m0, s55
	s_nop 0
	global_load_lds_dwordx4 v142, s[100:101]
	s_add_i32 m0, s10, 0xc000
	s_nop 0
	global_load_lds_dwordx4 v150, s[52:53]
	s_add_i32 m0, s10, 0xe000
	s_nop 0
	global_load_lds_dwordx4 v152, s[52:53]
	s_nop 0
	s_waitcnt vmcnt(8)
	s_waitcnt lgkmcnt(0)
	s_barrier
	v_mfma_f32_16x16x32_bf16 v[136:139], v[84:87], v[186:189], v[136:139]
	v_mfma_f32_16x16x32_bf16 v[136:139], v[88:91], v[190:193], v[136:139]
	v_mfma_f32_16x16x32_bf16 v[132:135], v[162:165], v[186:189], v[132:135]
	v_mfma_f32_16x16x32_bf16 v[132:135], v[166:169], v[190:193], v[132:135]
	v_mfma_f32_16x16x32_bf16 v[120:123], v[162:165], v[194:197], v[120:123]
	v_mfma_f32_16x16x32_bf16 v[120:123], v[166:169], v[214:217], v[120:123]
	v_mfma_f32_16x16x32_bf16 v[128:131], v[84:87], v[194:197], v[128:131]
	v_mfma_f32_16x16x32_bf16 v[128:131], v[88:91], v[214:217], v[128:131]
	v_mfma_f32_16x16x32_bf16 v[104:107], v[84:87], v[218:221], v[104:107]
	v_mfma_f32_16x16x32_bf16 v[104:107], v[88:91], v[234:237], v[104:107]
	v_mfma_f32_16x16x32_bf16 v[100:103], v[162:165], v[218:221], v[100:103]
	v_mfma_f32_16x16x32_bf16 v[100:103], v[166:169], v[234:237], v[100:103]
	v_mfma_f32_16x16x32_bf16 v[76:79], v[162:165], v[238:241], v[76:79]
	v_mfma_f32_16x16x32_bf16 v[76:79], v[166:169], v[242:245], v[76:79]
	v_mfma_f32_16x16x32_bf16 v[80:83], v[84:87], v[238:241], v[80:83]
	v_mfma_f32_16x16x32_bf16 v[80:83], v[88:91], v[242:245], v[80:83]
	v_mfma_f32_16x16x32_bf16 v[124:127], v[170:173], v[186:189], v[124:127]
	v_mfma_f32_16x16x32_bf16 v[124:127], v[174:177], v[190:193], v[124:127]
	v_mfma_f32_16x16x32_bf16 v[116:119], v[178:181], v[186:189], v[116:119]
	v_mfma_f32_16x16x32_bf16 v[116:119], v[182:185], v[190:193], v[116:119]
	v_mfma_f32_16x16x32_bf16 v[108:111], v[178:181], v[194:197], v[108:111]
	v_mfma_f32_16x16x32_bf16 v[108:111], v[182:185], v[214:217], v[108:111]
	v_mfma_f32_16x16x32_bf16 v[112:115], v[170:173], v[194:197], v[112:115]
	v_mfma_f32_16x16x32_bf16 v[112:115], v[174:177], v[214:217], v[112:115]
	v_mfma_f32_16x16x32_bf16 v[96:99], v[170:173], v[218:221], v[96:99]
	v_mfma_f32_16x16x32_bf16 v[96:99], v[174:177], v[234:237], v[96:99]
	v_mfma_f32_16x16x32_bf16 v[92:95], v[178:181], v[218:221], v[92:95]
	v_mfma_f32_16x16x32_bf16 v[92:95], v[182:185], v[234:237], v[92:95]
	v_mfma_f32_16x16x32_bf16 v[68:71], v[178:181], v[238:241], v[68:71]
	v_mfma_f32_16x16x32_bf16 v[68:71], v[182:185], v[242:245], v[68:71]
	v_mfma_f32_16x16x32_bf16 v[72:75], v[170:173], v[238:241], v[72:75]
	v_mfma_f32_16x16x32_bf16 v[72:75], v[174:177], v[242:245], v[72:75]
	s_barrier
	ds_read_b128 v[186:189], v160 offset:16384
	ds_read_b128 v[190:193], v160 offset:17408
	ds_read_b128 v[194:197], v160 offset:18432
	ds_read_b128 v[214:217], v160 offset:19456
	ds_read_b128 v[218:221], v160 offset:20480
	ds_read_b128 v[234:237], v160 offset:21504
	ds_read_b128 v[238:241], v160 offset:22528
	ds_read_b128 v[242:245], v160 offset:23552
	s_add_i32 s63, s63, s9
	s_mov_b32 m0, s63
	s_nop 0
	global_load_lds_dwordx4 v2, s[0:1]
	s_add_i32 m0, s63, 0x2000
	s_add_u32 s64, s0, 0x20000
	s_addc_u32 s65, s1, 0
	s_add_i32 s63, s66, s9
	global_load_lds_dwordx4 v144, s[0:1]
	s_mov_b32 m0, s63
	s_nop 0
	global_load_lds_dwordx4 v2, s[64:65]
	s_add_i32 m0, s63, 0x2000
	s_nop 0
	global_load_lds_dwordx4 v144, s[64:65]
	s_waitcnt vmcnt(6)
	s_waitcnt lgkmcnt(0)
	s_barrier
	v_mfma_f32_16x16x32_bf16 v[64:67], v[84:87], v[186:189], v[64:67]
	v_mfma_f32_16x16x32_bf16 v[64:67], v[88:91], v[190:193], v[64:67]
	v_mfma_f32_16x16x32_bf16 v[60:63], v[162:165], v[186:189], v[60:63]
	v_mfma_f32_16x16x32_bf16 v[60:63], v[166:169], v[190:193], v[60:63]
	v_mfma_f32_16x16x32_bf16 v[44:47], v[162:165], v[194:197], v[44:47]
	v_mfma_f32_16x16x32_bf16 v[44:47], v[166:169], v[214:217], v[44:47]
	v_mfma_f32_16x16x32_bf16 v[48:51], v[84:87], v[194:197], v[48:51]
	v_mfma_f32_16x16x32_bf16 v[48:51], v[88:91], v[214:217], v[48:51]
	v_mfma_f32_16x16x32_bf16 v[32:35], v[84:87], v[218:221], v[32:35]
	v_mfma_f32_16x16x32_bf16 v[32:35], v[88:91], v[234:237], v[32:35]
	v_mfma_f32_16x16x32_bf16 v[28:31], v[162:165], v[218:221], v[28:31]
	v_mfma_f32_16x16x32_bf16 v[28:31], v[166:169], v[234:237], v[28:31]
	v_mfma_f32_16x16x32_bf16 v[12:15], v[162:165], v[238:241], v[12:15]
	v_mfma_f32_16x16x32_bf16 v[12:15], v[166:169], v[242:245], v[12:15]
	v_mfma_f32_16x16x32_bf16 v[16:19], v[84:87], v[238:241], v[16:19]
	v_mfma_f32_16x16x32_bf16 v[16:19], v[88:91], v[242:245], v[16:19]
	v_mfma_f32_16x16x32_bf16 v[56:59], v[170:173], v[186:189], v[56:59]
	v_mfma_f32_16x16x32_bf16 v[56:59], v[174:177], v[190:193], v[56:59]
	v_mfma_f32_16x16x32_bf16 v[52:55], v[178:181], v[186:189], v[52:55]
	v_mfma_f32_16x16x32_bf16 v[52:55], v[182:185], v[190:193], v[52:55]
	v_mfma_f32_16x16x32_bf16 v[36:39], v[178:181], v[194:197], v[36:39]
	v_mfma_f32_16x16x32_bf16 v[36:39], v[182:185], v[214:217], v[36:39]
	v_mfma_f32_16x16x32_bf16 v[40:43], v[170:173], v[194:197], v[40:43]
	v_mfma_f32_16x16x32_bf16 v[40:43], v[174:177], v[214:217], v[40:43]
	v_mfma_f32_16x16x32_bf16 v[24:27], v[170:173], v[218:221], v[24:27]
	v_mfma_f32_16x16x32_bf16 v[24:27], v[174:177], v[234:237], v[24:27]
	v_mfma_f32_16x16x32_bf16 v[20:23], v[178:181], v[218:221], v[20:23]
	v_mfma_f32_16x16x32_bf16 v[20:23], v[182:185], v[234:237], v[20:23]
	v_mfma_f32_16x16x32_bf16 v[4:7], v[178:181], v[238:241], v[4:7]
	v_mfma_f32_16x16x32_bf16 v[4:7], v[182:185], v[242:245], v[4:7]
	v_mfma_f32_16x16x32_bf16 v[8:11], v[170:173], v[238:241], v[8:11]
	v_mfma_f32_16x16x32_bf16 v[8:11], v[174:177], v[242:245], v[8:11]
	s_barrier
; #define PG8_STAGE(bufoff, gbase, voff) do { _Pragma("unroll") for (int _i = 0; _i < 2; ++_i) \
;         __builtin_amdgcn_global_load_lds((const unsigned*)((const char*)(gbase) + (voff)[_i]), (PG8_LAS unsigned*)(lds + (bufoff) + ldsw + _i * 8192), 16, 0, 0); } while (0)
; #define PG8_LDA(dst, b, h) do { _Pragma("unroll") for (int m = 0; m < 4; ++m) _Pragma("unroll") for (int k = 0; k < 2; ++k) dst[m][k] = *(const PG8_LAS bf16x8*)(lds + PG8_SA(b, h) + aoff + m * 2048 + k * 1024); } while (0)
; #define PG8_LDB(dst, b, h) do { _Pragma("unroll") for (int n = 0; n < 2; ++n) _Pragma("unroll") for (int k = 0; k < 2; ++k) dst[n][k] = *(const PG8_LAS bf16x8*)(lds + PG8_SB(b, h) + boff + n * 2048 + k * 1024); } while (0)
; #define PG8_MMA(ai, bj, At, Bt) do { __builtin_amdgcn_s_setprio(1); _Pragma("unroll") for (int m = 0; m < 4; ++m) _Pragma("unroll") for (int n = 0; n < 2; ++n) _Pragma("unroll") for (int k = 0; k < 2; ++k) \
;         acc[ai][bj][m][n] = __builtin_amdgcn_mfma_f32_16x16x32_bf16(Bt[n][k], At[m][k], acc[ai][bj][m][n], 0, 0, 0); __builtin_amdgcn_s_setprio(0); } while (0)
; #define PG8_WAIT_V(n) asm volatile("s_waitcnt vmcnt(" #n ")" ::: "memory")
; #define PG8_WAIT_L(n) asm volatile("s_waitcnt lgkmcnt(" #n ")" ::: "memory")
; #define PG8_BAR __builtin_amdgcn_s_barrier()
; #define PG8_SCHED __builtin_amdgcn_sched_barrier(0)
; template <class Epi, class Sched, bool ALIGN_EPI = false, bool SP2 = false>
; __device__ __forceinline__ void gemm_phase(PG8_LAS unsigned char* lds, const Gemm g, const Sched& S, const Epi& E) {
;     ...
;         for (int t = 0; t < nt; t += 2) {
;             const bool last = (t == nt - 2);
;     ...
;             PG8_LDB(B0, 1, 0); PG8_LDB(B1, 1, 1); PG8_SCHED; PG8_LDA(At, 1, 0); PG8_STAGE(PG8_SA(0, 1), a2 + hstep, voffA);
;             PG8_WAIT_V(8); PG8_WAIT_L(0); PG8_BAR; PG8_MMA(0, 0, At, B0); PG8_MMA(0, 1, At, B1); PG8_BAR; PG8_SCHED;
;             PG8_LDA(At, 1, 1); PG8_STAGE(PG8_SB(1, 0), b3, voffB); PG8_STAGE(PG8_SB(1, 1), b3 + hstep, voffB); PG8_STAGE(PG8_SA(1, 0), a3, voffA);
;             PG8_WAIT_V(8); PG8_WAIT_L(0); PG8_BAR; PG8_MMA(1, 0, At, B0); PG8_MMA(1, 1, At, B1); PG8_BAR; PG8_SCHED;
	ds_read_b128 v[84:87], v154 offset:32768
	ds_read_b128 v[88:91], v154 offset:33792
	ds_read_b128 v[162:165], v154 offset:34816
	ds_read_b128 v[166:169], v154 offset:35840
	ds_read_b128 v[170:173], v154 offset:49152
	ds_read_b128 v[174:177], v154 offset:50176
	ds_read_b128 v[178:181], v154 offset:51200
	ds_read_b128 v[182:185], v154 offset:52224
	ds_read_b128 v[186:189], v160 offset:32768
	ds_read_b128 v[190:193], v160 offset:33792
	ds_read_b128 v[194:197], v160 offset:34816
	ds_read_b128 v[214:217], v160 offset:35840
	ds_read_b128 v[218:221], v160 offset:36864
	ds_read_b128 v[234:237], v160 offset:37888
	ds_read_b128 v[238:241], v160 offset:38912
	ds_read_b128 v[242:245], v160 offset:39936
	s_add_i32 s63, 0, 0x18000
	s_add_i32 s64, 0, 0x1c000
	s_mov_b32 m0, s10
	s_nop 0
	global_load_lds_dwordx4 v140, s[26:27]
	s_mov_b32 m0, s11
	s_nop 0
	global_load_lds_dwordx4 v142, s[26:27]
	s_add_u32 s26, s26, 0x20000
	s_addc_u32 s27, s27, 0
	s_mov_b32 m0, s25
	s_nop 0
	global_load_lds_dwordx4 v140, s[26:27]
	s_mov_b32 m0, s51
	s_nop 0
	global_load_lds_dwordx4 v142, s[26:27]
	s_nop 0
	s_waitcnt vmcnt(8)
	s_waitcnt lgkmcnt(0)
	s_barrier
	v_mfma_f32_16x16x32_bf16 v[136:139], v[84:87], v[186:189], v[136:139]
	v_mfma_f32_16x16x32_bf16 v[136:139], v[88:91], v[190:193], v[136:139]
	v_mfma_f32_16x16x32_bf16 v[132:135], v[162:165], v[186:189], v[132:135]
	v_mfma_f32_16x16x32_bf16 v[132:135], v[166:169], v[190:193], v[132:135]
	v_mfma_f32_16x16x32_bf16 v[120:123], v[162:165], v[194:197], v[120:123]
	v_mfma_f32_16x16x32_bf16 v[120:123], v[166:169], v[214:217], v[120:123]
	v_mfma_f32_16x16x32_bf16 v[128:131], v[84:87], v[194:197], v[128:131]
	v_mfma_f32_16x16x32_bf16 v[128:131], v[88:91], v[214:217], v[128:131]
	v_mfma_f32_16x16x32_bf16 v[104:107], v[84:87], v[218:221], v[104:107]
	v_mfma_f32_16x16x32_bf16 v[104:107], v[88:91], v[234:237], v[104:107]
	v_mfma_f32_16x16x32_bf16 v[100:103], v[162:165], v[218:221], v[100:103]
	v_mfma_f32_16x16x32_bf16 v[100:103], v[166:169], v[234:237], v[100:103]
	v_mfma_f32_16x16x32_bf16 v[76:79], v[162:165], v[238:241], v[76:79]
	v_mfma_f32_16x16x32_bf16 v[76:79], v[166:169], v[242:245], v[76:79]
	v_mfma_f32_16x16x32_bf16 v[80:83], v[84:87], v[238:241], v[80:83]
	v_mfma_f32_16x16x32_bf16 v[80:83], v[88:91], v[242:245], v[80:83]
	v_mfma_f32_16x16x32_bf16 v[124:127], v[170:173], v[186:189], v[124:127]
	v_mfma_f32_16x16x32_bf16 v[124:127], v[174:177], v[190:193], v[124:127]
	v_mfma_f32_16x16x32_bf16 v[116:119], v[178:181], v[186:189], v[116:119]
	v_mfma_f32_16x16x32_bf16 v[116:119], v[182:185], v[190:193], v[116:119]
	v_mfma_f32_16x16x32_bf16 v[108:111], v[178:181], v[194:197], v[108:111]
	v_mfma_f32_16x16x32_bf16 v[108:111], v[182:185], v[214:217], v[108:111]
	v_mfma_f32_16x16x32_bf16 v[112:115], v[170:173], v[194:197], v[112:115]
	v_mfma_f32_16x16x32_bf16 v[112:115], v[174:177], v[214:217], v[112:115]
	v_mfma_f32_16x16x32_bf16 v[96:99], v[170:173], v[218:221], v[96:99]
	v_mfma_f32_16x16x32_bf16 v[96:99], v[174:177], v[234:237], v[96:99]
	v_mfma_f32_16x16x32_bf16 v[92:95], v[178:181], v[218:221], v[92:95]
	v_mfma_f32_16x16x32_bf16 v[92:95], v[182:185], v[234:237], v[92:95]
	v_mfma_f32_16x16x32_bf16 v[68:71], v[178:181], v[238:241], v[68:71]
	v_mfma_f32_16x16x32_bf16 v[68:71], v[182:185], v[242:245], v[68:71]
	v_mfma_f32_16x16x32_bf16 v[72:75], v[170:173], v[238:241], v[72:75]
	v_mfma_f32_16x16x32_bf16 v[72:75], v[174:177], v[242:245], v[72:75]
	s_barrier
	ds_read_b128 v[186:189], v160 offset:49152
	ds_read_b128 v[190:193], v160 offset:50176
	ds_read_b128 v[194:197], v160 offset:51200
	ds_read_b128 v[214:217], v160 offset:52224
	ds_read_b128 v[218:221], v160 offset:53248
	ds_read_b128 v[234:237], v160 offset:54272
	ds_read_b128 v[238:241], v160 offset:55296
	ds_read_b128 v[242:245], v160 offset:56320
	s_add_i32 s26, s63, s9
	s_mov_b32 m0, s26
	s_add_u32 s0, s0, 0x80
	s_addc_u32 s1, s1, 0
	global_load_lds_dwordx4 v2, s[0:1]
	s_add_i32 m0, s26, 0x2000
	s_add_i32 s26, s64, s9
	global_load_lds_dwordx4 v144, s[0:1]
	s_add_u32 s0, s0, 0x20000
	s_addc_u32 s1, s1, 0
	s_mov_b32 m0, s26
	s_nop 0
	global_load_lds_dwordx4 v2, s[0:1]
	s_add_i32 m0, s26, 0x2000
	s_nop 0
	global_load_lds_dwordx4 v144, s[0:1]
	s_waitcnt vmcnt(6)
	s_waitcnt lgkmcnt(0)
	s_barrier
	v_mfma_f32_16x16x32_bf16 v[64:67], v[84:87], v[186:189], v[64:67]
	v_mfma_f32_16x16x32_bf16 v[64:67], v[88:91], v[190:193], v[64:67]
	v_mfma_f32_16x16x32_bf16 v[60:63], v[162:165], v[186:189], v[60:63]
	v_mfma_f32_16x16x32_bf16 v[60:63], v[166:169], v[190:193], v[60:63]
	v_mfma_f32_16x16x32_bf16 v[44:47], v[162:165], v[194:197], v[44:47]
	v_mfma_f32_16x16x32_bf16 v[44:47], v[166:169], v[214:217], v[44:47]
	v_mfma_f32_16x16x32_bf16 v[48:51], v[84:87], v[194:197], v[48:51]
	v_mfma_f32_16x16x32_bf16 v[48:51], v[88:91], v[214:217], v[48:51]
	v_mfma_f32_16x16x32_bf16 v[32:35], v[84:87], v[218:221], v[32:35]
	v_mfma_f32_16x16x32_bf16 v[32:35], v[88:91], v[234:237], v[32:35]
	v_mfma_f32_16x16x32_bf16 v[28:31], v[162:165], v[218:221], v[28:31]
	v_mfma_f32_16x16x32_bf16 v[28:31], v[166:169], v[234:237], v[28:31]
	v_mfma_f32_16x16x32_bf16 v[12:15], v[162:165], v[238:241], v[12:15]
	v_mfma_f32_16x16x32_bf16 v[12:15], v[166:169], v[242:245], v[12:15]
	v_mfma_f32_16x16x32_bf16 v[16:19], v[84:87], v[238:241], v[16:19]
	v_mfma_f32_16x16x32_bf16 v[16:19], v[88:91], v[242:245], v[16:19]
	s_add_i32 s62, s62, 2
	s_add_u32 s52, s52, 0x100
	s_addc_u32 s53, s53, 0
	s_add_u32 s60, s60, 0x100
	s_addc_u32 s61, s61, 0
	s_nop 0
	v_mfma_f32_16x16x32_bf16 v[56:59], v[170:173], v[186:189], v[56:59]
	v_mfma_f32_16x16x32_bf16 v[56:59], v[174:177], v[190:193], v[56:59]
	v_mfma_f32_16x16x32_bf16 v[52:55], v[178:181], v[186:189], v[52:55]
	v_mfma_f32_16x16x32_bf16 v[52:55], v[182:185], v[190:193], v[52:55]
	v_mfma_f32_16x16x32_bf16 v[36:39], v[178:181], v[194:197], v[36:39]
	v_mfma_f32_16x16x32_bf16 v[36:39], v[182:185], v[214:217], v[36:39]
	v_mfma_f32_16x16x32_bf16 v[40:43], v[170:173], v[194:197], v[40:43]
	v_mfma_f32_16x16x32_bf16 v[40:43], v[174:177], v[214:217], v[40:43]
	v_mfma_f32_16x16x32_bf16 v[24:27], v[170:173], v[218:221], v[24:27]
	v_mfma_f32_16x16x32_bf16 v[24:27], v[174:177], v[234:237], v[24:27]
	v_mfma_f32_16x16x32_bf16 v[20:23], v[178:181], v[218:221], v[20:23]
	v_mfma_f32_16x16x32_bf16 v[20:23], v[182:185], v[234:237], v[20:23]
	v_mfma_f32_16x16x32_bf16 v[4:7], v[178:181], v[238:241], v[4:7]
	v_mfma_f32_16x16x32_bf16 v[4:7], v[182:185], v[242:245], v[4:7]
	v_mfma_f32_16x16x32_bf16 v[8:11], v[170:173], v[238:241], v[8:11]
	v_mfma_f32_16x16x32_bf16 v[8:11], v[174:177], v[242:245], v[8:11]
	s_barrier
	s_cmp_gt_u32 s62, 5
	s_cbranch_scc0 .LBB0_1051
	s_and_b64 vcc, exec, s[36:37]
	s_cbranch_vccz .LBB0_1054
	s_barrier

; #define PG8_STAGE(bufoff, gbase, voff) do { _Pragma("unroll") for (int _i = 0; _i < 2; ++_i) \
;         __builtin_amdgcn_global_load_lds((const unsigned*)((const char*)(gbase) + (voff)[_i]), (PG8_LAS unsigned*)(lds + (bufoff) + ldsw + _i * 8192), 16, 0, 0); } while (0)
; #define PG8_LDA(dst, b, h) do { _Pragma("unroll") for (int m = 0; m < 4; ++m) _Pragma("unroll") for (int k = 0; k < 2; ++k) dst[m][k] = *(const PG8_LAS bf16x8*)(lds + PG8_SA(b, h) + aoff + m * 2048 + k * 1024); } while (0)
; #define PG8_LDB(dst, b, h) do { _Pragma("unroll") for (int n = 0; n < 2; ++n) _Pragma("unroll") for (int k = 0; k < 2; ++k) dst[n][k] = *(const PG8_LAS bf16x8*)(lds + PG8_SB(b, h) + boff + n * 2048 + k * 1024); } while (0)
; #define PG8_MMA(ai, bj, At, Bt) do { __builtin_amdgcn_s_setprio(1); _Pragma("unroll") for (int m = 0; m < 4; ++m) _Pragma("unroll") for (int n = 0; n < 2; ++n) _Pragma("unroll") for (int k = 0; k < 2; ++k) \
;         acc[ai][bj][m][n] = __builtin_amdgcn_mfma_f32_16x16x32_bf16(Bt[n][k], At[m][k], acc[ai][bj][m][n], 0, 0, 0); __builtin_amdgcn_s_setprio(0); } while (0)
; #define PG8_WAIT_V(n) asm volatile("s_waitcnt vmcnt(" #n ")" ::: "memory")
; #define PG8_WAIT_L(n) asm volatile("s_waitcnt lgkmcnt(" #n ")" ::: "memory")
; #define PG8_BAR __builtin_amdgcn_s_barrier()
; #define PG8_SCHED __builtin_amdgcn_sched_barrier(0)
; template <class Epi, class Sched, bool ALIGN_EPI = false, bool SP2 = false>
; __device__ __forceinline__ void gemm_phase(PG8_LAS unsigned char* lds, const Gemm g, const Sched& S, const Epi& E) {
;     ...
;             PG8_LDB(B0, 0, 0); PG8_LDB(B1, 0, 1); PG8_SCHED; PG8_LDA(At, 0, 0); PG8_STAGE(PG8_SA(1, 1), a1 + hstep, voffA);
;             PG8_WAIT_V(8); PG8_WAIT_L(0); PG8_BAR; PG8_MMA(0, 0, At, B0); PG8_MMA(0, 1, At, B1); PG8_BAR; PG8_SCHED;
;             PG8_LDA(At, 0, 1); PG8_STAGE(PG8_SB(0, 0), b2, voffB); PG8_STAGE(PG8_SB(0, 1), b2 + hstep, voffB); PG8_STAGE(PG8_SA(0, 0), a2, voffA);
;             PG8_WAIT_V(8); PG8_WAIT_L(0); PG8_BAR; PG8_MMA(1, 0, At, B0); PG8_MMA(1, 1, At, B1); PG8_BAR; PG8_SCHED;
.LBB0_1624:
	ds_read_b128 v[142:145], v210
	ds_read_b128 v[150:153], v210 offset:1024
	ds_read_b128 v[154:157], v210 offset:2048
	ds_read_b128 v[158:161], v210 offset:3072
	ds_read_b128 v[162:165], v210 offset:16384
	ds_read_b128 v[166:169], v210 offset:17408
	ds_read_b128 v[170:173], v210 offset:18432
	ds_read_b128 v[174:177], v210 offset:19456
	ds_read_b128 v[178:181], v149
	ds_read_b128 v[182:185], v149 offset:1024
	ds_read_b128 v[186:189], v149 offset:2048
	ds_read_b128 v[190:193], v149 offset:3072
	ds_read_b128 v[194:197], v149 offset:4096
	ds_read_b128 v[198:201], v149 offset:5120
	ds_read_b128 v[202:205], v149 offset:6144
	ds_read_b128 v[206:209], v149 offset:7168
	s_add_u32 s0, s56, 0xfff00080
	s_addc_u32 s1, s57, -1
	s_add_i32 s63, 0, 0x10000
	s_cmp_eq_u32 s62, 60
	s_cselect_b32 s27, s51, s1
	s_cselect_b32 s26, s50, s0
	s_cselect_b32 s1, s53, s49
	s_cselect_b32 s0, s52, s47
	s_add_i32 s66, 0, 0x14000
	s_add_u32 s100, s56, 0xfff00000
	s_addc_u32 s101, s57, -1
	s_mov_b32 m0, s58
	s_nop 0
	global_load_lds_dwordx4 v132, s[100:101]
	s_mov_b32 m0, s59
	s_nop 0
	global_load_lds_dwordx4 v134, s[100:101]
	s_add_i32 m0, s10, 0xc000
	s_nop 0
	global_load_lds_dwordx4 v138, s[56:57]
	s_add_i32 m0, s10, 0xe000
	s_nop 0
	global_load_lds_dwordx4 v140, s[56:57]
	s_nop 0
	s_nop 0
	s_waitcnt vmcnt(8)
	s_waitcnt lgkmcnt(0)
	s_barrier
	v_mfma_f32_16x16x32_bf16 v[128:131], v[142:145], v[178:181], v[128:131]
	v_mfma_f32_16x16x32_bf16 v[128:131], v[150:153], v[182:185], v[128:131]
	v_mfma_f32_16x16x32_bf16 v[124:127], v[154:157], v[178:181], v[124:127]
	v_mfma_f32_16x16x32_bf16 v[124:127], v[158:161], v[182:185], v[124:127]
	v_mfma_f32_16x16x32_bf16 v[108:111], v[154:157], v[186:189], v[108:111]
	v_mfma_f32_16x16x32_bf16 v[108:111], v[158:161], v[190:193], v[108:111]
	v_mfma_f32_16x16x32_bf16 v[112:115], v[142:145], v[186:189], v[112:115]
	v_mfma_f32_16x16x32_bf16 v[112:115], v[150:153], v[190:193], v[112:115]
	v_mfma_f32_16x16x32_bf16 v[96:99], v[142:145], v[194:197], v[96:99]
	v_mfma_f32_16x16x32_bf16 v[96:99], v[150:153], v[198:201], v[96:99]
	v_mfma_f32_16x16x32_bf16 v[92:95], v[154:157], v[194:197], v[92:95]
	v_mfma_f32_16x16x32_bf16 v[92:95], v[158:161], v[198:201], v[92:95]
	v_mfma_f32_16x16x32_bf16 v[76:79], v[154:157], v[202:205], v[76:79]
	v_mfma_f32_16x16x32_bf16 v[76:79], v[158:161], v[206:209], v[76:79]
	v_mfma_f32_16x16x32_bf16 v[80:83], v[142:145], v[202:205], v[80:83]
	v_mfma_f32_16x16x32_bf16 v[80:83], v[150:153], v[206:209], v[80:83]
	v_mfma_f32_16x16x32_bf16 v[120:123], v[162:165], v[178:181], v[120:123]
	v_mfma_f32_16x16x32_bf16 v[120:123], v[166:169], v[182:185], v[120:123]
	v_mfma_f32_16x16x32_bf16 v[116:119], v[170:173], v[178:181], v[116:119]
	v_mfma_f32_16x16x32_bf16 v[116:119], v[174:177], v[182:185], v[116:119]
	v_mfma_f32_16x16x32_bf16 v[100:103], v[170:173], v[186:189], v[100:103]
	v_mfma_f32_16x16x32_bf16 v[100:103], v[174:177], v[190:193], v[100:103]
	v_mfma_f32_16x16x32_bf16 v[104:107], v[162:165], v[186:189], v[104:107]
	v_mfma_f32_16x16x32_bf16 v[104:107], v[166:169], v[190:193], v[104:107]
	v_mfma_f32_16x16x32_bf16 v[88:91], v[162:165], v[194:197], v[88:91]
	v_mfma_f32_16x16x32_bf16 v[88:91], v[166:169], v[198:201], v[88:91]
	v_mfma_f32_16x16x32_bf16 v[84:87], v[170:173], v[194:197], v[84:87]
	v_mfma_f32_16x16x32_bf16 v[84:87], v[174:177], v[198:201], v[84:87]
	v_mfma_f32_16x16x32_bf16 v[68:71], v[170:173], v[202:205], v[68:71]
	v_mfma_f32_16x16x32_bf16 v[68:71], v[174:177], v[206:209], v[68:71]
	v_mfma_f32_16x16x32_bf16 v[72:75], v[162:165], v[202:205], v[72:75]
	v_mfma_f32_16x16x32_bf16 v[72:75], v[166:169], v[206:209], v[72:75]
	s_barrier
	ds_read_b128 v[178:181], v149 offset:16384
	ds_read_b128 v[182:185], v149 offset:17408
	ds_read_b128 v[186:189], v149 offset:18432
	ds_read_b128 v[190:193], v149 offset:19456
	ds_read_b128 v[194:197], v149 offset:20480
	ds_read_b128 v[198:201], v149 offset:21504
	ds_read_b128 v[202:205], v149 offset:22528
	ds_read_b128 v[206:209], v149 offset:23552
	s_add_i32 s63, s63, s9
	s_mov_b32 m0, s63
	s_nop 0
	global_load_lds_dwordx4 v2, s[0:1]
	s_add_i32 m0, s63, 0x2000
	s_add_u32 s64, s0, 0x100000
	s_addc_u32 s65, s1, 0
	s_add_i32 s63, s66, s9
	global_load_lds_dwordx4 v136, s[0:1]
	s_mov_b32 m0, s63
	s_nop 0
	global_load_lds_dwordx4 v2, s[64:65]
	s_add_i32 m0, s63, 0x2000
	s_nop 0
	global_load_lds_dwordx4 v136, s[64:65]
	s_waitcnt vmcnt(6)
	s_waitcnt lgkmcnt(0)
	s_barrier
	v_mfma_f32_16x16x32_bf16 v[64:67], v[142:145], v[178:181], v[64:67]
	v_mfma_f32_16x16x32_bf16 v[64:67], v[150:153], v[182:185], v[64:67]
	v_mfma_f32_16x16x32_bf16 v[60:63], v[154:157], v[178:181], v[60:63]
	v_mfma_f32_16x16x32_bf16 v[60:63], v[158:161], v[182:185], v[60:63]
	v_mfma_f32_16x16x32_bf16 v[44:47], v[154:157], v[186:189], v[44:47]
	v_mfma_f32_16x16x32_bf16 v[44:47], v[158:161], v[190:193], v[44:47]
	v_mfma_f32_16x16x32_bf16 v[48:51], v[142:145], v[186:189], v[48:51]
	v_mfma_f32_16x16x32_bf16 v[48:51], v[150:153], v[190:193], v[48:51]
	v_mfma_f32_16x16x32_bf16 v[32:35], v[142:145], v[194:197], v[32:35]
	v_mfma_f32_16x16x32_bf16 v[32:35], v[150:153], v[198:201], v[32:35]
	v_mfma_f32_16x16x32_bf16 v[28:31], v[154:157], v[194:197], v[28:31]
	v_mfma_f32_16x16x32_bf16 v[28:31], v[158:161], v[198:201], v[28:31]
	v_mfma_f32_16x16x32_bf16 v[12:15], v[154:157], v[202:205], v[12:15]
	v_mfma_f32_16x16x32_bf16 v[12:15], v[158:161], v[206:209], v[12:15]
	v_mfma_f32_16x16x32_bf16 v[16:19], v[142:145], v[202:205], v[16:19]
	v_mfma_f32_16x16x32_bf16 v[16:19], v[150:153], v[206:209], v[16:19]
	v_mfma_f32_16x16x32_bf16 v[56:59], v[162:165], v[178:181], v[56:59]
	v_mfma_f32_16x16x32_bf16 v[56:59], v[166:169], v[182:185], v[56:59]
	v_mfma_f32_16x16x32_bf16 v[52:55], v[170:173], v[178:181], v[52:55]
	v_mfma_f32_16x16x32_bf16 v[52:55], v[174:177], v[182:185], v[52:55]
	v_mfma_f32_16x16x32_bf16 v[36:39], v[170:173], v[186:189], v[36:39]
	v_mfma_f32_16x16x32_bf16 v[36:39], v[174:177], v[190:193], v[36:39]
	v_mfma_f32_16x16x32_bf16 v[40:43], v[162:165], v[186:189], v[40:43]
	v_mfma_f32_16x16x32_bf16 v[40:43], v[166:169], v[190:193], v[40:43]
	v_mfma_f32_16x16x32_bf16 v[24:27], v[162:165], v[194:197], v[24:27]
	v_mfma_f32_16x16x32_bf16 v[24:27], v[166:169], v[198:201], v[24:27]
	v_mfma_f32_16x16x32_bf16 v[20:23], v[170:173], v[194:197], v[20:23]
	v_mfma_f32_16x16x32_bf16 v[20:23], v[174:177], v[198:201], v[20:23]
	v_mfma_f32_16x16x32_bf16 v[4:7], v[170:173], v[202:205], v[4:7]
	v_mfma_f32_16x16x32_bf16 v[4:7], v[174:177], v[206:209], v[4:7]
	v_mfma_f32_16x16x32_bf16 v[8:11], v[162:165], v[202:205], v[8:11]
	v_mfma_f32_16x16x32_bf16 v[8:11], v[166:169], v[206:209], v[8:11]
	s_barrier
; #define PG8_STAGE(bufoff, gbase, voff) do { _Pragma("unroll") for (int _i = 0; _i < 2; ++_i) \
;         __builtin_amdgcn_global_load_lds((const unsigned*)((const char*)(gbase) + (voff)[_i]), (PG8_LAS unsigned*)(lds + (bufoff) + ldsw + _i * 8192), 16, 0, 0); } while (0)
; #define PG8_LDA(dst, b, h) do { _Pragma("unroll") for (int m = 0; m < 4; ++m) _Pragma("unroll") for (int k = 0; k < 2; ++k) dst[m][k] = *(const PG8_LAS bf16x8*)(lds + PG8_SA(b, h) + aoff + m * 2048 + k * 1024); } while (0)
; #define PG8_LDB(dst, b, h) do { _Pragma("unroll") for (int n = 0; n < 2; ++n) _Pragma("unroll") for (int k = 0; k < 2; ++k) dst[n][k] = *(const PG8_LAS bf16x8*)(lds + PG8_SB(b, h) + boff + n * 2048 + k * 1024); } while (0)
; #define PG8_MMA(ai, bj, At, Bt) do { __builtin_amdgcn_s_setprio(1); _Pragma("unroll") for (int m = 0; m < 4; ++m) _Pragma("unroll") for (int n = 0; n < 2; ++n) _Pragma("unroll") for (int k = 0; k < 2; ++k) \
;         acc[ai][bj][m][n] = __builtin_amdgcn_mfma_f32_16x16x32_bf16(Bt[n][k], At[m][k], acc[ai][bj][m][n], 0, 0, 0); __builtin_amdgcn_s_setprio(0); } while (0)
; #define PG8_WAIT_V(n) asm volatile("s_waitcnt vmcnt(" #n ")" ::: "memory")
; #define PG8_WAIT_L(n) asm volatile("s_waitcnt lgkmcnt(" #n ")" ::: "memory")
; #define PG8_BAR __builtin_amdgcn_s_barrier()
; #define PG8_SCHED __builtin_amdgcn_sched_barrier(0)
; template <class Epi, class Sched, bool ALIGN_EPI = false, bool SP2 = false>
; __device__ __forceinline__ void gemm_phase(PG8_LAS unsigned char* lds, const Gemm g, const Sched& S, const Epi& E) {
;     ...
;         for (int t = 0; t < nt; t += 2) {
;             const bool last = (t == nt - 2);
;     ...
;             PG8_LDB(B0, 1, 0); PG8_LDB(B1, 1, 1); PG8_SCHED; PG8_LDA(At, 1, 0); PG8_STAGE(PG8_SA(0, 1), a2 + hstep, voffA);
;             PG8_WAIT_V(8); PG8_WAIT_L(0); PG8_BAR; PG8_MMA(0, 0, At, B0); PG8_MMA(0, 1, At, B1); PG8_BAR; PG8_SCHED;
;             PG8_LDA(At, 1, 1); PG8_STAGE(PG8_SB(1, 0), b3, voffB); PG8_STAGE(PG8_SB(1, 1), b3 + hstep, voffB); PG8_STAGE(PG8_SA(1, 0), a3, voffA);
;             PG8_WAIT_V(8); PG8_WAIT_L(0); PG8_BAR; PG8_MMA(1, 0, At, B0); PG8_MMA(1, 1, At, B1); PG8_BAR; PG8_SCHED;
	ds_read_b128 v[142:145], v210 offset:32768
	ds_read_b128 v[150:153], v210 offset:33792
	ds_read_b128 v[154:157], v210 offset:34816
	ds_read_b128 v[158:161], v210 offset:35840
	ds_read_b128 v[162:165], v210 offset:49152
	ds_read_b128 v[166:169], v210 offset:50176
	ds_read_b128 v[170:173], v210 offset:51200
	ds_read_b128 v[174:177], v210 offset:52224
	ds_read_b128 v[178:181], v149 offset:32768
	ds_read_b128 v[182:185], v149 offset:33792
	ds_read_b128 v[186:189], v149 offset:34816
	ds_read_b128 v[190:193], v149 offset:35840
	ds_read_b128 v[194:197], v149 offset:36864
	ds_read_b128 v[198:201], v149 offset:37888
	ds_read_b128 v[202:205], v149 offset:38912
	ds_read_b128 v[206:209], v149 offset:39936
	s_add_i32 s63, 0, 0x18000
	s_add_i32 s64, 0, 0x1c000
	s_mov_b32 m0, s10
	s_nop 0
	global_load_lds_dwordx4 v132, s[26:27]
	s_mov_b32 m0, s11
	s_nop 0
	global_load_lds_dwordx4 v134, s[26:27]
	s_add_u32 s26, s26, 0x100000
	s_addc_u32 s27, s27, 0
	s_mov_b32 m0, s25
	s_nop 0
	global_load_lds_dwordx4 v132, s[26:27]
	s_mov_b32 m0, s55
	s_nop 0
	global_load_lds_dwordx4 v134, s[26:27]
	s_nop 0
	s_waitcnt vmcnt(8)
	s_waitcnt lgkmcnt(0)
	s_barrier
	v_mfma_f32_16x16x32_bf16 v[128:131], v[142:145], v[178:181], v[128:131]
	v_mfma_f32_16x16x32_bf16 v[128:131], v[150:153], v[182:185], v[128:131]
	v_mfma_f32_16x16x32_bf16 v[124:127], v[154:157], v[178:181], v[124:127]
	v_mfma_f32_16x16x32_bf16 v[124:127], v[158:161], v[182:185], v[124:127]
	v_mfma_f32_16x16x32_bf16 v[108:111], v[154:157], v[186:189], v[108:111]
	v_mfma_f32_16x16x32_bf16 v[108:111], v[158:161], v[190:193], v[108:111]
	v_mfma_f32_16x16x32_bf16 v[112:115], v[142:145], v[186:189], v[112:115]
	v_mfma_f32_16x16x32_bf16 v[112:115], v[150:153], v[190:193], v[112:115]
	v_mfma_f32_16x16x32_bf16 v[96:99], v[142:145], v[194:197], v[96:99]
	v_mfma_f32_16x16x32_bf16 v[96:99], v[150:153], v[198:201], v[96:99]
	v_mfma_f32_16x16x32_bf16 v[92:95], v[154:157], v[194:197], v[92:95]
	v_mfma_f32_16x16x32_bf16 v[92:95], v[158:161], v[198:201], v[92:95]
	v_mfma_f32_16x16x32_bf16 v[76:79], v[154:157], v[202:205], v[76:79]
	v_mfma_f32_16x16x32_bf16 v[76:79], v[158:161], v[206:209], v[76:79]
	v_mfma_f32_16x16x32_bf16 v[80:83], v[142:145], v[202:205], v[80:83]
	v_mfma_f32_16x16x32_bf16 v[80:83], v[150:153], v[206:209], v[80:83]
	v_mfma_f32_16x16x32_bf16 v[120:123], v[162:165], v[178:181], v[120:123]
	v_mfma_f32_16x16x32_bf16 v[120:123], v[166:169], v[182:185], v[120:123]
	v_mfma_f32_16x16x32_bf16 v[116:119], v[170:173], v[178:181], v[116:119]
	v_mfma_f32_16x16x32_bf16 v[116:119], v[174:177], v[182:185], v[116:119]
	v_mfma_f32_16x16x32_bf16 v[100:103], v[170:173], v[186:189], v[100:103]
	v_mfma_f32_16x16x32_bf16 v[100:103], v[174:177], v[190:193], v[100:103]
	v_mfma_f32_16x16x32_bf16 v[104:107], v[162:165], v[186:189], v[104:107]
	v_mfma_f32_16x16x32_bf16 v[104:107], v[166:169], v[190:193], v[104:107]
	v_mfma_f32_16x16x32_bf16 v[88:91], v[162:165], v[194:197], v[88:91]
	v_mfma_f32_16x16x32_bf16 v[88:91], v[166:169], v[198:201], v[88:91]
	v_mfma_f32_16x16x32_bf16 v[84:87], v[170:173], v[194:197], v[84:87]
	v_mfma_f32_16x16x32_bf16 v[84:87], v[174:177], v[198:201], v[84:87]
	v_mfma_f32_16x16x32_bf16 v[68:71], v[170:173], v[202:205], v[68:71]
	v_mfma_f32_16x16x32_bf16 v[68:71], v[174:177], v[206:209], v[68:71]
	v_mfma_f32_16x16x32_bf16 v[72:75], v[162:165], v[202:205], v[72:75]
	v_mfma_f32_16x16x32_bf16 v[72:75], v[166:169], v[206:209], v[72:75]
	s_barrier
	ds_read_b128 v[178:181], v149 offset:49152
	ds_read_b128 v[182:185], v149 offset:50176
	ds_read_b128 v[186:189], v149 offset:51200
	ds_read_b128 v[190:193], v149 offset:52224
	ds_read_b128 v[194:197], v149 offset:53248
	ds_read_b128 v[198:201], v149 offset:54272
	ds_read_b128 v[202:205], v149 offset:55296
	ds_read_b128 v[206:209], v149 offset:56320
	s_add_i32 s26, s63, s9
	s_mov_b32 m0, s26
	s_add_u32 s0, s0, 0x80
	s_addc_u32 s1, s1, 0
	global_load_lds_dwordx4 v2, s[0:1]
	s_add_i32 m0, s26, 0x2000
	s_add_i32 s26, s64, s9
	global_load_lds_dwordx4 v136, s[0:1]
	s_add_u32 s0, s0, 0x100000
	s_addc_u32 s1, s1, 0
	s_mov_b32 m0, s26
	s_nop 0
	global_load_lds_dwordx4 v2, s[0:1]
	s_add_i32 m0, s26, 0x2000
	s_nop 0
	global_load_lds_dwordx4 v136, s[0:1]
	s_waitcnt vmcnt(6)
	s_waitcnt lgkmcnt(0)
	s_barrier
	v_mfma_f32_16x16x32_bf16 v[64:67], v[142:145], v[178:181], v[64:67]
	v_mfma_f32_16x16x32_bf16 v[64:67], v[150:153], v[182:185], v[64:67]
	v_mfma_f32_16x16x32_bf16 v[60:63], v[154:157], v[178:181], v[60:63]
	v_mfma_f32_16x16x32_bf16 v[60:63], v[158:161], v[182:185], v[60:63]
	v_mfma_f32_16x16x32_bf16 v[44:47], v[154:157], v[186:189], v[44:47]
	v_mfma_f32_16x16x32_bf16 v[44:47], v[158:161], v[190:193], v[44:47]
	v_mfma_f32_16x16x32_bf16 v[48:51], v[142:145], v[186:189], v[48:51]
	v_mfma_f32_16x16x32_bf16 v[48:51], v[150:153], v[190:193], v[48:51]
	v_mfma_f32_16x16x32_bf16 v[32:35], v[142:145], v[194:197], v[32:35]
	v_mfma_f32_16x16x32_bf16 v[32:35], v[150:153], v[198:201], v[32:35]
	v_mfma_f32_16x16x32_bf16 v[28:31], v[154:157], v[194:197], v[28:31]
	v_mfma_f32_16x16x32_bf16 v[28:31], v[158:161], v[198:201], v[28:31]
	v_mfma_f32_16x16x32_bf16 v[12:15], v[154:157], v[202:205], v[12:15]
	v_mfma_f32_16x16x32_bf16 v[12:15], v[158:161], v[206:209], v[12:15]
	v_mfma_f32_16x16x32_bf16 v[16:19], v[142:145], v[202:205], v[16:19]
	v_mfma_f32_16x16x32_bf16 v[16:19], v[150:153], v[206:209], v[16:19]
	s_add_i32 s62, s62, 2
	s_add_u32 s56, s56, 0x100
	s_addc_u32 s57, s57, 0
	s_add_u32 s47, s47, 0x100
	s_addc_u32 s49, s49, 0
	s_nop 0
	v_mfma_f32_16x16x32_bf16 v[56:59], v[162:165], v[178:181], v[56:59]
	v_mfma_f32_16x16x32_bf16 v[56:59], v[166:169], v[182:185], v[56:59]
	v_mfma_f32_16x16x32_bf16 v[52:55], v[170:173], v[178:181], v[52:55]
	v_mfma_f32_16x16x32_bf16 v[52:55], v[174:177], v[182:185], v[52:55]
	v_mfma_f32_16x16x32_bf16 v[36:39], v[170:173], v[186:189], v[36:39]
	v_mfma_f32_16x16x32_bf16 v[36:39], v[174:177], v[190:193], v[36:39]
	v_mfma_f32_16x16x32_bf16 v[40:43], v[162:165], v[186:189], v[40:43]
	v_mfma_f32_16x16x32_bf16 v[40:43], v[166:169], v[190:193], v[40:43]
	v_mfma_f32_16x16x32_bf16 v[24:27], v[162:165], v[194:197], v[24:27]
	v_mfma_f32_16x16x32_bf16 v[24:27], v[166:169], v[198:201], v[24:27]
	v_mfma_f32_16x16x32_bf16 v[20:23], v[170:173], v[194:197], v[20:23]
	v_mfma_f32_16x16x32_bf16 v[20:23], v[174:177], v[198:201], v[20:23]
	v_mfma_f32_16x16x32_bf16 v[4:7], v[170:173], v[202:205], v[4:7]
	v_mfma_f32_16x16x32_bf16 v[4:7], v[174:177], v[206:209], v[4:7]
	v_mfma_f32_16x16x32_bf16 v[8:11], v[162:165], v[202:205], v[8:11]
	v_mfma_f32_16x16x32_bf16 v[8:11], v[166:169], v[206:209], v[8:11]
	s_barrier
	s_cmp_gt_u32 s62, 61
	s_cbranch_scc0 .LBB0_1624
	s_and_b64 vcc, exec, s[44:45]
	s_cbranch_vccz .LBB0_1627
	s_barrier

; #define PG8_STAGE(bufoff, gbase, voff) do { _Pragma("unroll") for (int _i = 0; _i < 2; ++_i) \
;         __builtin_amdgcn_global_load_lds((const unsigned*)((const char*)(gbase) + (voff)[_i]), (PG8_LAS unsigned*)(lds + (bufoff) + ldsw + _i * 8192), 16, 0, 0); } while (0)
; #define PG8_LDA(dst, b, h) do { _Pragma("unroll") for (int m = 0; m < 4; ++m) _Pragma("unroll") for (int k = 0; k < 2; ++k) dst[m][k] = *(const PG8_LAS bf16x8*)(lds + PG8_SA(b, h) + aoff + m * 2048 + k * 1024); } while (0)
; #define PG8_LDB(dst, b, h) do { _Pragma("unroll") for (int n = 0; n < 2; ++n) _Pragma("unroll") for (int k = 0; k < 2; ++k) dst[n][k] = *(const PG8_LAS bf16x8*)(lds + PG8_SB(b, h) + boff + n * 2048 + k * 1024); } while (0)
; #define PG8_MMA(ai, bj, At, Bt) do { __builtin_amdgcn_s_setprio(1); _Pragma("unroll") for (int m = 0; m < 4; ++m) _Pragma("unroll") for (int n = 0; n < 2; ++n) _Pragma("unroll") for (int k = 0; k < 2; ++k) \
;         acc[ai][bj][m][n] = __builtin_amdgcn_mfma_f32_16x16x32_bf16(Bt[n][k], At[m][k], acc[ai][bj][m][n], 0, 0, 0); __builtin_amdgcn_s_setprio(0); } while (0)
; #define PG8_WAIT_V(n) asm volatile("s_waitcnt vmcnt(" #n ")" ::: "memory")
; #define PG8_WAIT_L(n) asm volatile("s_waitcnt lgkmcnt(" #n ")" ::: "memory")
; #define PG8_BAR __builtin_amdgcn_s_barrier()
; #define PG8_SCHED __builtin_amdgcn_sched_barrier(0)
; template <class Epi, class Sched, bool ALIGN_EPI = false, bool SP2 = false>
; __device__ __forceinline__ void gemm_phase(PG8_LAS unsigned char* lds, const Gemm g, const Sched& S, const Epi& E) {
;     ...
;             PG8_LDB(B0, 0, 0); PG8_LDB(B1, 0, 1); PG8_SCHED; PG8_LDA(At, 0, 0); PG8_STAGE(PG8_SA(1, 1), a1 + hstep, voffA);
;             PG8_WAIT_V(8); PG8_WAIT_L(0); PG8_BAR; PG8_MMA(0, 0, At, B0); PG8_MMA(0, 1, At, B1); PG8_BAR; PG8_SCHED;
;             PG8_LDA(At, 0, 1); PG8_STAGE(PG8_SB(0, 0), b2, voffB); PG8_STAGE(PG8_SB(0, 1), b2 + hstep, voffB); PG8_STAGE(PG8_SA(0, 0), a2, voffA);
;             PG8_WAIT_V(8); PG8_WAIT_L(0); PG8_BAR; PG8_MMA(1, 0, At, B0); PG8_MMA(1, 1, At, B1); PG8_BAR; PG8_SCHED;
.LBB0_2089:
	ds_read_b128 v[142:145], v210
	ds_read_b128 v[146:149], v210 offset:1024
	ds_read_b128 v[154:157], v210 offset:2048
	ds_read_b128 v[158:161], v210 offset:3072
	ds_read_b128 v[162:165], v210 offset:16384
	ds_read_b128 v[166:169], v210 offset:17408
	ds_read_b128 v[170:173], v210 offset:18432
	ds_read_b128 v[174:177], v210 offset:19456
	ds_read_b128 v[178:181], v153
	ds_read_b128 v[182:185], v153 offset:1024
	ds_read_b128 v[186:189], v153 offset:2048
	ds_read_b128 v[190:193], v153 offset:3072
	ds_read_b128 v[194:197], v153 offset:4096
	ds_read_b128 v[198:201], v153 offset:5120
	ds_read_b128 v[202:205], v153 offset:6144
	ds_read_b128 v[206:209], v153 offset:7168
	s_add_u32 s0, s50, 0xfff00080
	s_addc_u32 s1, s51, -1
	s_add_i32 s61, 0, 0x10000
	s_cmp_eq_u32 s60, 60
	s_cselect_b32 s27, s47, s1
	s_cselect_b32 s26, s46, s0
	s_cselect_b32 s1, s49, s45
	s_cselect_b32 s0, s48, s43
	s_add_i32 s64, 0, 0x14000
	s_add_u32 s100, s50, 0xfff00000
	s_addc_u32 s101, s51, -1
	s_mov_b32 m0, s54
	s_nop 0
	global_load_lds_dwordx4 v136, s[100:101]
	s_mov_b32 m0, s55
	s_nop 0
	global_load_lds_dwordx4 v134, s[100:101]
	s_add_i32 m0, s10, 0xc000
	s_nop 0
	global_load_lds_dwordx4 v138, s[50:51]
	s_add_i32 m0, s10, 0xe000
	s_nop 0
	global_load_lds_dwordx4 v140, s[50:51]
	s_nop 0
	s_waitcnt vmcnt(8)
	s_waitcnt lgkmcnt(0)
	s_barrier
	v_mfma_f32_16x16x32_bf16 v[128:131], v[142:145], v[178:181], v[128:131]
	v_mfma_f32_16x16x32_bf16 v[128:131], v[146:149], v[182:185], v[128:131]
	v_mfma_f32_16x16x32_bf16 v[124:127], v[154:157], v[178:181], v[124:127]
	v_mfma_f32_16x16x32_bf16 v[124:127], v[158:161], v[182:185], v[124:127]
	v_mfma_f32_16x16x32_bf16 v[108:111], v[154:157], v[186:189], v[108:111]
	v_mfma_f32_16x16x32_bf16 v[108:111], v[158:161], v[190:193], v[108:111]
	v_mfma_f32_16x16x32_bf16 v[112:115], v[142:145], v[186:189], v[112:115]
	v_mfma_f32_16x16x32_bf16 v[112:115], v[146:149], v[190:193], v[112:115]
	v_mfma_f32_16x16x32_bf16 v[96:99], v[142:145], v[194:197], v[96:99]
	v_mfma_f32_16x16x32_bf16 v[96:99], v[146:149], v[198:201], v[96:99]
	v_mfma_f32_16x16x32_bf16 v[92:95], v[154:157], v[194:197], v[92:95]
	v_mfma_f32_16x16x32_bf16 v[92:95], v[158:161], v[198:201], v[92:95]
	v_mfma_f32_16x16x32_bf16 v[76:79], v[154:157], v[202:205], v[76:79]
	v_mfma_f32_16x16x32_bf16 v[76:79], v[158:161], v[206:209], v[76:79]
	v_mfma_f32_16x16x32_bf16 v[80:83], v[142:145], v[202:205], v[80:83]
	v_mfma_f32_16x16x32_bf16 v[80:83], v[146:149], v[206:209], v[80:83]
	v_mfma_f32_16x16x32_bf16 v[120:123], v[162:165], v[178:181], v[120:123]
	v_mfma_f32_16x16x32_bf16 v[120:123], v[166:169], v[182:185], v[120:123]
	v_mfma_f32_16x16x32_bf16 v[116:119], v[170:173], v[178:181], v[116:119]
	v_mfma_f32_16x16x32_bf16 v[116:119], v[174:177], v[182:185], v[116:119]
	v_mfma_f32_16x16x32_bf16 v[100:103], v[170:173], v[186:189], v[100:103]
	v_mfma_f32_16x16x32_bf16 v[100:103], v[174:177], v[190:193], v[100:103]
	v_mfma_f32_16x16x32_bf16 v[104:107], v[162:165], v[186:189], v[104:107]
	v_mfma_f32_16x16x32_bf16 v[104:107], v[166:169], v[190:193], v[104:107]
	v_mfma_f32_16x16x32_bf16 v[88:91], v[162:165], v[194:197], v[88:91]
	v_mfma_f32_16x16x32_bf16 v[88:91], v[166:169], v[198:201], v[88:91]
	v_mfma_f32_16x16x32_bf16 v[84:87], v[170:173], v[194:197], v[84:87]
	v_mfma_f32_16x16x32_bf16 v[84:87], v[174:177], v[198:201], v[84:87]
	v_mfma_f32_16x16x32_bf16 v[68:71], v[170:173], v[202:205], v[68:71]
	v_mfma_f32_16x16x32_bf16 v[68:71], v[174:177], v[206:209], v[68:71]
	v_mfma_f32_16x16x32_bf16 v[72:75], v[162:165], v[202:205], v[72:75]
	v_mfma_f32_16x16x32_bf16 v[72:75], v[166:169], v[206:209], v[72:75]
	s_barrier
	ds_read_b128 v[178:181], v153 offset:16384
	ds_read_b128 v[182:185], v153 offset:17408
	ds_read_b128 v[186:189], v153 offset:18432
	ds_read_b128 v[190:193], v153 offset:19456
	ds_read_b128 v[194:197], v153 offset:20480
	ds_read_b128 v[198:201], v153 offset:21504
	ds_read_b128 v[202:205], v153 offset:22528
	ds_read_b128 v[206:209], v153 offset:23552
	s_add_i32 s61, s61, s9
	s_mov_b32 m0, s61
	s_nop 0
	global_load_lds_dwordx4 v2, s[0:1]
	s_add_i32 m0, s61, 0x2000
	s_add_u32 s62, s0, 0x100000
	s_addc_u32 s63, s1, 0
	s_add_i32 s61, s64, s9
	global_load_lds_dwordx4 v132, s[0:1]
	s_mov_b32 m0, s61
	s_nop 0
	global_load_lds_dwordx4 v2, s[62:63]
	s_add_i32 m0, s61, 0x2000
	s_nop 0
	global_load_lds_dwordx4 v132, s[62:63]
	s_waitcnt vmcnt(6)
	s_waitcnt lgkmcnt(0)
	s_barrier
	v_mfma_f32_16x16x32_bf16 v[64:67], v[142:145], v[178:181], v[64:67]
	v_mfma_f32_16x16x32_bf16 v[64:67], v[146:149], v[182:185], v[64:67]
	v_mfma_f32_16x16x32_bf16 v[60:63], v[154:157], v[178:181], v[60:63]
	v_mfma_f32_16x16x32_bf16 v[60:63], v[158:161], v[182:185], v[60:63]
	v_mfma_f32_16x16x32_bf16 v[44:47], v[154:157], v[186:189], v[44:47]
	v_mfma_f32_16x16x32_bf16 v[44:47], v[158:161], v[190:193], v[44:47]
	v_mfma_f32_16x16x32_bf16 v[48:51], v[142:145], v[186:189], v[48:51]
	v_mfma_f32_16x16x32_bf16 v[48:51], v[146:149], v[190:193], v[48:51]
	v_mfma_f32_16x16x32_bf16 v[32:35], v[142:145], v[194:197], v[32:35]
	v_mfma_f32_16x16x32_bf16 v[32:35], v[146:149], v[198:201], v[32:35]
	v_mfma_f32_16x16x32_bf16 v[28:31], v[154:157], v[194:197], v[28:31]
	v_mfma_f32_16x16x32_bf16 v[28:31], v[158:161], v[198:201], v[28:31]
	v_mfma_f32_16x16x32_bf16 v[12:15], v[154:157], v[202:205], v[12:15]
	v_mfma_f32_16x16x32_bf16 v[12:15], v[158:161], v[206:209], v[12:15]
	v_mfma_f32_16x16x32_bf16 v[16:19], v[142:145], v[202:205], v[16:19]
	v_mfma_f32_16x16x32_bf16 v[16:19], v[146:149], v[206:209], v[16:19]
	v_mfma_f32_16x16x32_bf16 v[56:59], v[162:165], v[178:181], v[56:59]
	v_mfma_f32_16x16x32_bf16 v[56:59], v[166:169], v[182:185], v[56:59]
	v_mfma_f32_16x16x32_bf16 v[52:55], v[170:173], v[178:181], v[52:55]
	v_mfma_f32_16x16x32_bf16 v[52:55], v[174:177], v[182:185], v[52:55]
	v_mfma_f32_16x16x32_bf16 v[36:39], v[170:173], v[186:189], v[36:39]
	v_mfma_f32_16x16x32_bf16 v[36:39], v[174:177], v[190:193], v[36:39]
	v_mfma_f32_16x16x32_bf16 v[40:43], v[162:165], v[186:189], v[40:43]
	v_mfma_f32_16x16x32_bf16 v[40:43], v[166:169], v[190:193], v[40:43]
	v_mfma_f32_16x16x32_bf16 v[24:27], v[162:165], v[194:197], v[24:27]
	v_mfma_f32_16x16x32_bf16 v[24:27], v[166:169], v[198:201], v[24:27]
	v_mfma_f32_16x16x32_bf16 v[20:23], v[170:173], v[194:197], v[20:23]
	v_mfma_f32_16x16x32_bf16 v[20:23], v[174:177], v[198:201], v[20:23]
	v_mfma_f32_16x16x32_bf16 v[4:7], v[170:173], v[202:205], v[4:7]
	v_mfma_f32_16x16x32_bf16 v[4:7], v[174:177], v[206:209], v[4:7]
	v_mfma_f32_16x16x32_bf16 v[8:11], v[162:165], v[202:205], v[8:11]
	v_mfma_f32_16x16x32_bf16 v[8:11], v[166:169], v[206:209], v[8:11]
	s_barrier
; #define PG8_STAGE(bufoff, gbase, voff) do { _Pragma("unroll") for (int _i = 0; _i < 2; ++_i) \
;         __builtin_amdgcn_global_load_lds((const unsigned*)((const char*)(gbase) + (voff)[_i]), (PG8_LAS unsigned*)(lds + (bufoff) + ldsw + _i * 8192), 16, 0, 0); } while (0)
; #define PG8_LDA(dst, b, h) do { _Pragma("unroll") for (int m = 0; m < 4; ++m) _Pragma("unroll") for (int k = 0; k < 2; ++k) dst[m][k] = *(const PG8_LAS bf16x8*)(lds + PG8_SA(b, h) + aoff + m * 2048 + k * 1024); } while (0)
; #define PG8_LDB(dst, b, h) do { _Pragma("unroll") for (int n = 0; n < 2; ++n) _Pragma("unroll") for (int k = 0; k < 2; ++k) dst[n][k] = *(const PG8_LAS bf16x8*)(lds + PG8_SB(b, h) + boff + n * 2048 + k * 1024); } while (0)
; #define PG8_MMA(ai, bj, At, Bt) do { __builtin_amdgcn_s_setprio(1); _Pragma("unroll") for (int m = 0; m < 4; ++m) _Pragma("unroll") for (int n = 0; n < 2; ++n) _Pragma("unroll") for (int k = 0; k < 2; ++k) \
;         acc[ai][bj][m][n] = __builtin_amdgcn_mfma_f32_16x16x32_bf16(Bt[n][k], At[m][k], acc[ai][bj][m][n], 0, 0, 0); __builtin_amdgcn_s_setprio(0); } while (0)
; #define PG8_WAIT_V(n) asm volatile("s_waitcnt vmcnt(" #n ")" ::: "memory")
; #define PG8_WAIT_L(n) asm volatile("s_waitcnt lgkmcnt(" #n ")" ::: "memory")
; #define PG8_BAR __builtin_amdgcn_s_barrier()
; #define PG8_SCHED __builtin_amdgcn_sched_barrier(0)
; template <class Epi, class Sched, bool ALIGN_EPI = false, bool SP2 = false>
; __device__ __forceinline__ void gemm_phase(PG8_LAS unsigned char* lds, const Gemm g, const Sched& S, const Epi& E) {
;     ...
;         for (int t = 0; t < nt; t += 2) {
;             const bool last = (t == nt - 2);
;     ...
;             PG8_LDB(B0, 1, 0); PG8_LDB(B1, 1, 1); PG8_SCHED; PG8_LDA(At, 1, 0); PG8_STAGE(PG8_SA(0, 1), a2 + hstep, voffA);
;             PG8_WAIT_V(8); PG8_WAIT_L(0); PG8_BAR; PG8_MMA(0, 0, At, B0); PG8_MMA(0, 1, At, B1); PG8_BAR; PG8_SCHED;
;             PG8_LDA(At, 1, 1); PG8_STAGE(PG8_SB(1, 0), b3, voffB); PG8_STAGE(PG8_SB(1, 1), b3 + hstep, voffB); PG8_STAGE(PG8_SA(1, 0), a3, voffA);
;             PG8_WAIT_V(8); PG8_WAIT_L(0); PG8_BAR; PG8_MMA(1, 0, At, B0); PG8_MMA(1, 1, At, B1); PG8_BAR; PG8_SCHED;
	ds_read_b128 v[142:145], v210 offset:32768
	ds_read_b128 v[146:149], v210 offset:33792
	ds_read_b128 v[154:157], v210 offset:34816
	ds_read_b128 v[158:161], v210 offset:35840
	ds_read_b128 v[162:165], v210 offset:49152
	ds_read_b128 v[166:169], v210 offset:50176
	ds_read_b128 v[170:173], v210 offset:51200
	ds_read_b128 v[174:177], v210 offset:52224
	ds_read_b128 v[178:181], v153 offset:32768
	ds_read_b128 v[182:185], v153 offset:33792
	ds_read_b128 v[186:189], v153 offset:34816
	ds_read_b128 v[190:193], v153 offset:35840
	ds_read_b128 v[194:197], v153 offset:36864
	ds_read_b128 v[198:201], v153 offset:37888
	ds_read_b128 v[202:205], v153 offset:38912
	ds_read_b128 v[206:209], v153 offset:39936
	s_add_i32 s61, 0, 0x18000
	s_add_i32 s62, 0, 0x1c000
	s_mov_b32 m0, s10
	s_nop 0
	global_load_lds_dwordx4 v136, s[26:27]
	s_mov_b32 m0, s11
	s_nop 0
	global_load_lds_dwordx4 v134, s[26:27]
	s_add_u32 s26, s26, 0x100000
	s_addc_u32 s27, s27, 0
	s_mov_b32 m0, s52
	s_nop 0
	global_load_lds_dwordx4 v136, s[26:27]
	s_mov_b32 m0, s53
	s_nop 0
	global_load_lds_dwordx4 v134, s[26:27]
	s_nop 0
	s_waitcnt vmcnt(8)
	s_waitcnt lgkmcnt(0)
	s_barrier
	v_mfma_f32_16x16x32_bf16 v[128:131], v[142:145], v[178:181], v[128:131]
	v_mfma_f32_16x16x32_bf16 v[128:131], v[146:149], v[182:185], v[128:131]
	v_mfma_f32_16x16x32_bf16 v[124:127], v[154:157], v[178:181], v[124:127]
	v_mfma_f32_16x16x32_bf16 v[124:127], v[158:161], v[182:185], v[124:127]
	v_mfma_f32_16x16x32_bf16 v[108:111], v[154:157], v[186:189], v[108:111]
	v_mfma_f32_16x16x32_bf16 v[108:111], v[158:161], v[190:193], v[108:111]
	v_mfma_f32_16x16x32_bf16 v[112:115], v[142:145], v[186:189], v[112:115]
	v_mfma_f32_16x16x32_bf16 v[112:115], v[146:149], v[190:193], v[112:115]
	v_mfma_f32_16x16x32_bf16 v[96:99], v[142:145], v[194:197], v[96:99]
	v_mfma_f32_16x16x32_bf16 v[96:99], v[146:149], v[198:201], v[96:99]
	v_mfma_f32_16x16x32_bf16 v[92:95], v[154:157], v[194:197], v[92:95]
	v_mfma_f32_16x16x32_bf16 v[92:95], v[158:161], v[198:201], v[92:95]
	v_mfma_f32_16x16x32_bf16 v[76:79], v[154:157], v[202:205], v[76:79]
	v_mfma_f32_16x16x32_bf16 v[76:79], v[158:161], v[206:209], v[76:79]
	v_mfma_f32_16x16x32_bf16 v[80:83], v[142:145], v[202:205], v[80:83]
	v_mfma_f32_16x16x32_bf16 v[80:83], v[146:149], v[206:209], v[80:83]
	v_mfma_f32_16x16x32_bf16 v[120:123], v[162:165], v[178:181], v[120:123]
	v_mfma_f32_16x16x32_bf16 v[120:123], v[166:169], v[182:185], v[120:123]
	v_mfma_f32_16x16x32_bf16 v[116:119], v[170:173], v[178:181], v[116:119]
	v_mfma_f32_16x16x32_bf16 v[116:119], v[174:177], v[182:185], v[116:119]
	v_mfma_f32_16x16x32_bf16 v[100:103], v[170:173], v[186:189], v[100:103]
	v_mfma_f32_16x16x32_bf16 v[100:103], v[174:177], v[190:193], v[100:103]
	v_mfma_f32_16x16x32_bf16 v[104:107], v[162:165], v[186:189], v[104:107]
	v_mfma_f32_16x16x32_bf16 v[104:107], v[166:169], v[190:193], v[104:107]
	v_mfma_f32_16x16x32_bf16 v[88:91], v[162:165], v[194:197], v[88:91]
	v_mfma_f32_16x16x32_bf16 v[88:91], v[166:169], v[198:201], v[88:91]
	v_mfma_f32_16x16x32_bf16 v[84:87], v[170:173], v[194:197], v[84:87]
	v_mfma_f32_16x16x32_bf16 v[84:87], v[174:177], v[198:201], v[84:87]
	v_mfma_f32_16x16x32_bf16 v[68:71], v[170:173], v[202:205], v[68:71]
	v_mfma_f32_16x16x32_bf16 v[68:71], v[174:177], v[206:209], v[68:71]
	v_mfma_f32_16x16x32_bf16 v[72:75], v[162:165], v[202:205], v[72:75]
	v_mfma_f32_16x16x32_bf16 v[72:75], v[166:169], v[206:209], v[72:75]
	s_barrier
	ds_read_b128 v[178:181], v153 offset:49152
	ds_read_b128 v[182:185], v153 offset:50176
	ds_read_b128 v[186:189], v153 offset:51200
	ds_read_b128 v[190:193], v153 offset:52224
	ds_read_b128 v[194:197], v153 offset:53248
	ds_read_b128 v[198:201], v153 offset:54272
	ds_read_b128 v[202:205], v153 offset:55296
	ds_read_b128 v[206:209], v153 offset:56320
	s_add_i32 s26, s61, s9
	s_mov_b32 m0, s26
	s_add_u32 s0, s0, 0x80
	s_addc_u32 s1, s1, 0
	global_load_lds_dwordx4 v2, s[0:1]
	s_add_i32 m0, s26, 0x2000
	s_add_i32 s26, s62, s9
	global_load_lds_dwordx4 v132, s[0:1]
	s_add_u32 s0, s0, 0x100000
	s_addc_u32 s1, s1, 0
	s_mov_b32 m0, s26
	s_nop 0
	global_load_lds_dwordx4 v2, s[0:1]
	s_add_i32 m0, s26, 0x2000
	s_nop 0
	global_load_lds_dwordx4 v132, s[0:1]
	s_waitcnt vmcnt(6)
	s_waitcnt lgkmcnt(0)
	s_barrier
	v_mfma_f32_16x16x32_bf16 v[64:67], v[142:145], v[178:181], v[64:67]
	v_mfma_f32_16x16x32_bf16 v[64:67], v[146:149], v[182:185], v[64:67]
	v_mfma_f32_16x16x32_bf16 v[60:63], v[154:157], v[178:181], v[60:63]
	v_mfma_f32_16x16x32_bf16 v[60:63], v[158:161], v[182:185], v[60:63]
	v_mfma_f32_16x16x32_bf16 v[44:47], v[154:157], v[186:189], v[44:47]
	v_mfma_f32_16x16x32_bf16 v[44:47], v[158:161], v[190:193], v[44:47]
	v_mfma_f32_16x16x32_bf16 v[48:51], v[142:145], v[186:189], v[48:51]
	v_mfma_f32_16x16x32_bf16 v[48:51], v[146:149], v[190:193], v[48:51]
	v_mfma_f32_16x16x32_bf16 v[32:35], v[142:145], v[194:197], v[32:35]
	v_mfma_f32_16x16x32_bf16 v[32:35], v[146:149], v[198:201], v[32:35]
	v_mfma_f32_16x16x32_bf16 v[28:31], v[154:157], v[194:197], v[28:31]
	v_mfma_f32_16x16x32_bf16 v[28:31], v[158:161], v[198:201], v[28:31]
	v_mfma_f32_16x16x32_bf16 v[12:15], v[154:157], v[202:205], v[12:15]
	v_mfma_f32_16x16x32_bf16 v[12:15], v[158:161], v[206:209], v[12:15]
	v_mfma_f32_16x16x32_bf16 v[16:19], v[142:145], v[202:205], v[16:19]
	v_mfma_f32_16x16x32_bf16 v[16:19], v[146:149], v[206:209], v[16:19]
	s_add_i32 s60, s60, 2
	s_add_u32 s50, s50, 0x100
	s_addc_u32 s51, s51, 0
	s_add_u32 s43, s43, 0x100
	s_addc_u32 s45, s45, 0
	s_nop 0
	v_mfma_f32_16x16x32_bf16 v[56:59], v[162:165], v[178:181], v[56:59]
	v_mfma_f32_16x16x32_bf16 v[56:59], v[166:169], v[182:185], v[56:59]
	v_mfma_f32_16x16x32_bf16 v[52:55], v[170:173], v[178:181], v[52:55]
	v_mfma_f32_16x16x32_bf16 v[52:55], v[174:177], v[182:185], v[52:55]
	v_mfma_f32_16x16x32_bf16 v[36:39], v[170:173], v[186:189], v[36:39]
	v_mfma_f32_16x16x32_bf16 v[36:39], v[174:177], v[190:193], v[36:39]
	v_mfma_f32_16x16x32_bf16 v[40:43], v[162:165], v[186:189], v[40:43]
	v_mfma_f32_16x16x32_bf16 v[40:43], v[166:169], v[190:193], v[40:43]
	v_mfma_f32_16x16x32_bf16 v[24:27], v[162:165], v[194:197], v[24:27]
	v_mfma_f32_16x16x32_bf16 v[24:27], v[166:169], v[198:201], v[24:27]
	v_mfma_f32_16x16x32_bf16 v[20:23], v[170:173], v[194:197], v[20:23]
	v_mfma_f32_16x16x32_bf16 v[20:23], v[174:177], v[198:201], v[20:23]
	v_mfma_f32_16x16x32_bf16 v[4:7], v[170:173], v[202:205], v[4:7]
	v_mfma_f32_16x16x32_bf16 v[4:7], v[174:177], v[206:209], v[4:7]
	v_mfma_f32_16x16x32_bf16 v[8:11], v[162:165], v[202:205], v[8:11]
	v_mfma_f32_16x16x32_bf16 v[8:11], v[166:169], v[206:209], v[8:11]
	s_barrier
	s_cmp_gt_u32 s60, 61
	s_cbranch_scc0 .LBB0_2089
	s_and_b64 vcc, exec, s[40:41]
	s_cbranch_vccz .LBB0_2092
	s_barrier

; #define PG8_STAGE(bufoff, gbase, voff) do { _Pragma("unroll") for (int _i = 0; _i < 2; ++_i) \
;         __builtin_amdgcn_global_load_lds((const unsigned*)((const char*)(gbase) + (voff)[_i]), (PG8_LAS unsigned*)(lds + (bufoff) + ldsw + _i * 8192), 16, 0, 0); } while (0)
; #define PG8_LDA(dst, b, h) do { _Pragma("unroll") for (int m = 0; m < 4; ++m) _Pragma("unroll") for (int k = 0; k < 2; ++k) dst[m][k] = *(const PG8_LAS bf16x8*)(lds + PG8_SA(b, h) + aoff + m * 2048 + k * 1024); } while (0)
; #define PG8_LDB(dst, b, h) do { _Pragma("unroll") for (int n = 0; n < 2; ++n) _Pragma("unroll") for (int k = 0; k < 2; ++k) dst[n][k] = *(const PG8_LAS bf16x8*)(lds + PG8_SB(b, h) + boff + n * 2048 + k * 1024); } while (0)
; #define PG8_MMA(ai, bj, At, Bt) do { __builtin_amdgcn_s_setprio(1); _Pragma("unroll") for (int m = 0; m < 4; ++m) _Pragma("unroll") for (int n = 0; n < 2; ++n) _Pragma("unroll") for (int k = 0; k < 2; ++k) \
;         acc[ai][bj][m][n] = __builtin_amdgcn_mfma_f32_16x16x32_bf16(Bt[n][k], At[m][k], acc[ai][bj][m][n], 0, 0, 0); __builtin_amdgcn_s_setprio(0); } while (0)
; #define PG8_WAIT_V(n) asm volatile("s_waitcnt vmcnt(" #n ")" ::: "memory")
; #define PG8_WAIT_L(n) asm volatile("s_waitcnt lgkmcnt(" #n ")" ::: "memory")
; #define PG8_BAR __builtin_amdgcn_s_barrier()
; #define PG8_SCHED __builtin_amdgcn_sched_barrier(0)
; template <class Epi, class Sched, bool ALIGN_EPI = false, bool SP2 = false>
; __device__ __forceinline__ void gemm_phase(PG8_LAS unsigned char* lds, const Gemm g, const Sched& S, const Epi& E) {
;     ...
;             PG8_LDB(B0, 0, 0); PG8_LDB(B1, 0, 1); PG8_SCHED; PG8_LDA(At, 0, 0); PG8_STAGE(PG8_SA(1, 1), a1 + hstep, voffA);
;             PG8_WAIT_V(8); PG8_WAIT_L(0); PG8_BAR; PG8_MMA(0, 0, At, B0); PG8_MMA(0, 1, At, B1); PG8_BAR; PG8_SCHED;
;             PG8_LDA(At, 0, 1); PG8_STAGE(PG8_SB(0, 0), b2, voffB); PG8_STAGE(PG8_SB(0, 1), b2 + hstep, voffB); PG8_STAGE(PG8_SA(0, 0), a2, voffA);
;             PG8_WAIT_V(8); PG8_WAIT_L(0); PG8_BAR; PG8_MMA(1, 0, At, B0); PG8_MMA(1, 1, At, B1); PG8_BAR; PG8_SCHED;
.LBB0_2115:
	ds_read_b128 v[132:135], v188
	ds_read_b128 v[136:139], v188 offset:1024
	ds_read_b128 v[152:155], v188 offset:2048
	ds_read_b128 v[156:159], v188 offset:3072
	ds_read_b128 v[160:163], v188 offset:16384
	ds_read_b128 v[164:167], v188 offset:17408
	ds_read_b128 v[168:171], v188 offset:18432
	ds_read_b128 v[172:175], v188 offset:19456
	ds_read_b128 v[176:179], v194
	ds_read_b128 v[180:183], v194 offset:1024
	ds_read_b128 v[184:187], v194 offset:2048
	ds_read_b128 v[196:199], v194 offset:3072
	ds_read_b128 v[200:203], v194 offset:4096
	ds_read_b128 v[204:207], v194 offset:5120
	ds_read_b128 v[208:211], v194 offset:6144
	ds_read_b128 v[212:215], v194 offset:7168
	s_add_u32 s0, s40, 0xfff00080
	s_addc_u32 s1, s41, -1
	s_add_i32 s77, 0, 0x10000
	s_cmp_eq_u32 s76, 60
	s_cselect_b32 s27, s49, s1
	s_cselect_b32 s26, s57, s0
	s_cselect_b32 s1, s47, s59
	s_cselect_b32 s0, s73, s58
	s_add_i32 s80, 0, 0x14000
	s_add_u32 s100, s40, 0xfff00000
	s_addc_u32 s101, s41, -1
	s_mov_b32 m0, s62
	s_nop 0
	global_load_lds_dwordx4 v140, s[100:101]
	s_mov_b32 m0, s63
	s_nop 0
	global_load_lds_dwordx4 v142, s[100:101]
	s_add_i32 m0, s11, 0xc000
	s_nop 0
	global_load_lds_dwordx4 v148, s[40:41]
	s_add_i32 m0, s11, 0xe000
	s_nop 0
	global_load_lds_dwordx4 v150, s[40:41]
	s_nop 0
	s_nop 0
	s_waitcnt vmcnt(8)
	s_waitcnt lgkmcnt(0)
	s_barrier
	v_mfma_f32_16x16x32_bf16 v[128:131], v[132:135], v[176:179], v[128:131]
	v_mfma_f32_16x16x32_bf16 v[128:131], v[136:139], v[180:183], v[128:131]
	v_mfma_f32_16x16x32_bf16 v[124:127], v[152:155], v[176:179], v[124:127]
	v_mfma_f32_16x16x32_bf16 v[124:127], v[156:159], v[180:183], v[124:127]
	v_mfma_f32_16x16x32_bf16 v[108:111], v[152:155], v[184:187], v[108:111]
	v_mfma_f32_16x16x32_bf16 v[108:111], v[156:159], v[196:199], v[108:111]
	v_mfma_f32_16x16x32_bf16 v[112:115], v[132:135], v[184:187], v[112:115]
	v_mfma_f32_16x16x32_bf16 v[112:115], v[136:139], v[196:199], v[112:115]
	v_mfma_f32_16x16x32_bf16 v[96:99], v[132:135], v[200:203], v[96:99]
	v_mfma_f32_16x16x32_bf16 v[96:99], v[136:139], v[204:207], v[96:99]
	v_mfma_f32_16x16x32_bf16 v[92:95], v[152:155], v[200:203], v[92:95]
	v_mfma_f32_16x16x32_bf16 v[92:95], v[156:159], v[204:207], v[92:95]
	v_mfma_f32_16x16x32_bf16 v[76:79], v[152:155], v[208:211], v[76:79]
	v_mfma_f32_16x16x32_bf16 v[76:79], v[156:159], v[212:215], v[76:79]
	v_mfma_f32_16x16x32_bf16 v[80:83], v[132:135], v[208:211], v[80:83]
	v_mfma_f32_16x16x32_bf16 v[80:83], v[136:139], v[212:215], v[80:83]
	v_mfma_f32_16x16x32_bf16 v[120:123], v[160:163], v[176:179], v[120:123]
	v_mfma_f32_16x16x32_bf16 v[120:123], v[164:167], v[180:183], v[120:123]
	v_mfma_f32_16x16x32_bf16 v[116:119], v[168:171], v[176:179], v[116:119]
	v_mfma_f32_16x16x32_bf16 v[116:119], v[172:175], v[180:183], v[116:119]
	v_mfma_f32_16x16x32_bf16 v[100:103], v[168:171], v[184:187], v[100:103]
	v_mfma_f32_16x16x32_bf16 v[100:103], v[172:175], v[196:199], v[100:103]
	v_mfma_f32_16x16x32_bf16 v[104:107], v[160:163], v[184:187], v[104:107]
	v_mfma_f32_16x16x32_bf16 v[104:107], v[164:167], v[196:199], v[104:107]
	v_mfma_f32_16x16x32_bf16 v[88:91], v[160:163], v[200:203], v[88:91]
	v_mfma_f32_16x16x32_bf16 v[88:91], v[164:167], v[204:207], v[88:91]
	v_mfma_f32_16x16x32_bf16 v[84:87], v[168:171], v[200:203], v[84:87]
	v_mfma_f32_16x16x32_bf16 v[84:87], v[172:175], v[204:207], v[84:87]
	v_mfma_f32_16x16x32_bf16 v[68:71], v[168:171], v[208:211], v[68:71]
	v_mfma_f32_16x16x32_bf16 v[68:71], v[172:175], v[212:215], v[68:71]
	v_mfma_f32_16x16x32_bf16 v[72:75], v[160:163], v[208:211], v[72:75]
	v_mfma_f32_16x16x32_bf16 v[72:75], v[164:167], v[212:215], v[72:75]
	s_barrier
	ds_read_b128 v[176:179], v194 offset:16384
	ds_read_b128 v[180:183], v194 offset:17408
	ds_read_b128 v[184:187], v194 offset:18432
	ds_read_b128 v[196:199], v194 offset:19456
	ds_read_b128 v[200:203], v194 offset:20480
	ds_read_b128 v[204:207], v194 offset:21504
	ds_read_b128 v[208:211], v194 offset:22528
	ds_read_b128 v[212:215], v194 offset:23552
	s_add_i32 s77, s77, s10
	s_mov_b32 m0, s77
	s_nop 0
	global_load_lds_dwordx4 v2, s[0:1]
	s_add_i32 m0, s77, 0x2000
	s_add_u32 s78, s0, 0x100000
	s_addc_u32 s79, s1, 0
	s_add_i32 s77, s80, s10
	global_load_lds_dwordx4 v144, s[0:1]
	s_mov_b32 m0, s77
	s_nop 0
	global_load_lds_dwordx4 v2, s[78:79]
	s_add_i32 m0, s77, 0x2000
	s_nop 0
	global_load_lds_dwordx4 v144, s[78:79]
	s_waitcnt vmcnt(6)
	s_waitcnt lgkmcnt(0)
	s_barrier
	v_mfma_f32_16x16x32_bf16 v[64:67], v[132:135], v[176:179], v[64:67]
	v_mfma_f32_16x16x32_bf16 v[64:67], v[136:139], v[180:183], v[64:67]
	v_mfma_f32_16x16x32_bf16 v[60:63], v[152:155], v[176:179], v[60:63]
	v_mfma_f32_16x16x32_bf16 v[60:63], v[156:159], v[180:183], v[60:63]
	v_mfma_f32_16x16x32_bf16 v[44:47], v[152:155], v[184:187], v[44:47]
	v_mfma_f32_16x16x32_bf16 v[44:47], v[156:159], v[196:199], v[44:47]
	v_mfma_f32_16x16x32_bf16 v[48:51], v[132:135], v[184:187], v[48:51]
	v_mfma_f32_16x16x32_bf16 v[48:51], v[136:139], v[196:199], v[48:51]
	v_mfma_f32_16x16x32_bf16 v[32:35], v[132:135], v[200:203], v[32:35]
	v_mfma_f32_16x16x32_bf16 v[32:35], v[136:139], v[204:207], v[32:35]
	v_mfma_f32_16x16x32_bf16 v[28:31], v[152:155], v[200:203], v[28:31]
	v_mfma_f32_16x16x32_bf16 v[28:31], v[156:159], v[204:207], v[28:31]
	v_mfma_f32_16x16x32_bf16 v[12:15], v[152:155], v[208:211], v[12:15]
	v_mfma_f32_16x16x32_bf16 v[12:15], v[156:159], v[212:215], v[12:15]
	v_mfma_f32_16x16x32_bf16 v[16:19], v[132:135], v[208:211], v[16:19]
	v_mfma_f32_16x16x32_bf16 v[16:19], v[136:139], v[212:215], v[16:19]
	v_mfma_f32_16x16x32_bf16 v[56:59], v[160:163], v[176:179], v[56:59]
	v_mfma_f32_16x16x32_bf16 v[56:59], v[164:167], v[180:183], v[56:59]
	v_mfma_f32_16x16x32_bf16 v[52:55], v[168:171], v[176:179], v[52:55]
	v_mfma_f32_16x16x32_bf16 v[52:55], v[172:175], v[180:183], v[52:55]
	v_mfma_f32_16x16x32_bf16 v[36:39], v[168:171], v[184:187], v[36:39]
	v_mfma_f32_16x16x32_bf16 v[36:39], v[172:175], v[196:199], v[36:39]
	v_mfma_f32_16x16x32_bf16 v[40:43], v[160:163], v[184:187], v[40:43]
	v_mfma_f32_16x16x32_bf16 v[40:43], v[164:167], v[196:199], v[40:43]
	v_mfma_f32_16x16x32_bf16 v[24:27], v[160:163], v[200:203], v[24:27]
	v_mfma_f32_16x16x32_bf16 v[24:27], v[164:167], v[204:207], v[24:27]
	v_mfma_f32_16x16x32_bf16 v[20:23], v[168:171], v[200:203], v[20:23]
	v_mfma_f32_16x16x32_bf16 v[20:23], v[172:175], v[204:207], v[20:23]
	v_mfma_f32_16x16x32_bf16 v[4:7], v[168:171], v[208:211], v[4:7]
	v_mfma_f32_16x16x32_bf16 v[4:7], v[172:175], v[212:215], v[4:7]
	v_mfma_f32_16x16x32_bf16 v[8:11], v[160:163], v[208:211], v[8:11]
	v_mfma_f32_16x16x32_bf16 v[8:11], v[164:167], v[212:215], v[8:11]
	s_barrier
; #define PG8_STAGE(bufoff, gbase, voff) do { _Pragma("unroll") for (int _i = 0; _i < 2; ++_i) \
;         __builtin_amdgcn_global_load_lds((const unsigned*)((const char*)(gbase) + (voff)[_i]), (PG8_LAS unsigned*)(lds + (bufoff) + ldsw + _i * 8192), 16, 0, 0); } while (0)
; #define PG8_LDA(dst, b, h) do { _Pragma("unroll") for (int m = 0; m < 4; ++m) _Pragma("unroll") for (int k = 0; k < 2; ++k) dst[m][k] = *(const PG8_LAS bf16x8*)(lds + PG8_SA(b, h) + aoff + m * 2048 + k * 1024); } while (0)
; #define PG8_LDB(dst, b, h) do { _Pragma("unroll") for (int n = 0; n < 2; ++n) _Pragma("unroll") for (int k = 0; k < 2; ++k) dst[n][k] = *(const PG8_LAS bf16x8*)(lds + PG8_SB(b, h) + boff + n * 2048 + k * 1024); } while (0)
; #define PG8_MMA(ai, bj, At, Bt) do { __builtin_amdgcn_s_setprio(1); _Pragma("unroll") for (int m = 0; m < 4; ++m) _Pragma("unroll") for (int n = 0; n < 2; ++n) _Pragma("unroll") for (int k = 0; k < 2; ++k) \
;         acc[ai][bj][m][n] = __builtin_amdgcn_mfma_f32_16x16x32_bf16(Bt[n][k], At[m][k], acc[ai][bj][m][n], 0, 0, 0); __builtin_amdgcn_s_setprio(0); } while (0)
; #define PG8_WAIT_V(n) asm volatile("s_waitcnt vmcnt(" #n ")" ::: "memory")
; #define PG8_WAIT_L(n) asm volatile("s_waitcnt lgkmcnt(" #n ")" ::: "memory")
; #define PG8_BAR __builtin_amdgcn_s_barrier()
; #define PG8_SCHED __builtin_amdgcn_sched_barrier(0)
; template <class Epi, class Sched, bool ALIGN_EPI = false, bool SP2 = false>
; __device__ __forceinline__ void gemm_phase(PG8_LAS unsigned char* lds, const Gemm g, const Sched& S, const Epi& E) {
;     ...
;             PG8_LDB(B0, 1, 0); PG8_LDB(B1, 1, 1); PG8_SCHED; PG8_LDA(At, 1, 0); PG8_STAGE(PG8_SA(0, 1), a2 + hstep, voffA);
;             PG8_WAIT_V(8); PG8_WAIT_L(0); PG8_BAR; PG8_MMA(0, 0, At, B0); PG8_MMA(0, 1, At, B1); PG8_BAR; PG8_SCHED;
;             PG8_LDA(At, 1, 1); PG8_STAGE(PG8_SB(1, 0), b3, voffB); PG8_STAGE(PG8_SB(1, 1), b3 + hstep, voffB); PG8_STAGE(PG8_SA(1, 0), a3, voffA);
;             PG8_WAIT_V(8); PG8_WAIT_L(0); PG8_BAR; PG8_MMA(1, 0, At, B0); PG8_MMA(1, 1, At, B1); PG8_BAR; PG8_SCHED;
	ds_read_b128 v[132:135], v188 offset:32768
	ds_read_b128 v[136:139], v188 offset:33792
	ds_read_b128 v[152:155], v188 offset:34816
	ds_read_b128 v[156:159], v188 offset:35840
	ds_read_b128 v[160:163], v188 offset:49152
	ds_read_b128 v[164:167], v188 offset:50176
	ds_read_b128 v[168:171], v188 offset:51200
	ds_read_b128 v[172:175], v188 offset:52224
	ds_read_b128 v[176:179], v194 offset:32768
	ds_read_b128 v[180:183], v194 offset:33792
	ds_read_b128 v[184:187], v194 offset:34816
	ds_read_b128 v[196:199], v194 offset:35840
	ds_read_b128 v[200:203], v194 offset:36864
	ds_read_b128 v[204:207], v194 offset:37888
	ds_read_b128 v[208:211], v194 offset:38912
	ds_read_b128 v[212:215], v194 offset:39936
	s_add_i32 s77, 0, 0x18000
	s_add_i32 s78, 0, 0x1c000
	s_mov_b32 m0, s11
	s_nop 0
	global_load_lds_dwordx4 v140, s[26:27]
	s_mov_b32 m0, s55
	s_nop 0
	global_load_lds_dwordx4 v142, s[26:27]
	s_add_u32 s26, s26, 0x100000
	s_addc_u32 s27, s27, 0
	s_mov_b32 m0, s60
	s_nop 0
	global_load_lds_dwordx4 v140, s[26:27]
	s_mov_b32 m0, s61
	s_nop 0
	global_load_lds_dwordx4 v142, s[26:27]
	s_nop 0
	s_waitcnt vmcnt(8)
	s_waitcnt lgkmcnt(0)
	s_barrier
	v_mfma_f32_16x16x32_bf16 v[128:131], v[132:135], v[176:179], v[128:131]
	v_mfma_f32_16x16x32_bf16 v[128:131], v[136:139], v[180:183], v[128:131]
	v_mfma_f32_16x16x32_bf16 v[124:127], v[152:155], v[176:179], v[124:127]
	v_mfma_f32_16x16x32_bf16 v[124:127], v[156:159], v[180:183], v[124:127]
	v_mfma_f32_16x16x32_bf16 v[108:111], v[152:155], v[184:187], v[108:111]
	v_mfma_f32_16x16x32_bf16 v[108:111], v[156:159], v[196:199], v[108:111]
	v_mfma_f32_16x16x32_bf16 v[112:115], v[132:135], v[184:187], v[112:115]
	v_mfma_f32_16x16x32_bf16 v[112:115], v[136:139], v[196:199], v[112:115]
	v_mfma_f32_16x16x32_bf16 v[96:99], v[132:135], v[200:203], v[96:99]
	v_mfma_f32_16x16x32_bf16 v[96:99], v[136:139], v[204:207], v[96:99]
	v_mfma_f32_16x16x32_bf16 v[92:95], v[152:155], v[200:203], v[92:95]
	v_mfma_f32_16x16x32_bf16 v[92:95], v[156:159], v[204:207], v[92:95]
	v_mfma_f32_16x16x32_bf16 v[76:79], v[152:155], v[208:211], v[76:79]
	v_mfma_f32_16x16x32_bf16 v[76:79], v[156:159], v[212:215], v[76:79]
	v_mfma_f32_16x16x32_bf16 v[80:83], v[132:135], v[208:211], v[80:83]
	v_mfma_f32_16x16x32_bf16 v[80:83], v[136:139], v[212:215], v[80:83]
	v_mfma_f32_16x16x32_bf16 v[120:123], v[160:163], v[176:179], v[120:123]
	v_mfma_f32_16x16x32_bf16 v[120:123], v[164:167], v[180:183], v[120:123]
	v_mfma_f32_16x16x32_bf16 v[116:119], v[168:171], v[176:179], v[116:119]
	v_mfma_f32_16x16x32_bf16 v[116:119], v[172:175], v[180:183], v[116:119]
	v_mfma_f32_16x16x32_bf16 v[100:103], v[168:171], v[184:187], v[100:103]
	v_mfma_f32_16x16x32_bf16 v[100:103], v[172:175], v[196:199], v[100:103]
	v_mfma_f32_16x16x32_bf16 v[104:107], v[160:163], v[184:187], v[104:107]
	v_mfma_f32_16x16x32_bf16 v[104:107], v[164:167], v[196:199], v[104:107]
	v_mfma_f32_16x16x32_bf16 v[88:91], v[160:163], v[200:203], v[88:91]
	v_mfma_f32_16x16x32_bf16 v[88:91], v[164:167], v[204:207], v[88:91]
	v_mfma_f32_16x16x32_bf16 v[84:87], v[168:171], v[200:203], v[84:87]
	v_mfma_f32_16x16x32_bf16 v[84:87], v[172:175], v[204:207], v[84:87]
	v_mfma_f32_16x16x32_bf16 v[68:71], v[168:171], v[208:211], v[68:71]
	v_mfma_f32_16x16x32_bf16 v[68:71], v[172:175], v[212:215], v[68:71]
	v_mfma_f32_16x16x32_bf16 v[72:75], v[160:163], v[208:211], v[72:75]
	v_mfma_f32_16x16x32_bf16 v[72:75], v[164:167], v[212:215], v[72:75]
	s_barrier
	ds_read_b128 v[176:179], v194 offset:49152
	ds_read_b128 v[180:183], v194 offset:50176
	ds_read_b128 v[184:187], v194 offset:51200
	ds_read_b128 v[196:199], v194 offset:52224
	ds_read_b128 v[200:203], v194 offset:53248
	ds_read_b128 v[204:207], v194 offset:54272
	ds_read_b128 v[208:211], v194 offset:55296
	ds_read_b128 v[212:215], v194 offset:56320
	s_add_i32 s26, s77, s10
	s_mov_b32 m0, s26
	s_add_u32 s0, s0, 0x80
	s_addc_u32 s1, s1, 0
	global_load_lds_dwordx4 v2, s[0:1]
	s_add_i32 m0, s26, 0x2000
	s_add_i32 s26, s78, s10
	global_load_lds_dwordx4 v144, s[0:1]
	s_add_u32 s0, s0, 0x100000
	s_addc_u32 s1, s1, 0
	s_mov_b32 m0, s26
	s_nop 0
	global_load_lds_dwordx4 v2, s[0:1]
	s_add_i32 m0, s26, 0x2000
	s_nop 0
	global_load_lds_dwordx4 v144, s[0:1]
	s_waitcnt vmcnt(6)
	s_waitcnt lgkmcnt(0)
	s_barrier
	v_mfma_f32_16x16x32_bf16 v[64:67], v[132:135], v[176:179], v[64:67]
	v_mfma_f32_16x16x32_bf16 v[64:67], v[136:139], v[180:183], v[64:67]
	v_mfma_f32_16x16x32_bf16 v[60:63], v[152:155], v[176:179], v[60:63]
	v_mfma_f32_16x16x32_bf16 v[60:63], v[156:159], v[180:183], v[60:63]
	v_mfma_f32_16x16x32_bf16 v[44:47], v[152:155], v[184:187], v[44:47]
	v_mfma_f32_16x16x32_bf16 v[44:47], v[156:159], v[196:199], v[44:47]
	v_mfma_f32_16x16x32_bf16 v[48:51], v[132:135], v[184:187], v[48:51]
	v_mfma_f32_16x16x32_bf16 v[48:51], v[136:139], v[196:199], v[48:51]
	v_mfma_f32_16x16x32_bf16 v[32:35], v[132:135], v[200:203], v[32:35]
	v_mfma_f32_16x16x32_bf16 v[32:35], v[136:139], v[204:207], v[32:35]
	v_mfma_f32_16x16x32_bf16 v[28:31], v[152:155], v[200:203], v[28:31]
	v_mfma_f32_16x16x32_bf16 v[28:31], v[156:159], v[204:207], v[28:31]
	v_mfma_f32_16x16x32_bf16 v[12:15], v[152:155], v[208:211], v[12:15]
	v_mfma_f32_16x16x32_bf16 v[12:15], v[156:159], v[212:215], v[12:15]
	v_mfma_f32_16x16x32_bf16 v[16:19], v[132:135], v[208:211], v[16:19]
	v_mfma_f32_16x16x32_bf16 v[16:19], v[136:139], v[212:215], v[16:19]
	s_add_i32 s76, s76, 2
	s_add_u32 s40, s40, 0x100
	s_addc_u32 s41, s41, 0
	s_add_u32 s58, s58, 0x100
	s_addc_u32 s59, s59, 0
	s_nop 0
	v_mfma_f32_16x16x32_bf16 v[56:59], v[160:163], v[176:179], v[56:59]
	v_mfma_f32_16x16x32_bf16 v[56:59], v[164:167], v[180:183], v[56:59]
	v_mfma_f32_16x16x32_bf16 v[52:55], v[168:171], v[176:179], v[52:55]
	v_mfma_f32_16x16x32_bf16 v[52:55], v[172:175], v[180:183], v[52:55]
	v_mfma_f32_16x16x32_bf16 v[36:39], v[168:171], v[184:187], v[36:39]
	v_mfma_f32_16x16x32_bf16 v[36:39], v[172:175], v[196:199], v[36:39]
	v_mfma_f32_16x16x32_bf16 v[40:43], v[160:163], v[184:187], v[40:43]
	v_mfma_f32_16x16x32_bf16 v[40:43], v[164:167], v[196:199], v[40:43]
	v_mfma_f32_16x16x32_bf16 v[24:27], v[160:163], v[200:203], v[24:27]
	v_mfma_f32_16x16x32_bf16 v[24:27], v[164:167], v[204:207], v[24:27]
	v_mfma_f32_16x16x32_bf16 v[20:23], v[168:171], v[200:203], v[20:23]
	v_mfma_f32_16x16x32_bf16 v[20:23], v[172:175], v[204:207], v[20:23]
	v_mfma_f32_16x16x32_bf16 v[4:7], v[168:171], v[208:211], v[4:7]
	v_mfma_f32_16x16x32_bf16 v[4:7], v[172:175], v[212:215], v[4:7]
	v_mfma_f32_16x16x32_bf16 v[8:11], v[160:163], v[208:211], v[8:11]
	v_mfma_f32_16x16x32_bf16 v[8:11], v[164:167], v[212:215], v[8:11]
	s_barrier
	s_cmp_gt_u32 s76, 61
	s_cbranch_scc0 .LBB0_2115
	s_and_b64 vcc, exec, s[36:37]
	s_cbranch_vccz .LBB0_2118
	s_barrier

; #define PG8_STAGE(bufoff, gbase, voff) do { _Pragma("unroll") for (int _i = 0; _i < 2; ++_i) \
;         __builtin_amdgcn_global_load_lds((const unsigned*)((const char*)(gbase) + (voff)[_i]), (PG8_LAS unsigned*)(lds + (bufoff) + ldsw + _i * 8192), 16, 0, 0); } while (0)
; #define PG8_LDA(dst, b, h) do { _Pragma("unroll") for (int m = 0; m < 4; ++m) _Pragma("unroll") for (int k = 0; k < 2; ++k) dst[m][k] = *(const PG8_LAS bf16x8*)(lds + PG8_SA(b, h) + aoff + m * 2048 + k * 1024); } while (0)
; #define PG8_LDB(dst, b, h) do { _Pragma("unroll") for (int n = 0; n < 2; ++n) _Pragma("unroll") for (int k = 0; k < 2; ++k) dst[n][k] = *(const PG8_LAS bf16x8*)(lds + PG8_SB(b, h) + boff + n * 2048 + k * 1024); } while (0)
; #define PG8_MMA(ai, bj, At, Bt) do { __builtin_amdgcn_s_setprio(1); _Pragma("unroll") for (int m = 0; m < 4; ++m) _Pragma("unroll") for (int n = 0; n < 2; ++n) _Pragma("unroll") for (int k = 0; k < 2; ++k) \
;         acc[ai][bj][m][n] = __builtin_amdgcn_mfma_f32_16x16x32_bf16(Bt[n][k], At[m][k], acc[ai][bj][m][n], 0, 0, 0); __builtin_amdgcn_s_setprio(0); } while (0)
; #define PG8_WAIT_V(n) asm volatile("s_waitcnt vmcnt(" #n ")" ::: "memory")
; #define PG8_WAIT_L(n) asm volatile("s_waitcnt lgkmcnt(" #n ")" ::: "memory")
; #define PG8_BAR __builtin_amdgcn_s_barrier()
; #define PG8_SCHED __builtin_amdgcn_sched_barrier(0)
; template <class Epi, class Sched, bool ALIGN_EPI = false, bool SP2 = false>
; __device__ __forceinline__ void gemm_phase(PG8_LAS unsigned char* lds, const Gemm g, const Sched& S, const Epi& E) {
;     ...
;             PG8_LDB(B0, 0, 0); PG8_LDB(B1, 0, 1); PG8_SCHED; PG8_LDA(At, 0, 0); PG8_STAGE(PG8_SA(1, 1), a1 + hstep, voffA);
;             PG8_WAIT_V(8); PG8_WAIT_L(0); PG8_BAR; PG8_MMA(0, 0, At, B0); PG8_MMA(0, 1, At, B1); PG8_BAR; PG8_SCHED;
;             PG8_LDA(At, 0, 1); PG8_STAGE(PG8_SB(0, 0), b2, voffB); PG8_STAGE(PG8_SB(0, 1), b2 + hstep, voffB); PG8_STAGE(PG8_SA(0, 0), a2, voffA);
;             PG8_WAIT_V(8); PG8_WAIT_L(0); PG8_BAR; PG8_MMA(1, 0, At, B0); PG8_MMA(1, 1, At, B1); PG8_BAR; PG8_SCHED;
.LBB0_2692:
	ds_read_b128 v[142:145], v210
	ds_read_b128 v[150:153], v210 offset:1024
	ds_read_b128 v[154:157], v210 offset:2048
	ds_read_b128 v[158:161], v210 offset:3072
	ds_read_b128 v[162:165], v210 offset:16384
	ds_read_b128 v[166:169], v210 offset:17408
	ds_read_b128 v[170:173], v210 offset:18432
	ds_read_b128 v[174:177], v210 offset:19456
	ds_read_b128 v[178:181], v149
	ds_read_b128 v[182:185], v149 offset:1024
	ds_read_b128 v[186:189], v149 offset:2048
	ds_read_b128 v[190:193], v149 offset:3072
	ds_read_b128 v[194:197], v149 offset:4096
	ds_read_b128 v[198:201], v149 offset:5120
	ds_read_b128 v[202:205], v149 offset:6144
	ds_read_b128 v[206:209], v149 offset:7168
	s_add_u32 s0, s56, 0xfffe0080
	s_addc_u32 s1, s57, -1
	s_add_i32 s63, 0, 0x10000
	s_cmp_eq_u32 s62, 4
	s_cselect_b32 s27, s51, s1
	s_cselect_b32 s26, s50, s0
	s_cselect_b32 s1, s53, s49
	s_cselect_b32 s0, s52, s47
	s_add_i32 s66, 0, 0x14000
	s_add_u32 s100, s56, 0xfffe0000
	s_addc_u32 s101, s57, -1
	s_mov_b32 m0, s58
	s_nop 0
	global_load_lds_dwordx4 v132, s[100:101]
	s_mov_b32 m0, s59
	s_nop 0
	global_load_lds_dwordx4 v134, s[100:101]
	s_add_i32 m0, s10, 0xc000
	s_nop 0
	global_load_lds_dwordx4 v138, s[56:57]
	s_add_i32 m0, s10, 0xe000
	s_nop 0
	global_load_lds_dwordx4 v140, s[56:57]
	s_nop 0
	s_waitcnt vmcnt(8)
	s_waitcnt lgkmcnt(0)
	s_barrier
	v_mfma_f32_16x16x32_bf16 v[128:131], v[142:145], v[178:181], v[128:131]
	v_mfma_f32_16x16x32_bf16 v[128:131], v[150:153], v[182:185], v[128:131]
	v_mfma_f32_16x16x32_bf16 v[124:127], v[154:157], v[178:181], v[124:127]
	v_mfma_f32_16x16x32_bf16 v[124:127], v[158:161], v[182:185], v[124:127]
	v_mfma_f32_16x16x32_bf16 v[108:111], v[154:157], v[186:189], v[108:111]
	v_mfma_f32_16x16x32_bf16 v[108:111], v[158:161], v[190:193], v[108:111]
	v_mfma_f32_16x16x32_bf16 v[112:115], v[142:145], v[186:189], v[112:115]
	v_mfma_f32_16x16x32_bf16 v[112:115], v[150:153], v[190:193], v[112:115]
	v_mfma_f32_16x16x32_bf16 v[96:99], v[142:145], v[194:197], v[96:99]
	v_mfma_f32_16x16x32_bf16 v[96:99], v[150:153], v[198:201], v[96:99]
	v_mfma_f32_16x16x32_bf16 v[92:95], v[154:157], v[194:197], v[92:95]
	v_mfma_f32_16x16x32_bf16 v[92:95], v[158:161], v[198:201], v[92:95]
	v_mfma_f32_16x16x32_bf16 v[76:79], v[154:157], v[202:205], v[76:79]
	v_mfma_f32_16x16x32_bf16 v[76:79], v[158:161], v[206:209], v[76:79]
	v_mfma_f32_16x16x32_bf16 v[80:83], v[142:145], v[202:205], v[80:83]
	v_mfma_f32_16x16x32_bf16 v[80:83], v[150:153], v[206:209], v[80:83]
	v_mfma_f32_16x16x32_bf16 v[120:123], v[162:165], v[178:181], v[120:123]
	v_mfma_f32_16x16x32_bf16 v[120:123], v[166:169], v[182:185], v[120:123]
	v_mfma_f32_16x16x32_bf16 v[116:119], v[170:173], v[178:181], v[116:119]
	v_mfma_f32_16x16x32_bf16 v[116:119], v[174:177], v[182:185], v[116:119]
	v_mfma_f32_16x16x32_bf16 v[100:103], v[170:173], v[186:189], v[100:103]
	v_mfma_f32_16x16x32_bf16 v[100:103], v[174:177], v[190:193], v[100:103]
	v_mfma_f32_16x16x32_bf16 v[104:107], v[162:165], v[186:189], v[104:107]
	v_mfma_f32_16x16x32_bf16 v[104:107], v[166:169], v[190:193], v[104:107]
	v_mfma_f32_16x16x32_bf16 v[88:91], v[162:165], v[194:197], v[88:91]
	v_mfma_f32_16x16x32_bf16 v[88:91], v[166:169], v[198:201], v[88:91]
	v_mfma_f32_16x16x32_bf16 v[84:87], v[170:173], v[194:197], v[84:87]
	v_mfma_f32_16x16x32_bf16 v[84:87], v[174:177], v[198:201], v[84:87]
	v_mfma_f32_16x16x32_bf16 v[68:71], v[170:173], v[202:205], v[68:71]
	v_mfma_f32_16x16x32_bf16 v[68:71], v[174:177], v[206:209], v[68:71]
	v_mfma_f32_16x16x32_bf16 v[72:75], v[162:165], v[202:205], v[72:75]
	v_mfma_f32_16x16x32_bf16 v[72:75], v[166:169], v[206:209], v[72:75]
	s_barrier
	ds_read_b128 v[178:181], v149 offset:16384
	ds_read_b128 v[182:185], v149 offset:17408
	ds_read_b128 v[186:189], v149 offset:18432
	ds_read_b128 v[190:193], v149 offset:19456
	ds_read_b128 v[194:197], v149 offset:20480
	ds_read_b128 v[198:201], v149 offset:21504
	ds_read_b128 v[202:205], v149 offset:22528
	ds_read_b128 v[206:209], v149 offset:23552
	s_add_i32 s63, s63, s9
	s_mov_b32 m0, s63
	s_nop 0
	global_load_lds_dwordx4 v2, s[0:1]
	s_add_i32 m0, s63, 0x2000
	s_add_u32 s64, s0, 0x20000
	s_addc_u32 s65, s1, 0
	s_add_i32 s63, s66, s9
	global_load_lds_dwordx4 v136, s[0:1]
	s_mov_b32 m0, s63
	s_nop 0
	global_load_lds_dwordx4 v2, s[64:65]
	s_add_i32 m0, s63, 0x2000
	s_nop 0
	global_load_lds_dwordx4 v136, s[64:65]
	s_waitcnt vmcnt(6)
	s_waitcnt lgkmcnt(0)
	s_barrier
	v_mfma_f32_16x16x32_bf16 v[64:67], v[142:145], v[178:181], v[64:67]
	v_mfma_f32_16x16x32_bf16 v[64:67], v[150:153], v[182:185], v[64:67]
	v_mfma_f32_16x16x32_bf16 v[60:63], v[154:157], v[178:181], v[60:63]
	v_mfma_f32_16x16x32_bf16 v[60:63], v[158:161], v[182:185], v[60:63]
	v_mfma_f32_16x16x32_bf16 v[44:47], v[154:157], v[186:189], v[44:47]
	v_mfma_f32_16x16x32_bf16 v[44:47], v[158:161], v[190:193], v[44:47]
	v_mfma_f32_16x16x32_bf16 v[48:51], v[142:145], v[186:189], v[48:51]
	v_mfma_f32_16x16x32_bf16 v[48:51], v[150:153], v[190:193], v[48:51]
	v_mfma_f32_16x16x32_bf16 v[32:35], v[142:145], v[194:197], v[32:35]
	v_mfma_f32_16x16x32_bf16 v[32:35], v[150:153], v[198:201], v[32:35]
	v_mfma_f32_16x16x32_bf16 v[28:31], v[154:157], v[194:197], v[28:31]
	v_mfma_f32_16x16x32_bf16 v[28:31], v[158:161], v[198:201], v[28:31]
	v_mfma_f32_16x16x32_bf16 v[12:15], v[154:157], v[202:205], v[12:15]
	v_mfma_f32_16x16x32_bf16 v[12:15], v[158:161], v[206:209], v[12:15]
	v_mfma_f32_16x16x32_bf16 v[16:19], v[142:145], v[202:205], v[16:19]
	v_mfma_f32_16x16x32_bf16 v[16:19], v[150:153], v[206:209], v[16:19]
	v_mfma_f32_16x16x32_bf16 v[56:59], v[162:165], v[178:181], v[56:59]
	v_mfma_f32_16x16x32_bf16 v[56:59], v[166:169], v[182:185], v[56:59]
	v_mfma_f32_16x16x32_bf16 v[52:55], v[170:173], v[178:181], v[52:55]
	v_mfma_f32_16x16x32_bf16 v[52:55], v[174:177], v[182:185], v[52:55]
	v_mfma_f32_16x16x32_bf16 v[36:39], v[170:173], v[186:189], v[36:39]
	v_mfma_f32_16x16x32_bf16 v[36:39], v[174:177], v[190:193], v[36:39]
	v_mfma_f32_16x16x32_bf16 v[40:43], v[162:165], v[186:189], v[40:43]
	v_mfma_f32_16x16x32_bf16 v[40:43], v[166:169], v[190:193], v[40:43]
	v_mfma_f32_16x16x32_bf16 v[24:27], v[162:165], v[194:197], v[24:27]
	v_mfma_f32_16x16x32_bf16 v[24:27], v[166:169], v[198:201], v[24:27]
	v_mfma_f32_16x16x32_bf16 v[20:23], v[170:173], v[194:197], v[20:23]
	v_mfma_f32_16x16x32_bf16 v[20:23], v[174:177], v[198:201], v[20:23]
	v_mfma_f32_16x16x32_bf16 v[4:7], v[170:173], v[202:205], v[4:7]
	v_mfma_f32_16x16x32_bf16 v[4:7], v[174:177], v[206:209], v[4:7]
	v_mfma_f32_16x16x32_bf16 v[8:11], v[162:165], v[202:205], v[8:11]
	v_mfma_f32_16x16x32_bf16 v[8:11], v[166:169], v[206:209], v[8:11]
	s_barrier
; #define PG8_STAGE(bufoff, gbase, voff) do { _Pragma("unroll") for (int _i = 0; _i < 2; ++_i) \
;         __builtin_amdgcn_global_load_lds((const unsigned*)((const char*)(gbase) + (voff)[_i]), (PG8_LAS unsigned*)(lds + (bufoff) + ldsw + _i * 8192), 16, 0, 0); } while (0)
; #define PG8_LDA(dst, b, h) do { _Pragma("unroll") for (int m = 0; m < 4; ++m) _Pragma("unroll") for (int k = 0; k < 2; ++k) dst[m][k] = *(const PG8_LAS bf16x8*)(lds + PG8_SA(b, h) + aoff + m * 2048 + k * 1024); } while (0)
; #define PG8_LDB(dst, b, h) do { _Pragma("unroll") for (int n = 0; n < 2; ++n) _Pragma("unroll") for (int k = 0; k < 2; ++k) dst[n][k] = *(const PG8_LAS bf16x8*)(lds + PG8_SB(b, h) + boff + n * 2048 + k * 1024); } while (0)
; #define PG8_MMA(ai, bj, At, Bt) do { __builtin_amdgcn_s_setprio(1); _Pragma("unroll") for (int m = 0; m < 4; ++m) _Pragma("unroll") for (int n = 0; n < 2; ++n) _Pragma("unroll") for (int k = 0; k < 2; ++k) \
;         acc[ai][bj][m][n] = __builtin_amdgcn_mfma_f32_16x16x32_bf16(Bt[n][k], At[m][k], acc[ai][bj][m][n], 0, 0, 0); __builtin_amdgcn_s_setprio(0); } while (0)
; #define PG8_WAIT_V(n) asm volatile("s_waitcnt vmcnt(" #n ")" ::: "memory")
; #define PG8_WAIT_L(n) asm volatile("s_waitcnt lgkmcnt(" #n ")" ::: "memory")
; #define PG8_BAR __builtin_amdgcn_s_barrier()
; #define PG8_SCHED __builtin_amdgcn_sched_barrier(0)
; template <class Epi, class Sched, bool ALIGN_EPI = false, bool SP2 = false>
; __device__ __forceinline__ void gemm_phase(PG8_LAS unsigned char* lds, const Gemm g, const Sched& S, const Epi& E) {
;     ...
;             PG8_LDB(B0, 1, 0); PG8_LDB(B1, 1, 1); PG8_SCHED; PG8_LDA(At, 1, 0); PG8_STAGE(PG8_SA(0, 1), a2 + hstep, voffA);
;             PG8_WAIT_V(8); PG8_WAIT_L(0); PG8_BAR; PG8_MMA(0, 0, At, B0); PG8_MMA(0, 1, At, B1); PG8_BAR; PG8_SCHED;
;             PG8_LDA(At, 1, 1); PG8_STAGE(PG8_SB(1, 0), b3, voffB); PG8_STAGE(PG8_SB(1, 1), b3 + hstep, voffB); PG8_STAGE(PG8_SA(1, 0), a3, voffA);
;             PG8_WAIT_V(8); PG8_WAIT_L(0); PG8_BAR; PG8_MMA(1, 0, At, B0); PG8_MMA(1, 1, At, B1); PG8_BAR; PG8_SCHED;
	ds_read_b128 v[142:145], v210 offset:32768
	ds_read_b128 v[150:153], v210 offset:33792
	ds_read_b128 v[154:157], v210 offset:34816
	ds_read_b128 v[158:161], v210 offset:35840
	ds_read_b128 v[162:165], v210 offset:49152
	ds_read_b128 v[166:169], v210 offset:50176
	ds_read_b128 v[170:173], v210 offset:51200
	ds_read_b128 v[174:177], v210 offset:52224
	ds_read_b128 v[178:181], v149 offset:32768
	ds_read_b128 v[182:185], v149 offset:33792
	ds_read_b128 v[186:189], v149 offset:34816
	ds_read_b128 v[190:193], v149 offset:35840
	ds_read_b128 v[194:197], v149 offset:36864
	ds_read_b128 v[198:201], v149 offset:37888
	ds_read_b128 v[202:205], v149 offset:38912
	ds_read_b128 v[206:209], v149 offset:39936
	s_add_i32 s63, 0, 0x18000
	s_add_i32 s64, 0, 0x1c000
	s_mov_b32 m0, s10
	s_nop 0
	global_load_lds_dwordx4 v132, s[26:27]
	s_mov_b32 m0, s11
	s_nop 0
	global_load_lds_dwordx4 v134, s[26:27]
	s_add_u32 s26, s26, 0x20000
	s_addc_u32 s27, s27, 0
	s_mov_b32 m0, s25
	s_nop 0
	global_load_lds_dwordx4 v132, s[26:27]
	s_mov_b32 m0, s55
	s_nop 0
	global_load_lds_dwordx4 v134, s[26:27]
	s_nop 0
	s_waitcnt vmcnt(8)
	s_waitcnt lgkmcnt(0)
	s_barrier
	v_mfma_f32_16x16x32_bf16 v[128:131], v[142:145], v[178:181], v[128:131]
	v_mfma_f32_16x16x32_bf16 v[128:131], v[150:153], v[182:185], v[128:131]
	v_mfma_f32_16x16x32_bf16 v[124:127], v[154:157], v[178:181], v[124:127]
	v_mfma_f32_16x16x32_bf16 v[124:127], v[158:161], v[182:185], v[124:127]
	v_mfma_f32_16x16x32_bf16 v[108:111], v[154:157], v[186:189], v[108:111]
	v_mfma_f32_16x16x32_bf16 v[108:111], v[158:161], v[190:193], v[108:111]
	v_mfma_f32_16x16x32_bf16 v[112:115], v[142:145], v[186:189], v[112:115]
	v_mfma_f32_16x16x32_bf16 v[112:115], v[150:153], v[190:193], v[112:115]
	v_mfma_f32_16x16x32_bf16 v[96:99], v[142:145], v[194:197], v[96:99]
	v_mfma_f32_16x16x32_bf16 v[96:99], v[150:153], v[198:201], v[96:99]
	v_mfma_f32_16x16x32_bf16 v[92:95], v[154:157], v[194:197], v[92:95]
	v_mfma_f32_16x16x32_bf16 v[92:95], v[158:161], v[198:201], v[92:95]
	v_mfma_f32_16x16x32_bf16 v[76:79], v[154:157], v[202:205], v[76:79]
	v_mfma_f32_16x16x32_bf16 v[76:79], v[158:161], v[206:209], v[76:79]
	v_mfma_f32_16x16x32_bf16 v[80:83], v[142:145], v[202:205], v[80:83]
	v_mfma_f32_16x16x32_bf16 v[80:83], v[150:153], v[206:209], v[80:83]
	v_mfma_f32_16x16x32_bf16 v[120:123], v[162:165], v[178:181], v[120:123]
	v_mfma_f32_16x16x32_bf16 v[120:123], v[166:169], v[182:185], v[120:123]
	v_mfma_f32_16x16x32_bf16 v[116:119], v[170:173], v[178:181], v[116:119]
	v_mfma_f32_16x16x32_bf16 v[116:119], v[174:177], v[182:185], v[116:119]
	v_mfma_f32_16x16x32_bf16 v[100:103], v[170:173], v[186:189], v[100:103]
	v_mfma_f32_16x16x32_bf16 v[100:103], v[174:177], v[190:193], v[100:103]
	v_mfma_f32_16x16x32_bf16 v[104:107], v[162:165], v[186:189], v[104:107]
	v_mfma_f32_16x16x32_bf16 v[104:107], v[166:169], v[190:193], v[104:107]
	v_mfma_f32_16x16x32_bf16 v[88:91], v[162:165], v[194:197], v[88:91]
	v_mfma_f32_16x16x32_bf16 v[88:91], v[166:169], v[198:201], v[88:91]
	v_mfma_f32_16x16x32_bf16 v[84:87], v[170:173], v[194:197], v[84:87]
	v_mfma_f32_16x16x32_bf16 v[84:87], v[174:177], v[198:201], v[84:87]
	v_mfma_f32_16x16x32_bf16 v[68:71], v[170:173], v[202:205], v[68:71]
	v_mfma_f32_16x16x32_bf16 v[68:71], v[174:177], v[206:209], v[68:71]
	v_mfma_f32_16x16x32_bf16 v[72:75], v[162:165], v[202:205], v[72:75]
	v_mfma_f32_16x16x32_bf16 v[72:75], v[166:169], v[206:209], v[72:75]
	s_barrier
	ds_read_b128 v[178:181], v149 offset:49152
	ds_read_b128 v[182:185], v149 offset:50176
	ds_read_b128 v[186:189], v149 offset:51200
	ds_read_b128 v[190:193], v149 offset:52224
	ds_read_b128 v[194:197], v149 offset:53248
	ds_read_b128 v[198:201], v149 offset:54272
	ds_read_b128 v[202:205], v149 offset:55296
	ds_read_b128 v[206:209], v149 offset:56320
	s_add_i32 s26, s63, s9
	s_mov_b32 m0, s26
	s_add_u32 s0, s0, 0x80
	s_addc_u32 s1, s1, 0
	global_load_lds_dwordx4 v2, s[0:1]
	s_add_i32 m0, s26, 0x2000
	s_add_i32 s26, s64, s9
	global_load_lds_dwordx4 v136, s[0:1]
	s_add_u32 s0, s0, 0x20000
	s_addc_u32 s1, s1, 0
	s_mov_b32 m0, s26
	s_nop 0
	global_load_lds_dwordx4 v2, s[0:1]
	s_add_i32 m0, s26, 0x2000
	s_nop 0
	global_load_lds_dwordx4 v136, s[0:1]
	s_waitcnt vmcnt(6)
	s_waitcnt lgkmcnt(0)
	s_barrier
	v_mfma_f32_16x16x32_bf16 v[64:67], v[142:145], v[178:181], v[64:67]
	v_mfma_f32_16x16x32_bf16 v[64:67], v[150:153], v[182:185], v[64:67]
	v_mfma_f32_16x16x32_bf16 v[60:63], v[154:157], v[178:181], v[60:63]
	v_mfma_f32_16x16x32_bf16 v[60:63], v[158:161], v[182:185], v[60:63]
	v_mfma_f32_16x16x32_bf16 v[44:47], v[154:157], v[186:189], v[44:47]
	v_mfma_f32_16x16x32_bf16 v[44:47], v[158:161], v[190:193], v[44:47]
	v_mfma_f32_16x16x32_bf16 v[48:51], v[142:145], v[186:189], v[48:51]
	v_mfma_f32_16x16x32_bf16 v[48:51], v[150:153], v[190:193], v[48:51]
	v_mfma_f32_16x16x32_bf16 v[32:35], v[142:145], v[194:197], v[32:35]
	v_mfma_f32_16x16x32_bf16 v[32:35], v[150:153], v[198:201], v[32:35]
	v_mfma_f32_16x16x32_bf16 v[28:31], v[154:157], v[194:197], v[28:31]
	v_mfma_f32_16x16x32_bf16 v[28:31], v[158:161], v[198:201], v[28:31]
	v_mfma_f32_16x16x32_bf16 v[12:15], v[154:157], v[202:205], v[12:15]
	v_mfma_f32_16x16x32_bf16 v[12:15], v[158:161], v[206:209], v[12:15]
	v_mfma_f32_16x16x32_bf16 v[16:19], v[142:145], v[202:205], v[16:19]
	v_mfma_f32_16x16x32_bf16 v[16:19], v[150:153], v[206:209], v[16:19]
	s_add_i32 s62, s62, 2
	s_add_u32 s56, s56, 0x100
	s_addc_u32 s57, s57, 0
	s_add_u32 s47, s47, 0x100
	s_addc_u32 s49, s49, 0
	s_nop 0
	v_mfma_f32_16x16x32_bf16 v[56:59], v[162:165], v[178:181], v[56:59]
	v_mfma_f32_16x16x32_bf16 v[56:59], v[166:169], v[182:185], v[56:59]
	v_mfma_f32_16x16x32_bf16 v[52:55], v[170:173], v[178:181], v[52:55]
	v_mfma_f32_16x16x32_bf16 v[52:55], v[174:177], v[182:185], v[52:55]
	v_mfma_f32_16x16x32_bf16 v[36:39], v[170:173], v[186:189], v[36:39]
	v_mfma_f32_16x16x32_bf16 v[36:39], v[174:177], v[190:193], v[36:39]
	v_mfma_f32_16x16x32_bf16 v[40:43], v[162:165], v[186:189], v[40:43]
	v_mfma_f32_16x16x32_bf16 v[40:43], v[166:169], v[190:193], v[40:43]
	v_mfma_f32_16x16x32_bf16 v[24:27], v[162:165], v[194:197], v[24:27]
	v_mfma_f32_16x16x32_bf16 v[24:27], v[166:169], v[198:201], v[24:27]
	v_mfma_f32_16x16x32_bf16 v[20:23], v[170:173], v[194:197], v[20:23]
	v_mfma_f32_16x16x32_bf16 v[20:23], v[174:177], v[198:201], v[20:23]
	v_mfma_f32_16x16x32_bf16 v[4:7], v[170:173], v[202:205], v[4:7]
	v_mfma_f32_16x16x32_bf16 v[4:7], v[174:177], v[206:209], v[4:7]
	v_mfma_f32_16x16x32_bf16 v[8:11], v[162:165], v[202:205], v[8:11]
	v_mfma_f32_16x16x32_bf16 v[8:11], v[166:169], v[206:209], v[8:11]
	s_barrier
	s_cmp_gt_u32 s62, 5
	s_cbranch_scc0 .LBB0_2692
	s_and_b64 vcc, exec, s[44:45]
	s_cbranch_vccz .LBB0_2695
	s_barrier

; #define PG8_STAGE(bufoff, gbase, voff) do { _Pragma("unroll") for (int _i = 0; _i < 2; ++_i) \
;         __builtin_amdgcn_global_load_lds((const unsigned*)((const char*)(gbase) + (voff)[_i]), (PG8_LAS unsigned*)(lds + (bufoff) + ldsw + _i * 8192), 16, 0, 0); } while (0)
; #define PG8_LDA(dst, b, h) do { _Pragma("unroll") for (int m = 0; m < 4; ++m) _Pragma("unroll") for (int k = 0; k < 2; ++k) dst[m][k] = *(const PG8_LAS bf16x8*)(lds + PG8_SA(b, h) + aoff + m * 2048 + k * 1024); } while (0)
; #define PG8_LDB(dst, b, h) do { _Pragma("unroll") for (int n = 0; n < 2; ++n) _Pragma("unroll") for (int k = 0; k < 2; ++k) dst[n][k] = *(const PG8_LAS bf16x8*)(lds + PG8_SB(b, h) + boff + n * 2048 + k * 1024); } while (0)
; #define PG8_MMA(ai, bj, At, Bt) do { __builtin_amdgcn_s_setprio(1); _Pragma("unroll") for (int m = 0; m < 4; ++m) _Pragma("unroll") for (int n = 0; n < 2; ++n) _Pragma("unroll") for (int k = 0; k < 2; ++k) \
;         acc[ai][bj][m][n] = __builtin_amdgcn_mfma_f32_16x16x32_bf16(Bt[n][k], At[m][k], acc[ai][bj][m][n], 0, 0, 0); __builtin_amdgcn_s_setprio(0); } while (0)
; #define PG8_WAIT_V(n) asm volatile("s_waitcnt vmcnt(" #n ")" ::: "memory")
; #define PG8_WAIT_L(n) asm volatile("s_waitcnt lgkmcnt(" #n ")" ::: "memory")
; #define PG8_BAR __builtin_amdgcn_s_barrier()
; #define PG8_SCHED __builtin_amdgcn_sched_barrier(0)
; template <class Epi, class Sched, bool ALIGN_EPI = false, bool SP2 = false>
; __device__ __forceinline__ void gemm_phase(PG8_LAS unsigned char* lds, const Gemm g, const Sched& S, const Epi& E) {
;     ...
;             PG8_LDB(B0, 0, 0); PG8_LDB(B1, 0, 1); PG8_SCHED; PG8_LDA(At, 0, 0); PG8_STAGE(PG8_SA(1, 1), a1 + hstep, voffA);
;             PG8_WAIT_V(8); PG8_WAIT_L(0); PG8_BAR; PG8_MMA(0, 0, At, B0); PG8_MMA(0, 1, At, B1); PG8_BAR; PG8_SCHED;
;             PG8_LDA(At, 0, 1); PG8_STAGE(PG8_SB(0, 0), b2, voffB); PG8_STAGE(PG8_SB(0, 1), b2 + hstep, voffB); PG8_STAGE(PG8_SA(0, 0), a2, voffA);
;             PG8_WAIT_V(8); PG8_WAIT_L(0); PG8_BAR; PG8_MMA(1, 0, At, B0); PG8_MMA(1, 1, At, B1); PG8_BAR; PG8_SCHED;
.LBB0_3159:
	ds_read_b128 v[142:145], v146
	ds_read_b128 v[152:155], v146 offset:1024
	ds_read_b128 v[156:159], v146 offset:2048
	ds_read_b128 v[160:163], v146 offset:3072
	ds_read_b128 v[164:167], v146 offset:16384
	ds_read_b128 v[168:171], v146 offset:17408
	ds_read_b128 v[172:175], v146 offset:18432
	ds_read_b128 v[176:179], v146 offset:19456
	ds_read_b128 v[180:183], v151
	ds_read_b128 v[184:187], v151 offset:1024
	ds_read_b128 v[188:191], v151 offset:2048
	ds_read_b128 v[192:195], v151 offset:3072
	ds_read_b128 v[196:199], v151 offset:4096
	ds_read_b128 v[200:203], v151 offset:5120
	ds_read_b128 v[204:207], v151 offset:6144
	ds_read_b128 v[208:211], v151 offset:7168
	s_add_u32 s0, s24, 0xfff00080
	s_addc_u32 s1, s25, -1
	s_add_i32 s65, 0, 0x10000
	s_cmp_eq_u32 s64, 60
	s_cselect_b32 s27, s51, s1
	s_cselect_b32 s26, s60, s0
	s_cselect_b32 s1, s49, s63
	s_cselect_b32 s0, s61, s62
	s_add_i32 s70, 0, 0x14000
	s_add_u32 s100, s24, 0xfff00000
	s_addc_u32 s101, s25, -1
	s_mov_b32 m0, s56
	s_nop 0
	global_load_lds_dwordx4 v136, s[100:101]
	s_mov_b32 m0, s57
	s_nop 0
	global_load_lds_dwordx4 v134, s[100:101]
	s_add_i32 m0, s34, 0xc000
	s_nop 0
	global_load_lds_dwordx4 v138, s[24:25]
	s_add_i32 m0, s34, 0xe000
	s_nop 0
	global_load_lds_dwordx4 v140, s[24:25]
	s_nop 0
	s_nop 0
	s_waitcnt vmcnt(8)
	s_waitcnt lgkmcnt(0)
	s_barrier
	v_mfma_f32_16x16x32_bf16 v[128:131], v[142:145], v[180:183], v[128:131]
	v_mfma_f32_16x16x32_bf16 v[128:131], v[152:155], v[184:187], v[128:131]
	v_mfma_f32_16x16x32_bf16 v[124:127], v[156:159], v[180:183], v[124:127]
	v_mfma_f32_16x16x32_bf16 v[124:127], v[160:163], v[184:187], v[124:127]
	v_mfma_f32_16x16x32_bf16 v[108:111], v[156:159], v[188:191], v[108:111]
	v_mfma_f32_16x16x32_bf16 v[108:111], v[160:163], v[192:195], v[108:111]
	v_mfma_f32_16x16x32_bf16 v[112:115], v[142:145], v[188:191], v[112:115]
	v_mfma_f32_16x16x32_bf16 v[112:115], v[152:155], v[192:195], v[112:115]
	v_mfma_f32_16x16x32_bf16 v[96:99], v[142:145], v[196:199], v[96:99]
	v_mfma_f32_16x16x32_bf16 v[96:99], v[152:155], v[200:203], v[96:99]
	v_mfma_f32_16x16x32_bf16 v[92:95], v[156:159], v[196:199], v[92:95]
	v_mfma_f32_16x16x32_bf16 v[92:95], v[160:163], v[200:203], v[92:95]
	v_mfma_f32_16x16x32_bf16 v[76:79], v[156:159], v[204:207], v[76:79]
	v_mfma_f32_16x16x32_bf16 v[76:79], v[160:163], v[208:211], v[76:79]
	v_mfma_f32_16x16x32_bf16 v[80:83], v[142:145], v[204:207], v[80:83]
	v_mfma_f32_16x16x32_bf16 v[80:83], v[152:155], v[208:211], v[80:83]
	v_mfma_f32_16x16x32_bf16 v[120:123], v[164:167], v[180:183], v[120:123]
	v_mfma_f32_16x16x32_bf16 v[120:123], v[168:171], v[184:187], v[120:123]
	v_mfma_f32_16x16x32_bf16 v[116:119], v[172:175], v[180:183], v[116:119]
	v_mfma_f32_16x16x32_bf16 v[116:119], v[176:179], v[184:187], v[116:119]
	v_mfma_f32_16x16x32_bf16 v[100:103], v[172:175], v[188:191], v[100:103]
	v_mfma_f32_16x16x32_bf16 v[100:103], v[176:179], v[192:195], v[100:103]
	v_mfma_f32_16x16x32_bf16 v[104:107], v[164:167], v[188:191], v[104:107]
	v_mfma_f32_16x16x32_bf16 v[104:107], v[168:171], v[192:195], v[104:107]
	v_mfma_f32_16x16x32_bf16 v[88:91], v[164:167], v[196:199], v[88:91]
	v_mfma_f32_16x16x32_bf16 v[88:91], v[168:171], v[200:203], v[88:91]
	v_mfma_f32_16x16x32_bf16 v[84:87], v[172:175], v[196:199], v[84:87]
	v_mfma_f32_16x16x32_bf16 v[84:87], v[176:179], v[200:203], v[84:87]
	v_mfma_f32_16x16x32_bf16 v[68:71], v[172:175], v[204:207], v[68:71]
	v_mfma_f32_16x16x32_bf16 v[68:71], v[176:179], v[208:211], v[68:71]
	v_mfma_f32_16x16x32_bf16 v[72:75], v[164:167], v[204:207], v[72:75]
	v_mfma_f32_16x16x32_bf16 v[72:75], v[168:171], v[208:211], v[72:75]
	s_barrier
	ds_read_b128 v[180:183], v151 offset:16384
	ds_read_b128 v[184:187], v151 offset:17408
	ds_read_b128 v[188:191], v151 offset:18432
	ds_read_b128 v[192:195], v151 offset:19456
	ds_read_b128 v[196:199], v151 offset:20480
	ds_read_b128 v[200:203], v151 offset:21504
	ds_read_b128 v[204:207], v151 offset:22528
	ds_read_b128 v[208:211], v151 offset:23552
	s_add_i32 s65, s65, s9
	s_mov_b32 m0, s65
	s_nop 0
	global_load_lds_dwordx4 v2, s[0:1]
	s_add_i32 m0, s65, 0x2000
	s_add_u32 s66, s0, 0x100000
	s_addc_u32 s67, s1, 0
	s_add_i32 s65, s70, s9
	global_load_lds_dwordx4 v132, s[0:1]
	s_mov_b32 m0, s65
	s_nop 0
	global_load_lds_dwordx4 v2, s[66:67]
	s_add_i32 m0, s65, 0x2000
	s_nop 0
	global_load_lds_dwordx4 v132, s[66:67]
	s_waitcnt vmcnt(6)
	s_waitcnt lgkmcnt(0)
	s_barrier
	v_mfma_f32_16x16x32_bf16 v[64:67], v[142:145], v[180:183], v[64:67]
	v_mfma_f32_16x16x32_bf16 v[64:67], v[152:155], v[184:187], v[64:67]
	v_mfma_f32_16x16x32_bf16 v[60:63], v[156:159], v[180:183], v[60:63]
	v_mfma_f32_16x16x32_bf16 v[60:63], v[160:163], v[184:187], v[60:63]
	v_mfma_f32_16x16x32_bf16 v[44:47], v[156:159], v[188:191], v[44:47]
	v_mfma_f32_16x16x32_bf16 v[44:47], v[160:163], v[192:195], v[44:47]
	v_mfma_f32_16x16x32_bf16 v[48:51], v[142:145], v[188:191], v[48:51]
	v_mfma_f32_16x16x32_bf16 v[48:51], v[152:155], v[192:195], v[48:51]
	v_mfma_f32_16x16x32_bf16 v[32:35], v[142:145], v[196:199], v[32:35]
	v_mfma_f32_16x16x32_bf16 v[32:35], v[152:155], v[200:203], v[32:35]
	v_mfma_f32_16x16x32_bf16 v[28:31], v[156:159], v[196:199], v[28:31]
	v_mfma_f32_16x16x32_bf16 v[28:31], v[160:163], v[200:203], v[28:31]
	v_mfma_f32_16x16x32_bf16 v[12:15], v[156:159], v[204:207], v[12:15]
	v_mfma_f32_16x16x32_bf16 v[12:15], v[160:163], v[208:211], v[12:15]
	v_mfma_f32_16x16x32_bf16 v[16:19], v[142:145], v[204:207], v[16:19]
	v_mfma_f32_16x16x32_bf16 v[16:19], v[152:155], v[208:211], v[16:19]
	v_mfma_f32_16x16x32_bf16 v[56:59], v[164:167], v[180:183], v[56:59]
	v_mfma_f32_16x16x32_bf16 v[56:59], v[168:171], v[184:187], v[56:59]
	v_mfma_f32_16x16x32_bf16 v[52:55], v[172:175], v[180:183], v[52:55]
	v_mfma_f32_16x16x32_bf16 v[52:55], v[176:179], v[184:187], v[52:55]
	v_mfma_f32_16x16x32_bf16 v[36:39], v[172:175], v[188:191], v[36:39]
	v_mfma_f32_16x16x32_bf16 v[36:39], v[176:179], v[192:195], v[36:39]
	v_mfma_f32_16x16x32_bf16 v[40:43], v[164:167], v[188:191], v[40:43]
	v_mfma_f32_16x16x32_bf16 v[40:43], v[168:171], v[192:195], v[40:43]
	v_mfma_f32_16x16x32_bf16 v[24:27], v[164:167], v[196:199], v[24:27]
	v_mfma_f32_16x16x32_bf16 v[24:27], v[168:171], v[200:203], v[24:27]
	v_mfma_f32_16x16x32_bf16 v[20:23], v[172:175], v[196:199], v[20:23]
	v_mfma_f32_16x16x32_bf16 v[20:23], v[176:179], v[200:203], v[20:23]
	v_mfma_f32_16x16x32_bf16 v[4:7], v[172:175], v[204:207], v[4:7]
	v_mfma_f32_16x16x32_bf16 v[4:7], v[176:179], v[208:211], v[4:7]
	v_mfma_f32_16x16x32_bf16 v[8:11], v[164:167], v[204:207], v[8:11]
	v_mfma_f32_16x16x32_bf16 v[8:11], v[168:171], v[208:211], v[8:11]
	s_barrier
; #define PG8_STAGE(bufoff, gbase, voff) do { _Pragma("unroll") for (int _i = 0; _i < 2; ++_i) \
;         __builtin_amdgcn_global_load_lds((const unsigned*)((const char*)(gbase) + (voff)[_i]), (PG8_LAS unsigned*)(lds + (bufoff) + ldsw + _i * 8192), 16, 0, 0); } while (0)
; #define PG8_LDA(dst, b, h) do { _Pragma("unroll") for (int m = 0; m < 4; ++m) _Pragma("unroll") for (int k = 0; k < 2; ++k) dst[m][k] = *(const PG8_LAS bf16x8*)(lds + PG8_SA(b, h) + aoff + m * 2048 + k * 1024); } while (0)
; #define PG8_LDB(dst, b, h) do { _Pragma("unroll") for (int n = 0; n < 2; ++n) _Pragma("unroll") for (int k = 0; k < 2; ++k) dst[n][k] = *(const PG8_LAS bf16x8*)(lds + PG8_SB(b, h) + boff + n * 2048 + k * 1024); } while (0)
; #define PG8_MMA(ai, bj, At, Bt) do { __builtin_amdgcn_s_setprio(1); _Pragma("unroll") for (int m = 0; m < 4; ++m) _Pragma("unroll") for (int n = 0; n < 2; ++n) _Pragma("unroll") for (int k = 0; k < 2; ++k) \
;         acc[ai][bj][m][n] = __builtin_amdgcn_mfma_f32_16x16x32_bf16(Bt[n][k], At[m][k], acc[ai][bj][m][n], 0, 0, 0); __builtin_amdgcn_s_setprio(0); } while (0)
; #define PG8_WAIT_V(n) asm volatile("s_waitcnt vmcnt(" #n ")" ::: "memory")
; #define PG8_WAIT_L(n) asm volatile("s_waitcnt lgkmcnt(" #n ")" ::: "memory")
; #define PG8_BAR __builtin_amdgcn_s_barrier()
; #define PG8_SCHED __builtin_amdgcn_sched_barrier(0)
; template <class Epi, class Sched, bool ALIGN_EPI = false, bool SP2 = false>
; __device__ __forceinline__ void gemm_phase(PG8_LAS unsigned char* lds, const Gemm g, const Sched& S, const Epi& E) {
;     ...
;             PG8_LDB(B0, 1, 0); PG8_LDB(B1, 1, 1); PG8_SCHED; PG8_LDA(At, 1, 0); PG8_STAGE(PG8_SA(0, 1), a2 + hstep, voffA);
;             PG8_WAIT_V(8); PG8_WAIT_L(0); PG8_BAR; PG8_MMA(0, 0, At, B0); PG8_MMA(0, 1, At, B1); PG8_BAR; PG8_SCHED;
;             PG8_LDA(At, 1, 1); PG8_STAGE(PG8_SB(1, 0), b3, voffB); PG8_STAGE(PG8_SB(1, 1), b3 + hstep, voffB); PG8_STAGE(PG8_SA(1, 0), a3, voffA);
;             PG8_WAIT_V(8); PG8_WAIT_L(0); PG8_BAR; PG8_MMA(1, 0, At, B0); PG8_MMA(1, 1, At, B1); PG8_BAR; PG8_SCHED;
	ds_read_b128 v[142:145], v146 offset:32768
	ds_read_b128 v[152:155], v146 offset:33792
	ds_read_b128 v[156:159], v146 offset:34816
	ds_read_b128 v[160:163], v146 offset:35840
	ds_read_b128 v[164:167], v146 offset:49152
	ds_read_b128 v[168:171], v146 offset:50176
	ds_read_b128 v[172:175], v146 offset:51200
	ds_read_b128 v[176:179], v146 offset:52224
	ds_read_b128 v[180:183], v151 offset:32768
	ds_read_b128 v[184:187], v151 offset:33792
	ds_read_b128 v[188:191], v151 offset:34816
	ds_read_b128 v[192:195], v151 offset:35840
	ds_read_b128 v[196:199], v151 offset:36864
	ds_read_b128 v[200:203], v151 offset:37888
	ds_read_b128 v[204:207], v151 offset:38912
	ds_read_b128 v[208:211], v151 offset:39936
	s_add_i32 s65, 0, 0x18000
	s_add_i32 s66, 0, 0x1c000
	s_mov_b32 m0, s34
	s_nop 0
	global_load_lds_dwordx4 v136, s[26:27]
	s_mov_b32 m0, s35
	s_nop 0
	global_load_lds_dwordx4 v134, s[26:27]
	s_add_u32 s26, s26, 0x100000
	s_addc_u32 s27, s27, 0
	s_mov_b32 m0, s54
	s_nop 0
	global_load_lds_dwordx4 v136, s[26:27]
	s_mov_b32 m0, s55
	s_nop 0
	global_load_lds_dwordx4 v134, s[26:27]
	s_nop 0
	s_waitcnt vmcnt(8)
	s_waitcnt lgkmcnt(0)
	s_barrier
	v_mfma_f32_16x16x32_bf16 v[128:131], v[142:145], v[180:183], v[128:131]
	v_mfma_f32_16x16x32_bf16 v[128:131], v[152:155], v[184:187], v[128:131]
	v_mfma_f32_16x16x32_bf16 v[124:127], v[156:159], v[180:183], v[124:127]
	v_mfma_f32_16x16x32_bf16 v[124:127], v[160:163], v[184:187], v[124:127]
	v_mfma_f32_16x16x32_bf16 v[108:111], v[156:159], v[188:191], v[108:111]
	v_mfma_f32_16x16x32_bf16 v[108:111], v[160:163], v[192:195], v[108:111]
	v_mfma_f32_16x16x32_bf16 v[112:115], v[142:145], v[188:191], v[112:115]
	v_mfma_f32_16x16x32_bf16 v[112:115], v[152:155], v[192:195], v[112:115]
	v_mfma_f32_16x16x32_bf16 v[96:99], v[142:145], v[196:199], v[96:99]
	v_mfma_f32_16x16x32_bf16 v[96:99], v[152:155], v[200:203], v[96:99]
	v_mfma_f32_16x16x32_bf16 v[92:95], v[156:159], v[196:199], v[92:95]
	v_mfma_f32_16x16x32_bf16 v[92:95], v[160:163], v[200:203], v[92:95]
	v_mfma_f32_16x16x32_bf16 v[76:79], v[156:159], v[204:207], v[76:79]
	v_mfma_f32_16x16x32_bf16 v[76:79], v[160:163], v[208:211], v[76:79]
	v_mfma_f32_16x16x32_bf16 v[80:83], v[142:145], v[204:207], v[80:83]
	v_mfma_f32_16x16x32_bf16 v[80:83], v[152:155], v[208:211], v[80:83]
	v_mfma_f32_16x16x32_bf16 v[120:123], v[164:167], v[180:183], v[120:123]
	v_mfma_f32_16x16x32_bf16 v[120:123], v[168:171], v[184:187], v[120:123]
	v_mfma_f32_16x16x32_bf16 v[116:119], v[172:175], v[180:183], v[116:119]
	v_mfma_f32_16x16x32_bf16 v[116:119], v[176:179], v[184:187], v[116:119]
	v_mfma_f32_16x16x32_bf16 v[100:103], v[172:175], v[188:191], v[100:103]
	v_mfma_f32_16x16x32_bf16 v[100:103], v[176:179], v[192:195], v[100:103]
	v_mfma_f32_16x16x32_bf16 v[104:107], v[164:167], v[188:191], v[104:107]
	v_mfma_f32_16x16x32_bf16 v[104:107], v[168:171], v[192:195], v[104:107]
	v_mfma_f32_16x16x32_bf16 v[88:91], v[164:167], v[196:199], v[88:91]
	v_mfma_f32_16x16x32_bf16 v[88:91], v[168:171], v[200:203], v[88:91]
	v_mfma_f32_16x16x32_bf16 v[84:87], v[172:175], v[196:199], v[84:87]
	v_mfma_f32_16x16x32_bf16 v[84:87], v[176:179], v[200:203], v[84:87]
	v_mfma_f32_16x16x32_bf16 v[68:71], v[172:175], v[204:207], v[68:71]
	v_mfma_f32_16x16x32_bf16 v[68:71], v[176:179], v[208:211], v[68:71]
	v_mfma_f32_16x16x32_bf16 v[72:75], v[164:167], v[204:207], v[72:75]
	v_mfma_f32_16x16x32_bf16 v[72:75], v[168:171], v[208:211], v[72:75]
	s_barrier
	ds_read_b128 v[180:183], v151 offset:49152
	ds_read_b128 v[184:187], v151 offset:50176
	ds_read_b128 v[188:191], v151 offset:51200
	ds_read_b128 v[192:195], v151 offset:52224
	ds_read_b128 v[196:199], v151 offset:53248
	ds_read_b128 v[200:203], v151 offset:54272
	ds_read_b128 v[204:207], v151 offset:55296
	ds_read_b128 v[208:211], v151 offset:56320
	s_add_i32 s26, s65, s9
	s_mov_b32 m0, s26
	s_add_u32 s0, s0, 0x80
	s_addc_u32 s1, s1, 0
	global_load_lds_dwordx4 v2, s[0:1]
	s_add_i32 m0, s26, 0x2000
	s_add_i32 s26, s66, s9
	global_load_lds_dwordx4 v132, s[0:1]
	s_add_u32 s0, s0, 0x100000
	s_addc_u32 s1, s1, 0
	s_mov_b32 m0, s26
	s_nop 0
	global_load_lds_dwordx4 v2, s[0:1]
	s_add_i32 m0, s26, 0x2000
	s_nop 0
	global_load_lds_dwordx4 v132, s[0:1]
	s_waitcnt vmcnt(6)
	s_waitcnt lgkmcnt(0)
	s_barrier
	v_mfma_f32_16x16x32_bf16 v[64:67], v[142:145], v[180:183], v[64:67]
	v_mfma_f32_16x16x32_bf16 v[64:67], v[152:155], v[184:187], v[64:67]
	v_mfma_f32_16x16x32_bf16 v[60:63], v[156:159], v[180:183], v[60:63]
	v_mfma_f32_16x16x32_bf16 v[60:63], v[160:163], v[184:187], v[60:63]
	v_mfma_f32_16x16x32_bf16 v[44:47], v[156:159], v[188:191], v[44:47]
	v_mfma_f32_16x16x32_bf16 v[44:47], v[160:163], v[192:195], v[44:47]
	v_mfma_f32_16x16x32_bf16 v[48:51], v[142:145], v[188:191], v[48:51]
	v_mfma_f32_16x16x32_bf16 v[48:51], v[152:155], v[192:195], v[48:51]
	v_mfma_f32_16x16x32_bf16 v[32:35], v[142:145], v[196:199], v[32:35]
	v_mfma_f32_16x16x32_bf16 v[32:35], v[152:155], v[200:203], v[32:35]
	v_mfma_f32_16x16x32_bf16 v[28:31], v[156:159], v[196:199], v[28:31]
	v_mfma_f32_16x16x32_bf16 v[28:31], v[160:163], v[200:203], v[28:31]
	v_mfma_f32_16x16x32_bf16 v[12:15], v[156:159], v[204:207], v[12:15]
	v_mfma_f32_16x16x32_bf16 v[12:15], v[160:163], v[208:211], v[12:15]
	v_mfma_f32_16x16x32_bf16 v[16:19], v[142:145], v[204:207], v[16:19]
	v_mfma_f32_16x16x32_bf16 v[16:19], v[152:155], v[208:211], v[16:19]
	s_add_i32 s64, s64, 2
	s_add_u32 s24, s24, 0x100
	s_addc_u32 s25, s25, 0
	s_add_u32 s62, s62, 0x100
	s_addc_u32 s63, s63, 0
	s_nop 0
	v_mfma_f32_16x16x32_bf16 v[56:59], v[164:167], v[180:183], v[56:59]
	v_mfma_f32_16x16x32_bf16 v[56:59], v[168:171], v[184:187], v[56:59]
	v_mfma_f32_16x16x32_bf16 v[52:55], v[172:175], v[180:183], v[52:55]
	v_mfma_f32_16x16x32_bf16 v[52:55], v[176:179], v[184:187], v[52:55]
	v_mfma_f32_16x16x32_bf16 v[36:39], v[172:175], v[188:191], v[36:39]
	v_mfma_f32_16x16x32_bf16 v[36:39], v[176:179], v[192:195], v[36:39]
	v_mfma_f32_16x16x32_bf16 v[40:43], v[164:167], v[188:191], v[40:43]
	v_mfma_f32_16x16x32_bf16 v[40:43], v[168:171], v[192:195], v[40:43]
	v_mfma_f32_16x16x32_bf16 v[24:27], v[164:167], v[196:199], v[24:27]
	v_mfma_f32_16x16x32_bf16 v[24:27], v[168:171], v[200:203], v[24:27]
	v_mfma_f32_16x16x32_bf16 v[20:23], v[172:175], v[196:199], v[20:23]
	v_mfma_f32_16x16x32_bf16 v[20:23], v[176:179], v[200:203], v[20:23]
	v_mfma_f32_16x16x32_bf16 v[4:7], v[172:175], v[204:207], v[4:7]
	v_mfma_f32_16x16x32_bf16 v[4:7], v[176:179], v[208:211], v[4:7]
	v_mfma_f32_16x16x32_bf16 v[8:11], v[164:167], v[204:207], v[8:11]
	v_mfma_f32_16x16x32_bf16 v[8:11], v[168:171], v[208:211], v[8:11]
	s_barrier
	s_cmp_gt_u32 s64, 61
	s_cbranch_scc0 .LBB0_3159
	s_and_b64 vcc, exec, s[46:47]
	s_cbranch_vccz .LBB0_3162
	s_barrier

; #define PG8_STAGE(bufoff, gbase, voff) do { _Pragma("unroll") for (int _i = 0; _i < 2; ++_i) \
;         __builtin_amdgcn_global_load_lds((const unsigned*)((const char*)(gbase) + (voff)[_i]), (PG8_LAS unsigned*)(lds + (bufoff) + ldsw + _i * 8192), 16, 0, 0); } while (0)
; #define PG8_LDA(dst, b, h) do { _Pragma("unroll") for (int m = 0; m < 4; ++m) _Pragma("unroll") for (int k = 0; k < 2; ++k) dst[m][k] = *(const PG8_LAS bf16x8*)(lds + PG8_SA(b, h) + aoff + m * 2048 + k * 1024); } while (0)
; #define PG8_LDB(dst, b, h) do { _Pragma("unroll") for (int n = 0; n < 2; ++n) _Pragma("unroll") for (int k = 0; k < 2; ++k) dst[n][k] = *(const PG8_LAS bf16x8*)(lds + PG8_SB(b, h) + boff + n * 2048 + k * 1024); } while (0)
; #define PG8_MMA(ai, bj, At, Bt) do { __builtin_amdgcn_s_setprio(1); _Pragma("unroll") for (int m = 0; m < 4; ++m) _Pragma("unroll") for (int n = 0; n < 2; ++n) _Pragma("unroll") for (int k = 0; k < 2; ++k) \
;         acc[ai][bj][m][n] = __builtin_amdgcn_mfma_f32_16x16x32_bf16(Bt[n][k], At[m][k], acc[ai][bj][m][n], 0, 0, 0); __builtin_amdgcn_s_setprio(0); } while (0)
; #define PG8_WAIT_V(n) asm volatile("s_waitcnt vmcnt(" #n ")" ::: "memory")
; #define PG8_WAIT_L(n) asm volatile("s_waitcnt lgkmcnt(" #n ")" ::: "memory")
; #define PG8_BAR __builtin_amdgcn_s_barrier()
; #define PG8_SCHED __builtin_amdgcn_sched_barrier(0)
; template <class Epi, class Sched, bool ALIGN_EPI = false, bool SP2 = false>
; __device__ __forceinline__ void gemm_phase(PG8_LAS unsigned char* lds, const Gemm g, const Sched& S, const Epi& E) {
;     ...
;             PG8_LDB(B0, 0, 0); PG8_LDB(B1, 0, 1); PG8_SCHED; PG8_LDA(At, 0, 0); PG8_STAGE(PG8_SA(1, 1), a1 + hstep, voffA);
;             PG8_WAIT_V(8); PG8_WAIT_L(0); PG8_BAR; PG8_MMA(0, 0, At, B0); PG8_MMA(0, 1, At, B1); PG8_BAR; PG8_SCHED;
;             PG8_LDA(At, 0, 1); PG8_STAGE(PG8_SB(0, 0), b2, voffB); PG8_STAGE(PG8_SB(0, 1), b2 + hstep, voffB); PG8_STAGE(PG8_SA(0, 0), a2, voffA);
;             PG8_WAIT_V(8); PG8_WAIT_L(0); PG8_BAR; PG8_MMA(1, 0, At, B0); PG8_MMA(1, 1, At, B1); PG8_BAR; PG8_SCHED;
.LBB0_3627:
	s_waitcnt lgkmcnt(0)
	ds_read_b128 v[132:135], v162
	ds_read_b128 v[136:139], v162 offset:1024
	ds_read_b128 v[140:143], v162 offset:2048
	ds_read_b128 v[154:157], v162 offset:3072
	ds_read_b128 v[158:161], v162 offset:16384
	ds_read_b128 v[170:173], v162 offset:17408
	ds_read_b128 v[174:177], v162 offset:18432
	ds_read_b128 v[178:181], v162 offset:19456
	ds_read_b128 v[182:185], v169
	ds_read_b128 v[186:189], v169 offset:1024
	ds_read_b128 v[190:193], v169 offset:2048
	ds_read_b128 v[194:197], v169 offset:3072
	ds_read_b128 v[198:201], v169 offset:4096
	ds_read_b128 v[202:205], v169 offset:5120
	ds_read_b128 v[206:209], v169 offset:6144
	ds_read_b128 v[210:213], v169 offset:7168
	s_add_i32 s72, s26, 2
	s_add_u32 s0, s24, 0x100
	s_addc_u32 s1, s25, 0
	s_add_i32 s73, 0, 0x10000
	s_cmp_eq_u32 s44, s26
	s_cselect_b32 s35, s79, s1
	s_cselect_b32 s34, s78, s0
	s_cselect_b32 s27, s81, s47
	s_cselect_b32 s26, s80, s45
	s_add_i32 vcc_lo, 0, 0x14000
	s_add_u32 s100, s24, 0x80
	s_addc_u32 s101, s25, 0
	s_mov_b32 m0, s65
	s_nop 0
	global_load_lds_dwordx4 v144, s[100:101]
	s_mov_b32 m0, s4
	s_nop 0
	global_load_lds_dwordx4 v146, s[100:101]
	s_add_i32 m0, s92, 0xc000
	s_nop 0
	global_load_lds_dwordx4 v150, s[24:25]
	s_add_i32 m0, s92, 0xe000
	s_nop 0
	global_load_lds_dwordx4 v152, s[24:25]
	s_nop 0
	s_waitcnt vmcnt(8)
	s_waitcnt lgkmcnt(0)
	s_barrier
	v_mfma_f32_16x16x32_bf16 v[128:131], v[132:135], v[182:185], v[128:131]
	v_mfma_f32_16x16x32_bf16 v[128:131], v[136:139], v[186:189], v[128:131]
	v_mfma_f32_16x16x32_bf16 v[124:127], v[140:143], v[182:185], v[124:127]
	v_mfma_f32_16x16x32_bf16 v[124:127], v[154:157], v[186:189], v[124:127]
	v_mfma_f32_16x16x32_bf16 v[116:119], v[140:143], v[190:193], v[116:119]
	v_mfma_f32_16x16x32_bf16 v[116:119], v[154:157], v[194:197], v[116:119]
	v_mfma_f32_16x16x32_bf16 v[120:123], v[132:135], v[190:193], v[120:123]
	v_mfma_f32_16x16x32_bf16 v[120:123], v[136:139], v[194:197], v[120:123]
	v_mfma_f32_16x16x32_bf16 v[112:115], v[132:135], v[198:201], v[112:115]
	v_mfma_f32_16x16x32_bf16 v[112:115], v[136:139], v[202:205], v[112:115]
	v_mfma_f32_16x16x32_bf16 v[108:111], v[140:143], v[198:201], v[108:111]
	v_mfma_f32_16x16x32_bf16 v[108:111], v[154:157], v[202:205], v[108:111]
	v_mfma_f32_16x16x32_bf16 v[100:103], v[140:143], v[206:209], v[100:103]
	v_mfma_f32_16x16x32_bf16 v[100:103], v[154:157], v[210:213], v[100:103]
	v_mfma_f32_16x16x32_bf16 v[104:107], v[132:135], v[206:209], v[104:107]
	v_mfma_f32_16x16x32_bf16 v[104:107], v[136:139], v[210:213], v[104:107]
	v_mfma_f32_16x16x32_bf16 v[96:99], v[158:161], v[182:185], v[96:99]
	v_mfma_f32_16x16x32_bf16 v[96:99], v[170:173], v[186:189], v[96:99]
	v_mfma_f32_16x16x32_bf16 v[92:95], v[174:177], v[182:185], v[92:95]
	v_mfma_f32_16x16x32_bf16 v[92:95], v[178:181], v[186:189], v[92:95]
	v_mfma_f32_16x16x32_bf16 v[84:87], v[174:177], v[190:193], v[84:87]
	v_mfma_f32_16x16x32_bf16 v[84:87], v[178:181], v[194:197], v[84:87]
	v_mfma_f32_16x16x32_bf16 v[88:91], v[158:161], v[190:193], v[88:91]
	v_mfma_f32_16x16x32_bf16 v[88:91], v[170:173], v[194:197], v[88:91]
	v_mfma_f32_16x16x32_bf16 v[80:83], v[158:161], v[198:201], v[80:83]
	v_mfma_f32_16x16x32_bf16 v[80:83], v[170:173], v[202:205], v[80:83]
	v_mfma_f32_16x16x32_bf16 v[76:79], v[174:177], v[198:201], v[76:79]
	v_mfma_f32_16x16x32_bf16 v[76:79], v[178:181], v[202:205], v[76:79]
	v_mfma_f32_16x16x32_bf16 v[68:71], v[174:177], v[206:209], v[68:71]
	v_mfma_f32_16x16x32_bf16 v[68:71], v[178:181], v[210:213], v[68:71]
	v_mfma_f32_16x16x32_bf16 v[72:75], v[158:161], v[206:209], v[72:75]
	v_mfma_f32_16x16x32_bf16 v[72:75], v[170:173], v[210:213], v[72:75]
	s_barrier
	ds_read_b128 v[182:185], v169 offset:16384
	ds_read_b128 v[186:189], v169 offset:17408
	ds_read_b128 v[190:193], v169 offset:18432
	ds_read_b128 v[194:197], v169 offset:19456
	ds_read_b128 v[198:201], v169 offset:20480
	ds_read_b128 v[202:205], v169 offset:21504
	ds_read_b128 v[206:209], v169 offset:22528
	ds_read_b128 v[210:213], v169 offset:23552
	s_add_i32 s24, s73, s83
	s_mov_b32 m0, s24
	s_nop 0
	global_load_lds_dwordx4 v2, s[26:27]
	s_add_i32 m0, s24, 0x2000
	s_add_u32 s24, s26, 0x2b0000
	s_addc_u32 s25, s27, 0
	s_add_i32 s73, vcc_lo, s83
	global_load_lds_dwordx4 v148, s[26:27]
	s_mov_b32 m0, s73
	s_nop 0
	global_load_lds_dwordx4 v2, s[24:25]
	s_add_i32 m0, s73, 0x2000
	s_nop 0
	global_load_lds_dwordx4 v148, s[24:25]
	s_nop 0
	s_nop 0
	s_waitcnt vmcnt(6)
	s_waitcnt lgkmcnt(0)
	s_barrier
	v_mfma_f32_16x16x32_bf16 v[64:67], v[132:135], v[182:185], v[64:67]
	v_mfma_f32_16x16x32_bf16 v[64:67], v[136:139], v[186:189], v[64:67]
	v_mfma_f32_16x16x32_bf16 v[60:63], v[140:143], v[182:185], v[60:63]
	v_mfma_f32_16x16x32_bf16 v[60:63], v[154:157], v[186:189], v[60:63]
	v_mfma_f32_16x16x32_bf16 v[52:55], v[140:143], v[190:193], v[52:55]
	v_mfma_f32_16x16x32_bf16 v[52:55], v[154:157], v[194:197], v[52:55]
	v_mfma_f32_16x16x32_bf16 v[56:59], v[132:135], v[190:193], v[56:59]
	v_mfma_f32_16x16x32_bf16 v[56:59], v[136:139], v[194:197], v[56:59]
	v_mfma_f32_16x16x32_bf16 v[48:51], v[132:135], v[198:201], v[48:51]
	v_mfma_f32_16x16x32_bf16 v[48:51], v[136:139], v[202:205], v[48:51]
	v_mfma_f32_16x16x32_bf16 v[44:47], v[140:143], v[198:201], v[44:47]
	v_mfma_f32_16x16x32_bf16 v[44:47], v[154:157], v[202:205], v[44:47]
	v_mfma_f32_16x16x32_bf16 v[36:39], v[140:143], v[206:209], v[36:39]
	v_mfma_f32_16x16x32_bf16 v[36:39], v[154:157], v[210:213], v[36:39]
	v_mfma_f32_16x16x32_bf16 v[40:43], v[132:135], v[206:209], v[40:43]
	v_mfma_f32_16x16x32_bf16 v[40:43], v[136:139], v[210:213], v[40:43]
	v_mfma_f32_16x16x32_bf16 v[32:35], v[158:161], v[182:185], v[32:35]
	v_mfma_f32_16x16x32_bf16 v[32:35], v[170:173], v[186:189], v[32:35]
	v_mfma_f32_16x16x32_bf16 v[28:31], v[174:177], v[182:185], v[28:31]
	v_mfma_f32_16x16x32_bf16 v[28:31], v[178:181], v[186:189], v[28:31]
	v_mfma_f32_16x16x32_bf16 v[20:23], v[174:177], v[190:193], v[20:23]
	v_mfma_f32_16x16x32_bf16 v[20:23], v[178:181], v[194:197], v[20:23]
	v_mfma_f32_16x16x32_bf16 v[24:27], v[158:161], v[190:193], v[24:27]
	v_mfma_f32_16x16x32_bf16 v[24:27], v[170:173], v[194:197], v[24:27]
	v_mfma_f32_16x16x32_bf16 v[16:19], v[158:161], v[198:201], v[16:19]
	v_mfma_f32_16x16x32_bf16 v[16:19], v[170:173], v[202:205], v[16:19]
	v_mfma_f32_16x16x32_bf16 v[12:15], v[174:177], v[198:201], v[12:15]
	v_mfma_f32_16x16x32_bf16 v[12:15], v[178:181], v[202:205], v[12:15]
	v_mfma_f32_16x16x32_bf16 v[4:7], v[174:177], v[206:209], v[4:7]
	v_mfma_f32_16x16x32_bf16 v[4:7], v[178:181], v[210:213], v[4:7]
	v_mfma_f32_16x16x32_bf16 v[8:11], v[158:161], v[206:209], v[8:11]
	v_mfma_f32_16x16x32_bf16 v[8:11], v[170:173], v[210:213], v[8:11]
	s_barrier
; #define PG8_STAGE(bufoff, gbase, voff) do { _Pragma("unroll") for (int _i = 0; _i < 2; ++_i) \
;         __builtin_amdgcn_global_load_lds((const unsigned*)((const char*)(gbase) + (voff)[_i]), (PG8_LAS unsigned*)(lds + (bufoff) + ldsw + _i * 8192), 16, 0, 0); } while (0)
; #define PG8_LDA(dst, b, h) do { _Pragma("unroll") for (int m = 0; m < 4; ++m) _Pragma("unroll") for (int k = 0; k < 2; ++k) dst[m][k] = *(const PG8_LAS bf16x8*)(lds + PG8_SA(b, h) + aoff + m * 2048 + k * 1024); } while (0)
; #define PG8_LDB(dst, b, h) do { _Pragma("unroll") for (int n = 0; n < 2; ++n) _Pragma("unroll") for (int k = 0; k < 2; ++k) dst[n][k] = *(const PG8_LAS bf16x8*)(lds + PG8_SB(b, h) + boff + n * 2048 + k * 1024); } while (0)
; #define PG8_MMA(ai, bj, At, Bt) do { __builtin_amdgcn_s_setprio(1); _Pragma("unroll") for (int m = 0; m < 4; ++m) _Pragma("unroll") for (int n = 0; n < 2; ++n) _Pragma("unroll") for (int k = 0; k < 2; ++k) \
;         acc[ai][bj][m][n] = __builtin_amdgcn_mfma_f32_16x16x32_bf16(Bt[n][k], At[m][k], acc[ai][bj][m][n], 0, 0, 0); __builtin_amdgcn_s_setprio(0); } while (0)
; #define PG8_WAIT_V(n) asm volatile("s_waitcnt vmcnt(" #n ")" ::: "memory")
; #define PG8_WAIT_L(n) asm volatile("s_waitcnt lgkmcnt(" #n ")" ::: "memory")
; #define PG8_BAR __builtin_amdgcn_s_barrier()
; #define PG8_SCHED __builtin_amdgcn_sched_barrier(0)
; template <class Epi, class Sched, bool ALIGN_EPI = false, bool SP2 = false>
; __device__ __forceinline__ void gemm_phase(PG8_LAS unsigned char* lds, const Gemm g, const Sched& S, const Epi& E) {
;     ...
;             PG8_LDB(B0, 1, 0); PG8_LDB(B1, 1, 1); PG8_SCHED; PG8_LDA(At, 1, 0); PG8_STAGE(PG8_SA(0, 1), a2 + hstep, voffA);
;             PG8_WAIT_V(8); PG8_WAIT_L(0); PG8_BAR; PG8_MMA(0, 0, At, B0); PG8_MMA(0, 1, At, B1); PG8_BAR; PG8_SCHED;
;             PG8_LDA(At, 1, 1); PG8_STAGE(PG8_SB(1, 0), b3, voffB); PG8_STAGE(PG8_SB(1, 1), b3 + hstep, voffB); PG8_STAGE(PG8_SA(1, 0), a3, voffA);
;             PG8_WAIT_V(8); PG8_WAIT_L(0); PG8_BAR; PG8_MMA(1, 0, At, B0); PG8_MMA(1, 1, At, B1); PG8_BAR; PG8_SCHED;
	ds_read_b128 v[132:135], v162 offset:32768
	ds_read_b128 v[136:139], v162 offset:33792
	ds_read_b128 v[140:143], v162 offset:34816
	ds_read_b128 v[154:157], v162 offset:35840
	ds_read_b128 v[158:161], v162 offset:49152
	ds_read_b128 v[170:173], v162 offset:50176
	ds_read_b128 v[174:177], v162 offset:51200
	ds_read_b128 v[178:181], v162 offset:52224
	ds_read_b128 v[182:185], v169 offset:32768
	ds_read_b128 v[186:189], v169 offset:33792
	ds_read_b128 v[190:193], v169 offset:34816
	ds_read_b128 v[194:197], v169 offset:35840
	ds_read_b128 v[198:201], v169 offset:36864
	ds_read_b128 v[202:205], v169 offset:37888
	ds_read_b128 v[206:209], v169 offset:38912
	ds_read_b128 v[210:213], v169 offset:39936
	s_add_i32 s73, 0, 0x18000
	s_add_i32 vcc_lo, 0, 0x1c000
	s_mov_b32 m0, s92
	s_nop 0
	global_load_lds_dwordx4 v144, s[34:35]
	s_mov_b32 m0, s93
	s_nop 0
	global_load_lds_dwordx4 v146, s[34:35]
	s_add_u32 s24, s34, 0x2b0000
	s_addc_u32 s25, s35, 0
	s_mov_b32 m0, s94
	s_nop 0
	global_load_lds_dwordx4 v144, s[24:25]
	s_mov_b32 m0, s95
	s_nop 0
	global_load_lds_dwordx4 v146, s[24:25]
	s_nop 0
	s_waitcnt vmcnt(8)
	s_waitcnt lgkmcnt(0)
	s_barrier
	v_mfma_f32_16x16x32_bf16 v[128:131], v[132:135], v[182:185], v[128:131]
	v_mfma_f32_16x16x32_bf16 v[128:131], v[136:139], v[186:189], v[128:131]
	v_mfma_f32_16x16x32_bf16 v[124:127], v[140:143], v[182:185], v[124:127]
	v_mfma_f32_16x16x32_bf16 v[124:127], v[154:157], v[186:189], v[124:127]
	v_mfma_f32_16x16x32_bf16 v[116:119], v[140:143], v[190:193], v[116:119]
	v_mfma_f32_16x16x32_bf16 v[116:119], v[154:157], v[194:197], v[116:119]
	v_mfma_f32_16x16x32_bf16 v[120:123], v[132:135], v[190:193], v[120:123]
	v_mfma_f32_16x16x32_bf16 v[120:123], v[136:139], v[194:197], v[120:123]
	v_mfma_f32_16x16x32_bf16 v[112:115], v[132:135], v[198:201], v[112:115]
	v_mfma_f32_16x16x32_bf16 v[112:115], v[136:139], v[202:205], v[112:115]
	v_mfma_f32_16x16x32_bf16 v[108:111], v[140:143], v[198:201], v[108:111]
	v_mfma_f32_16x16x32_bf16 v[108:111], v[154:157], v[202:205], v[108:111]
	v_mfma_f32_16x16x32_bf16 v[100:103], v[140:143], v[206:209], v[100:103]
	v_mfma_f32_16x16x32_bf16 v[100:103], v[154:157], v[210:213], v[100:103]
	v_mfma_f32_16x16x32_bf16 v[104:107], v[132:135], v[206:209], v[104:107]
	v_mfma_f32_16x16x32_bf16 v[104:107], v[136:139], v[210:213], v[104:107]
	v_mfma_f32_16x16x32_bf16 v[96:99], v[158:161], v[182:185], v[96:99]
	v_mfma_f32_16x16x32_bf16 v[96:99], v[170:173], v[186:189], v[96:99]
	v_mfma_f32_16x16x32_bf16 v[92:95], v[174:177], v[182:185], v[92:95]
	v_mfma_f32_16x16x32_bf16 v[92:95], v[178:181], v[186:189], v[92:95]
	v_mfma_f32_16x16x32_bf16 v[84:87], v[174:177], v[190:193], v[84:87]
	v_mfma_f32_16x16x32_bf16 v[84:87], v[178:181], v[194:197], v[84:87]
	v_mfma_f32_16x16x32_bf16 v[88:91], v[158:161], v[190:193], v[88:91]
	v_mfma_f32_16x16x32_bf16 v[88:91], v[170:173], v[194:197], v[88:91]
	v_mfma_f32_16x16x32_bf16 v[80:83], v[158:161], v[198:201], v[80:83]
	v_mfma_f32_16x16x32_bf16 v[80:83], v[170:173], v[202:205], v[80:83]
	v_mfma_f32_16x16x32_bf16 v[76:79], v[174:177], v[198:201], v[76:79]
	v_mfma_f32_16x16x32_bf16 v[76:79], v[178:181], v[202:205], v[76:79]
	v_mfma_f32_16x16x32_bf16 v[68:71], v[174:177], v[206:209], v[68:71]
	v_mfma_f32_16x16x32_bf16 v[68:71], v[178:181], v[210:213], v[68:71]
	v_mfma_f32_16x16x32_bf16 v[72:75], v[158:161], v[206:209], v[72:75]
	v_mfma_f32_16x16x32_bf16 v[72:75], v[170:173], v[210:213], v[72:75]
	s_barrier
	ds_read_b128 v[182:185], v169 offset:49152
	ds_read_b128 v[186:189], v169 offset:50176
	ds_read_b128 v[190:193], v169 offset:51200
	ds_read_b128 v[194:197], v169 offset:52224
	ds_read_b128 v[198:201], v169 offset:53248
	ds_read_b128 v[202:205], v169 offset:54272
	ds_read_b128 v[206:209], v169 offset:55296
	ds_read_b128 v[210:213], v169 offset:56320
	s_add_i32 s24, s73, s83
	s_add_u32 s100, s26, 0x80
	s_addc_u32 s101, s27, 0
	s_mov_b32 m0, s24
	s_nop 0
	global_load_lds_dwordx4 v2, s[100:101]
	s_add_i32 m0, s24, 0x2000
	s_add_u32 s24, s26, 0x2b0080
	s_addc_u32 s25, s27, 0
	s_add_i32 s26, vcc_lo, s83
	global_load_lds_dwordx4 v148, s[100:101]
	s_mov_b32 m0, s26
	s_nop 0
	global_load_lds_dwordx4 v2, s[24:25]
	s_add_i32 m0, s26, 0x2000
	s_nop 0
	global_load_lds_dwordx4 v148, s[24:25]
	s_nop 0
	s_waitcnt vmcnt(6)
	s_waitcnt lgkmcnt(0)
	s_barrier
	v_mfma_f32_16x16x32_bf16 v[64:67], v[132:135], v[182:185], v[64:67]
	v_mfma_f32_16x16x32_bf16 v[64:67], v[136:139], v[186:189], v[64:67]
	v_mfma_f32_16x16x32_bf16 v[60:63], v[140:143], v[182:185], v[60:63]
	v_mfma_f32_16x16x32_bf16 v[60:63], v[154:157], v[186:189], v[60:63]
	v_mfma_f32_16x16x32_bf16 v[52:55], v[140:143], v[190:193], v[52:55]
	v_mfma_f32_16x16x32_bf16 v[52:55], v[154:157], v[194:197], v[52:55]
	v_mfma_f32_16x16x32_bf16 v[56:59], v[132:135], v[190:193], v[56:59]
	v_mfma_f32_16x16x32_bf16 v[56:59], v[136:139], v[194:197], v[56:59]
	v_mfma_f32_16x16x32_bf16 v[48:51], v[132:135], v[198:201], v[48:51]
	v_mfma_f32_16x16x32_bf16 v[48:51], v[136:139], v[202:205], v[48:51]
	v_mfma_f32_16x16x32_bf16 v[44:47], v[140:143], v[198:201], v[44:47]
	v_mfma_f32_16x16x32_bf16 v[44:47], v[154:157], v[202:205], v[44:47]
	v_mfma_f32_16x16x32_bf16 v[36:39], v[140:143], v[206:209], v[36:39]
	v_mfma_f32_16x16x32_bf16 v[36:39], v[154:157], v[210:213], v[36:39]
	v_mfma_f32_16x16x32_bf16 v[40:43], v[132:135], v[206:209], v[40:43]
	v_mfma_f32_16x16x32_bf16 v[40:43], v[136:139], v[210:213], v[40:43]
	s_add_u32 s45, s45, 0x100
	s_addc_u32 s47, s47, 0
	s_mov_b64 s[24:25], s[0:1]
	s_mov_b32 s26, s72
	s_nop 0
	v_mfma_f32_16x16x32_bf16 v[32:35], v[158:161], v[182:185], v[32:35]
	v_mfma_f32_16x16x32_bf16 v[32:35], v[170:173], v[186:189], v[32:35]
	v_mfma_f32_16x16x32_bf16 v[28:31], v[174:177], v[182:185], v[28:31]
	v_mfma_f32_16x16x32_bf16 v[28:31], v[178:181], v[186:189], v[28:31]
	v_mfma_f32_16x16x32_bf16 v[20:23], v[174:177], v[190:193], v[20:23]
	v_mfma_f32_16x16x32_bf16 v[20:23], v[178:181], v[194:197], v[20:23]
	v_mfma_f32_16x16x32_bf16 v[24:27], v[158:161], v[190:193], v[24:27]
	v_mfma_f32_16x16x32_bf16 v[24:27], v[170:173], v[194:197], v[24:27]
	v_mfma_f32_16x16x32_bf16 v[16:19], v[158:161], v[198:201], v[16:19]
	v_mfma_f32_16x16x32_bf16 v[16:19], v[170:173], v[202:205], v[16:19]
	v_mfma_f32_16x16x32_bf16 v[12:15], v[174:177], v[198:201], v[12:15]
	v_mfma_f32_16x16x32_bf16 v[12:15], v[178:181], v[202:205], v[12:15]
	v_mfma_f32_16x16x32_bf16 v[4:7], v[174:177], v[206:209], v[4:7]
	v_mfma_f32_16x16x32_bf16 v[4:7], v[178:181], v[210:213], v[4:7]
	v_mfma_f32_16x16x32_bf16 v[8:11], v[158:161], v[206:209], v[8:11]
	v_mfma_f32_16x16x32_bf16 v[8:11], v[170:173], v[210:213], v[8:11]
	s_barrier
	s_cmp_ge_i32 s72, s46
	s_cbranch_scc0 .LBB0_3627
	s_and_b64 vcc, exec, s[50:51]
	s_cbranch_vccz .LBB0_3630
	s_barrier
